# ROWS epilogue passes de-serialised (all row-chunk loads in flight), sector-friendly u-sweep lane mapping, GEMM k-loop LDS fragment double-buffering
# speedup vs baseline: 1.0177x; 1.0177x over previous
.LBB0_83:
	s_and_b32 s0, s0, 0x10000
	v_add_u32_e32 v136, s0, v139
	v_or_b32_e32 v147, s0, v140
	ds_read_b128 v[148:151], v136
	ds_read_b128 v[156:159], v136 offset:4096
	ds_read_b128 v[160:163], v136 offset:8192
	ds_read_b128 v[164:167], v136 offset:12288
	ds_read_b128 v[168:171], v147
	ds_read_b128 v[178:181], v147 offset:4096
	v_add_u32_e32 v214, s0, v141
	v_or_b32_e32 v215, s0, v142
	ds_read_b128 v[216:219], v214
	ds_read_b128 v[220:223], v214 offset:4096
	ds_read_b128 v[224:227], v214 offset:8192
	ds_read_b128 v[228:231], v214 offset:12288
	ds_read_b128 v[232:235], v215
	ds_read_b128 v[236:239], v215 offset:4096
	v_add_u32_e32 v136, s0, v143
	v_or_b32_e32 v147, s0, v144
	s_waitcnt lgkmcnt(6)
	v_mfma_f32_32x32x16_bf16 v[112:127], v[148:151], v[168:171], v[112:127]
	s_add_u32 s46, s46, 0x80
	s_addc_u32 s47, s47, 0
	s_cmpk_lg_i32 s46, 0x800
	v_mfma_f32_32x32x16_bf16 v[80:95], v[148:151], v[178:181], v[80:95]
	v_mfma_f32_32x32x16_bf16 v[48:63], v[156:159], v[168:171], v[48:63]
	v_mfma_f32_32x32x16_bf16 v[16:31], v[156:159], v[178:181], v[16:31]
	v_mfma_f32_32x32x16_bf16 v[96:111], v[160:163], v[168:171], v[96:111]
	v_mfma_f32_32x32x16_bf16 v[64:79], v[160:163], v[178:181], v[64:79]
	v_mfma_f32_32x32x16_bf16 v[32:47], v[164:167], v[168:171], v[32:47]
	v_mfma_f32_32x32x16_bf16 v[0:15], v[164:167], v[178:181], v[0:15]
	ds_read_b128 v[148:151], v136
	ds_read_b128 v[156:159], v136 offset:4096
	ds_read_b128 v[160:163], v136 offset:8192
	ds_read_b128 v[164:167], v136 offset:12288
	ds_read_b128 v[168:171], v147
	ds_read_b128 v[178:181], v147 offset:4096
	v_add_u32_e32 v214, s0, v145
	v_or_b32_e32 v215, s0, v146
	s_mov_b32 s0, s1
	s_waitcnt lgkmcnt(6)
	v_mfma_f32_32x32x16_bf16 v[112:127], v[216:219], v[232:235], v[112:127]
	v_mfma_f32_32x32x16_bf16 v[80:95], v[216:219], v[236:239], v[80:95]
	v_mfma_f32_32x32x16_bf16 v[48:63], v[220:223], v[232:235], v[48:63]
	v_mfma_f32_32x32x16_bf16 v[16:31], v[220:223], v[236:239], v[16:31]
	v_mfma_f32_32x32x16_bf16 v[96:111], v[224:227], v[232:235], v[96:111]
	v_mfma_f32_32x32x16_bf16 v[64:79], v[224:227], v[236:239], v[64:79]
	v_mfma_f32_32x32x16_bf16 v[32:47], v[228:231], v[232:235], v[32:47]
	v_mfma_f32_32x32x16_bf16 v[0:15], v[228:231], v[236:239], v[0:15]
	ds_read_b128 v[216:219], v214
	ds_read_b128 v[220:223], v214 offset:4096
	ds_read_b128 v[224:227], v214 offset:8192
	ds_read_b128 v[228:231], v214 offset:12288
	ds_read_b128 v[232:235], v215
	ds_read_b128 v[236:239], v215 offset:4096
	s_waitcnt lgkmcnt(6)
	v_mfma_f32_32x32x16_bf16 v[112:127], v[148:151], v[168:171], v[112:127]
	v_mfma_f32_32x32x16_bf16 v[80:95], v[148:151], v[178:181], v[80:95]
	v_mfma_f32_32x32x16_bf16 v[48:63], v[156:159], v[168:171], v[48:63]
	v_mfma_f32_32x32x16_bf16 v[16:31], v[156:159], v[178:181], v[16:31]
	v_mfma_f32_32x32x16_bf16 v[96:111], v[160:163], v[168:171], v[96:111]
	v_mfma_f32_32x32x16_bf16 v[64:79], v[160:163], v[178:181], v[64:79]
	v_mfma_f32_32x32x16_bf16 v[32:47], v[164:167], v[168:171], v[32:47]
	v_mfma_f32_32x32x16_bf16 v[0:15], v[164:167], v[178:181], v[0:15]
	s_waitcnt lgkmcnt(0)
	v_mfma_f32_32x32x16_bf16 v[112:127], v[216:219], v[232:235], v[112:127]
	v_mfma_f32_32x32x16_bf16 v[80:95], v[216:219], v[236:239], v[80:95]
	v_mfma_f32_32x32x16_bf16 v[48:63], v[220:223], v[232:235], v[48:63]
	v_mfma_f32_32x32x16_bf16 v[16:31], v[220:223], v[236:239], v[16:31]
	v_mfma_f32_32x32x16_bf16 v[96:111], v[224:227], v[232:235], v[96:111]
	v_mfma_f32_32x32x16_bf16 v[64:79], v[224:227], v[236:239], v[64:79]
	v_mfma_f32_32x32x16_bf16 v[32:47], v[228:231], v[232:235], v[32:47]
	v_mfma_f32_32x32x16_bf16 v[0:15], v[228:231], v[236:239], v[0:15]
	s_cbranch_scc0 .LBB0_88

.LBB0_91:
	s_and_b32 s1, s1, 0x10000
	v_add_u32_e32 v136, s1, v139
	v_or_b32_e32 v147, s1, v140
	ds_read_b128 v[148:151], v136
	ds_read_b128 v[156:159], v136 offset:4096
	ds_read_b128 v[160:163], v136 offset:8192
	ds_read_b128 v[164:167], v136 offset:12288
	ds_read_b128 v[168:171], v147
	ds_read_b128 v[178:181], v147 offset:4096
	v_add_u32_e32 v214, s1, v141
	v_or_b32_e32 v215, s1, v142
	ds_read_b128 v[216:219], v214
	ds_read_b128 v[220:223], v214 offset:4096
	ds_read_b128 v[224:227], v214 offset:8192
	ds_read_b128 v[228:231], v214 offset:12288
	ds_read_b128 v[232:235], v215
	ds_read_b128 v[236:239], v215 offset:4096
	v_add_u32_e32 v136, s1, v143
	v_or_b32_e32 v147, s1, v144
	s_waitcnt lgkmcnt(6)
	v_mfma_f32_32x32x16_bf16 v[112:127], v[168:171], v[148:151], v[112:127]
	s_add_u32 s40, s40, 0x80
	s_addc_u32 s41, s41, 0
	s_add_i32 s0, s0, 1
	s_cmpk_eq_i32 s40, 0x800
	v_mfma_f32_32x32x16_bf16 v[80:95], v[168:171], v[156:159], v[80:95]
	v_mfma_f32_32x32x16_bf16 v[48:63], v[168:171], v[160:163], v[48:63]
	v_mfma_f32_32x32x16_bf16 v[16:31], v[168:171], v[164:167], v[16:31]
	v_mfma_f32_32x32x16_bf16 v[96:111], v[178:181], v[148:151], v[96:111]
	v_mfma_f32_32x32x16_bf16 v[64:79], v[178:181], v[156:159], v[64:79]
	v_mfma_f32_32x32x16_bf16 v[32:47], v[178:181], v[160:163], v[32:47]
	v_mfma_f32_32x32x16_bf16 v[0:15], v[178:181], v[164:167], v[0:15]
	ds_read_b128 v[148:151], v136
	ds_read_b128 v[156:159], v136 offset:4096
	ds_read_b128 v[160:163], v136 offset:8192
	ds_read_b128 v[164:167], v136 offset:12288
	ds_read_b128 v[168:171], v147
	ds_read_b128 v[178:181], v147 offset:4096
	v_add_u32_e32 v214, s1, v145
	v_or_b32_e32 v215, s1, v146
	s_mov_b32 s1, s3
	s_waitcnt lgkmcnt(6)
	v_mfma_f32_32x32x16_bf16 v[112:127], v[232:235], v[216:219], v[112:127]
	v_mfma_f32_32x32x16_bf16 v[80:95], v[232:235], v[220:223], v[80:95]
	v_mfma_f32_32x32x16_bf16 v[48:63], v[232:235], v[224:227], v[48:63]
	v_mfma_f32_32x32x16_bf16 v[16:31], v[232:235], v[228:231], v[16:31]
	v_mfma_f32_32x32x16_bf16 v[96:111], v[236:239], v[216:219], v[96:111]
	v_mfma_f32_32x32x16_bf16 v[64:79], v[236:239], v[220:223], v[64:79]
	v_mfma_f32_32x32x16_bf16 v[32:47], v[236:239], v[224:227], v[32:47]
	v_mfma_f32_32x32x16_bf16 v[0:15], v[236:239], v[228:231], v[0:15]
	ds_read_b128 v[216:219], v214
	ds_read_b128 v[220:223], v214 offset:4096
	ds_read_b128 v[224:227], v214 offset:8192
	ds_read_b128 v[228:231], v214 offset:12288
	ds_read_b128 v[232:235], v215
	ds_read_b128 v[236:239], v215 offset:4096
	s_waitcnt lgkmcnt(6)
	v_mfma_f32_32x32x16_bf16 v[112:127], v[168:171], v[148:151], v[112:127]
	v_mfma_f32_32x32x16_bf16 v[80:95], v[168:171], v[156:159], v[80:95]
	v_mfma_f32_32x32x16_bf16 v[48:63], v[168:171], v[160:163], v[48:63]
	v_mfma_f32_32x32x16_bf16 v[16:31], v[168:171], v[164:167], v[16:31]
	v_mfma_f32_32x32x16_bf16 v[96:111], v[178:181], v[148:151], v[96:111]
	v_mfma_f32_32x32x16_bf16 v[64:79], v[178:181], v[156:159], v[64:79]
	v_mfma_f32_32x32x16_bf16 v[32:47], v[178:181], v[160:163], v[32:47]
	v_mfma_f32_32x32x16_bf16 v[0:15], v[178:181], v[164:167], v[0:15]
	s_waitcnt lgkmcnt(0)
	v_mfma_f32_32x32x16_bf16 v[112:127], v[232:235], v[216:219], v[112:127]
	v_mfma_f32_32x32x16_bf16 v[80:95], v[232:235], v[220:223], v[80:95]
	v_mfma_f32_32x32x16_bf16 v[48:63], v[232:235], v[224:227], v[48:63]
	v_mfma_f32_32x32x16_bf16 v[16:31], v[232:235], v[228:231], v[16:31]
	v_mfma_f32_32x32x16_bf16 v[96:111], v[236:239], v[216:219], v[96:111]
	v_mfma_f32_32x32x16_bf16 v[64:79], v[236:239], v[220:223], v[64:79]
	v_mfma_f32_32x32x16_bf16 v[32:47], v[236:239], v[224:227], v[32:47]
	v_mfma_f32_32x32x16_bf16 v[0:15], v[236:239], v[228:231], v[0:15]
	s_cbranch_scc1 .LBB0_96

.LBB0_984:
	s_and_b32 s66, s70, 0x10000
	v_add_u32_e32 v132, s66, v142
	v_or_b32_e32 v170, s66, v143
	ds_read_b128 v[150:153], v132
	ds_read_b128 v[154:157], v132 offset:4096
	ds_read_b128 v[158:161], v132 offset:8192
	ds_read_b128 v[162:165], v132 offset:12288
	ds_read_b128 v[166:169], v170
	ds_read_b128 v[172:175], v170 offset:4096
	v_add_u32_e32 v214, s66, v144
	v_or_b32_e32 v215, s66, v145
	ds_read_b128 v[216:219], v214
	ds_read_b128 v[220:223], v214 offset:4096
	ds_read_b128 v[224:227], v214 offset:8192
	ds_read_b128 v[228:231], v214 offset:12288
	ds_read_b128 v[232:235], v215
	ds_read_b128 v[236:239], v215 offset:4096
	v_add_u32_e32 v132, s66, v146
	v_or_b32_e32 v170, s66, v147
	s_waitcnt lgkmcnt(6)
	v_mfma_f32_32x32x16_bf16 v[112:127], v[166:169], v[150:153], v[112:127]
	s_add_u32 s64, s64, 0x80
	s_addc_u32 s65, s65, 0
	s_add_i32 s3, s3, 1
	s_cmpk_lg_i32 s64, 0x800
	s_mov_b32 s70, s71
	v_mfma_f32_32x32x16_bf16 v[80:95], v[166:169], v[154:157], v[80:95]
	v_mfma_f32_32x32x16_bf16 v[48:63], v[166:169], v[158:161], v[48:63]
	v_mfma_f32_32x32x16_bf16 v[16:31], v[166:169], v[162:165], v[16:31]
	v_mfma_f32_32x32x16_bf16 v[96:111], v[172:175], v[150:153], v[96:111]
	v_mfma_f32_32x32x16_bf16 v[64:79], v[172:175], v[154:157], v[64:79]
	v_mfma_f32_32x32x16_bf16 v[32:47], v[172:175], v[158:161], v[32:47]
	v_mfma_f32_32x32x16_bf16 v[0:15], v[172:175], v[162:165], v[0:15]
	ds_read_b128 v[150:153], v132
	ds_read_b128 v[154:157], v132 offset:4096
	ds_read_b128 v[158:161], v132 offset:8192
	ds_read_b128 v[162:165], v132 offset:12288
	ds_read_b128 v[166:169], v170
	ds_read_b128 v[172:175], v170 offset:4096
	v_add_u32_e32 v214, s66, v148
	v_or_b32_e32 v215, s66, v149
	s_waitcnt lgkmcnt(6)
	v_mfma_f32_32x32x16_bf16 v[112:127], v[232:235], v[216:219], v[112:127]
	v_mfma_f32_32x32x16_bf16 v[80:95], v[232:235], v[220:223], v[80:95]
	v_mfma_f32_32x32x16_bf16 v[48:63], v[232:235], v[224:227], v[48:63]
	v_mfma_f32_32x32x16_bf16 v[16:31], v[232:235], v[228:231], v[16:31]
	v_mfma_f32_32x32x16_bf16 v[96:111], v[236:239], v[216:219], v[96:111]
	v_mfma_f32_32x32x16_bf16 v[64:79], v[236:239], v[220:223], v[64:79]
	v_mfma_f32_32x32x16_bf16 v[32:47], v[236:239], v[224:227], v[32:47]
	v_mfma_f32_32x32x16_bf16 v[0:15], v[236:239], v[228:231], v[0:15]
	ds_read_b128 v[216:219], v214
	ds_read_b128 v[220:223], v214 offset:4096
	ds_read_b128 v[224:227], v214 offset:8192
	ds_read_b128 v[228:231], v214 offset:12288
	ds_read_b128 v[232:235], v215
	ds_read_b128 v[236:239], v215 offset:4096
	s_waitcnt lgkmcnt(6)
	v_mfma_f32_32x32x16_bf16 v[112:127], v[166:169], v[150:153], v[112:127]
	v_mfma_f32_32x32x16_bf16 v[80:95], v[166:169], v[154:157], v[80:95]
	v_mfma_f32_32x32x16_bf16 v[48:63], v[166:169], v[158:161], v[48:63]
	v_mfma_f32_32x32x16_bf16 v[16:31], v[166:169], v[162:165], v[16:31]
	v_mfma_f32_32x32x16_bf16 v[96:111], v[172:175], v[150:153], v[96:111]
	v_mfma_f32_32x32x16_bf16 v[64:79], v[172:175], v[154:157], v[64:79]
	v_mfma_f32_32x32x16_bf16 v[32:47], v[172:175], v[158:161], v[32:47]
	v_mfma_f32_32x32x16_bf16 v[0:15], v[172:175], v[162:165], v[0:15]
	s_waitcnt lgkmcnt(0)
	v_mfma_f32_32x32x16_bf16 v[112:127], v[232:235], v[216:219], v[112:127]
	v_mfma_f32_32x32x16_bf16 v[80:95], v[232:235], v[220:223], v[80:95]
	v_mfma_f32_32x32x16_bf16 v[48:63], v[232:235], v[224:227], v[48:63]
	v_mfma_f32_32x32x16_bf16 v[16:31], v[232:235], v[228:231], v[16:31]
	v_mfma_f32_32x32x16_bf16 v[96:111], v[236:239], v[216:219], v[96:111]
	v_mfma_f32_32x32x16_bf16 v[64:79], v[236:239], v[220:223], v[64:79]
	v_mfma_f32_32x32x16_bf16 v[32:47], v[236:239], v[224:227], v[32:47]
	v_mfma_f32_32x32x16_bf16 v[0:15], v[236:239], v[228:231], v[0:15]
	s_cbranch_scc0 .LBB0_989

.LBB0_994:
	s_and_b32 s70, s84, 0x10000
	v_add_u32_e32 v132, s70, v142
	v_or_b32_e32 v170, s70, v143
	ds_read_b128 v[150:153], v132
	ds_read_b128 v[154:157], v132 offset:4096
	ds_read_b128 v[158:161], v132 offset:8192
	ds_read_b128 v[162:165], v132 offset:12288
	ds_read_b128 v[166:169], v170
	ds_read_b128 v[172:175], v170 offset:4096
	v_add_u32_e32 v214, s70, v144
	v_or_b32_e32 v215, s70, v145
	ds_read_b128 v[216:219], v214
	ds_read_b128 v[220:223], v214 offset:4096
	ds_read_b128 v[224:227], v214 offset:8192
	ds_read_b128 v[228:231], v214 offset:12288
	ds_read_b128 v[232:235], v215
	ds_read_b128 v[236:239], v215 offset:4096
	v_add_u32_e32 v132, s70, v146
	v_or_b32_e32 v170, s70, v147
	s_waitcnt lgkmcnt(6)
	v_mfma_f32_32x32x16_bf16 v[112:127], v[166:169], v[150:153], v[112:127]
	s_add_u32 s68, s68, 0x80
	s_addc_u32 s69, s69, 0
	s_add_i32 s73, s73, 1
	s_cmpk_lg_i32 s68, 0x400
	s_mov_b32 s84, s85
	v_mfma_f32_32x32x16_bf16 v[96:111], v[166:169], v[154:157], v[96:111]
	v_mfma_f32_32x32x16_bf16 v[64:79], v[166:169], v[158:161], v[64:79]
	v_mfma_f32_32x32x16_bf16 v[32:47], v[166:169], v[162:165], v[32:47]
	v_mfma_f32_32x32x16_bf16 v[80:95], v[172:175], v[150:153], v[80:95]
	v_mfma_f32_32x32x16_bf16 v[48:63], v[172:175], v[154:157], v[48:63]
	v_mfma_f32_32x32x16_bf16 v[16:31], v[172:175], v[158:161], v[16:31]
	v_mfma_f32_32x32x16_bf16 v[0:15], v[172:175], v[162:165], v[0:15]
	ds_read_b128 v[150:153], v132
	ds_read_b128 v[154:157], v132 offset:4096
	ds_read_b128 v[158:161], v132 offset:8192
	ds_read_b128 v[162:165], v132 offset:12288
	ds_read_b128 v[166:169], v170
	ds_read_b128 v[172:175], v170 offset:4096
	v_add_u32_e32 v214, s70, v148
	v_or_b32_e32 v215, s70, v149
	s_waitcnt lgkmcnt(6)
	v_mfma_f32_32x32x16_bf16 v[112:127], v[232:235], v[216:219], v[112:127]
	v_mfma_f32_32x32x16_bf16 v[96:111], v[232:235], v[220:223], v[96:111]
	v_mfma_f32_32x32x16_bf16 v[64:79], v[232:235], v[224:227], v[64:79]
	v_mfma_f32_32x32x16_bf16 v[32:47], v[232:235], v[228:231], v[32:47]
	v_mfma_f32_32x32x16_bf16 v[80:95], v[236:239], v[216:219], v[80:95]
	v_mfma_f32_32x32x16_bf16 v[48:63], v[236:239], v[220:223], v[48:63]
	v_mfma_f32_32x32x16_bf16 v[16:31], v[236:239], v[224:227], v[16:31]
	v_mfma_f32_32x32x16_bf16 v[0:15], v[236:239], v[228:231], v[0:15]
	ds_read_b128 v[216:219], v214
	ds_read_b128 v[220:223], v214 offset:4096
	ds_read_b128 v[224:227], v214 offset:8192
	ds_read_b128 v[228:231], v214 offset:12288
	ds_read_b128 v[232:235], v215
	ds_read_b128 v[236:239], v215 offset:4096
	s_waitcnt lgkmcnt(6)
	v_mfma_f32_32x32x16_bf16 v[112:127], v[166:169], v[150:153], v[112:127]
	v_mfma_f32_32x32x16_bf16 v[96:111], v[166:169], v[154:157], v[96:111]
	v_mfma_f32_32x32x16_bf16 v[64:79], v[166:169], v[158:161], v[64:79]
	v_mfma_f32_32x32x16_bf16 v[32:47], v[166:169], v[162:165], v[32:47]
	v_mfma_f32_32x32x16_bf16 v[80:95], v[172:175], v[150:153], v[80:95]
	v_mfma_f32_32x32x16_bf16 v[48:63], v[172:175], v[154:157], v[48:63]
	v_mfma_f32_32x32x16_bf16 v[16:31], v[172:175], v[158:161], v[16:31]
	v_mfma_f32_32x32x16_bf16 v[0:15], v[172:175], v[162:165], v[0:15]
	s_waitcnt lgkmcnt(0)
	v_mfma_f32_32x32x16_bf16 v[112:127], v[232:235], v[216:219], v[112:127]
	v_mfma_f32_32x32x16_bf16 v[96:111], v[232:235], v[220:223], v[96:111]
	v_mfma_f32_32x32x16_bf16 v[64:79], v[232:235], v[224:227], v[64:79]
	v_mfma_f32_32x32x16_bf16 v[32:47], v[232:235], v[228:231], v[32:47]
	v_mfma_f32_32x32x16_bf16 v[80:95], v[236:239], v[216:219], v[80:95]
	v_mfma_f32_32x32x16_bf16 v[48:63], v[236:239], v[220:223], v[48:63]
	v_mfma_f32_32x32x16_bf16 v[16:31], v[236:239], v[224:227], v[16:31]
	v_mfma_f32_32x32x16_bf16 v[0:15], v[236:239], v[228:231], v[0:15]
	s_cbranch_scc0 .LBB0_999

.LBB0_999:
	v_mov_b32_e32 v128, v176
	s_waitcnt vmcnt(0) lgkmcnt(0)
	s_barrier
	s_nop 4
	v_cvt_pk_bf16_f32 v80, v80, v81
	v_and_b32_e32 v129, 0xc0, v128
	v_and_b32_e32 v130, 31, v128
	v_lshrrev_b32_e32 v131, 1, v128
	v_lshrrev_b32_e32 v128, 2, v128
	v_and_b32_e32 v128, 8, v128
	v_and_or_b32 v130, v131, s93, v130
	v_lshl_or_b32 v128, v129, 1, v128
	v_mad_u64_u32 v[128:129], s[68:69], v130, s0, v[128:129]
	v_cvt_pk_bf16_f32 v81, v82, v83
	v_cvt_pk_bf16_f32 v82, v84, v85
	v_cvt_pk_bf16_f32 v83, v86, v87
	v_add_u32_e32 v84, 0x4000, v128
	v_cvt_pk_bf16_f32 v48, v48, v49
	v_cvt_pk_bf16_f32 v49, v50, v51
	v_cvt_pk_bf16_f32 v50, v52, v53
	v_cvt_pk_bf16_f32 v51, v54, v55
	v_add_u32_e32 v52, 0x8000, v128
	v_cvt_pk_bf16_f32 v16, v16, v17
	v_cvt_pk_bf16_f32 v17, v18, v19
	v_cvt_pk_bf16_f32 v18, v20, v21
	v_cvt_pk_bf16_f32 v19, v22, v23
	ds_write2_b64 v128, v[80:81], v[82:83] offset0:8 offset1:10
	v_cvt_pk_bf16_f32 v80, v88, v89
	v_cvt_pk_bf16_f32 v81, v90, v91
	v_cvt_pk_bf16_f32 v82, v92, v93
	v_cvt_pk_bf16_f32 v83, v94, v95
	ds_write2_b64 v84, v[48:49], v[50:51] offset0:72 offset1:74
	v_cvt_pk_bf16_f32 v48, v56, v57
	v_cvt_pk_bf16_f32 v49, v58, v59
	v_cvt_pk_bf16_f32 v50, v60, v61
	v_cvt_pk_bf16_f32 v51, v62, v63
	ds_write2_b64 v52, v[16:17], v[18:19] offset0:136 offset1:138
	v_cvt_pk_bf16_f32 v16, v24, v25
	v_cvt_pk_bf16_f32 v17, v26, v27
	v_cvt_pk_bf16_f32 v18, v28, v29
	v_cvt_pk_bf16_f32 v19, v30, v31
	v_add_u32_e32 v20, 0xc000, v128
	v_cvt_pk_bf16_f32 v0, v0, v1
	v_cvt_pk_bf16_f32 v1, v2, v3
	v_cvt_pk_bf16_f32 v2, v4, v5
	v_cvt_pk_bf16_f32 v3, v6, v7
	v_cvt_pk_bf16_f32 v112, v112, v113
	v_cvt_pk_bf16_f32 v113, v114, v115
	v_cvt_pk_bf16_f32 v114, v116, v117
	v_cvt_pk_bf16_f32 v115, v118, v119
	ds_write2_b64 v128, v[80:81], v[82:83] offset0:12 offset1:14
	v_cvt_pk_bf16_f32 v80, v96, v97
	v_cvt_pk_bf16_f32 v81, v98, v99
	v_cvt_pk_bf16_f32 v82, v100, v101
	v_cvt_pk_bf16_f32 v83, v102, v103
	ds_write2_b64 v84, v[48:49], v[50:51] offset0:76 offset1:78
	v_cvt_pk_bf16_f32 v48, v64, v65
	v_cvt_pk_bf16_f32 v49, v66, v67
	v_cvt_pk_bf16_f32 v50, v68, v69
	v_cvt_pk_bf16_f32 v51, v70, v71
	ds_write2_b64 v52, v[16:17], v[18:19] offset0:140 offset1:142
	v_cvt_pk_bf16_f32 v16, v32, v33
	v_cvt_pk_bf16_f32 v17, v34, v35
	v_cvt_pk_bf16_f32 v18, v36, v37
	v_cvt_pk_bf16_f32 v19, v38, v39
	ds_write2_b64 v20, v[0:1], v[2:3] offset0:200 offset1:202
	v_cvt_pk_bf16_f32 v0, v8, v9
	v_cvt_pk_bf16_f32 v1, v10, v11
	v_cvt_pk_bf16_f32 v2, v12, v13
	v_cvt_pk_bf16_f32 v3, v14, v15
	ds_write2_b64 v128, v[112:113], v[114:115] offset1:2
	v_cvt_pk_bf16_f32 v112, v120, v121
	v_cvt_pk_bf16_f32 v113, v122, v123
	v_cvt_pk_bf16_f32 v114, v124, v125
	v_cvt_pk_bf16_f32 v115, v126, v127
	ds_write2_b64 v84, v[80:81], v[82:83] offset0:64 offset1:66
	v_cvt_pk_bf16_f32 v80, v104, v105
	v_cvt_pk_bf16_f32 v81, v106, v107
	v_cvt_pk_bf16_f32 v82, v108, v109
	v_cvt_pk_bf16_f32 v83, v110, v111
	ds_write2_b64 v52, v[48:49], v[50:51] offset0:128 offset1:130
	v_cvt_pk_bf16_f32 v48, v72, v73
	v_cvt_pk_bf16_f32 v49, v74, v75
	v_cvt_pk_bf16_f32 v50, v76, v77
	v_cvt_pk_bf16_f32 v51, v78, v79
	ds_write2_b64 v20, v[16:17], v[18:19] offset0:192 offset1:194
	v_cvt_pk_bf16_f32 v16, v40, v41
	v_cvt_pk_bf16_f32 v17, v42, v43
	v_cvt_pk_bf16_f32 v18, v44, v45
	v_cvt_pk_bf16_f32 v19, v46, v47
	ds_write2_b64 v20, v[0:1], v[2:3] offset0:204 offset1:206
	v_mov_b32_e32 v1, v176
	ds_write2_b64 v128, v[112:113], v[114:115] offset0:4 offset1:6
	ds_write2_b64 v84, v[80:81], v[82:83] offset0:68 offset1:70
	ds_write2_b64 v52, v[48:49], v[50:51] offset0:132 offset1:134
	ds_write2_b64 v20, v[16:17], v[18:19] offset0:196 offset1:198
	s_waitcnt lgkmcnt(0)
	s_barrier
	v_mov_b32_e32 v1, v176
	s_mov_b32 s98, 0xffff0000
	v_lshlrev_b32_e32 v0, 4, v1
	v_and_b32_e32 v0, 0x1f0, v0
	v_lshrrev_b32_e32 v2, 5, v1
	v_mov_b32_e32 v6, 0x210
	v_mad_u32_u24 v4, v2, v6, v0
	v_add_u32_e32 v5, 0x10800, v4
	v_lshl_or_b32 v132, s72, 9, v0
	v_lshl_add_u32 v3, v2, 11, v132
	v_add_u32_e32 v6, 0x0, v3
	global_load_dwordx4 v[32:35], v6, s[54:55]
	ds_read_b128 v[96:99], v4
	v_add_u32_e32 v6, 0x8000, v3
	global_load_dwordx4 v[36:39], v6, s[54:55]
	ds_read_b128 v[100:103], v4 offset:8448
	v_add_u32_e32 v6, 0x10000, v3
	global_load_dwordx4 v[40:43], v6, s[54:55]
	ds_read_b128 v[104:107], v4 offset:16896
	v_add_u32_e32 v6, 0x18000, v3
	global_load_dwordx4 v[44:47], v6, s[54:55]
	ds_read_b128 v[108:111], v4 offset:25344
	v_add_u32_e32 v6, 0x20000, v3
	global_load_dwordx4 v[48:51], v6, s[54:55]
	ds_read_b128 v[112:115], v4 offset:33792
	v_add_u32_e32 v6, 0x28000, v3
	global_load_dwordx4 v[52:55], v6, s[54:55]
	ds_read_b128 v[116:119], v4 offset:42240
	v_add_u32_e32 v6, 0x30000, v3
	global_load_dwordx4 v[56:59], v6, s[54:55]
	ds_read_b128 v[120:123], v4 offset:50688
	v_add_u32_e32 v6, 0x38000, v3
	global_load_dwordx4 v[60:63], v6, s[54:55]
	ds_read_b128 v[124:127], v4 offset:59136
	v_add_u32_e32 v6, 0x40000, v3
	global_load_dwordx4 v[64:67], v6, s[54:55]
	v_add_u32_e32 v6, 0x48000, v3
	global_load_dwordx4 v[68:71], v6, s[54:55]
	v_add_u32_e32 v6, 0x50000, v3
	global_load_dwordx4 v[72:75], v6, s[54:55]
	v_add_u32_e32 v6, 0x58000, v3
	global_load_dwordx4 v[76:79], v6, s[54:55]
	v_add_u32_e32 v6, 0x60000, v3
	global_load_dwordx4 v[80:83], v6, s[54:55]
	v_add_u32_e32 v6, 0x68000, v3
	global_load_dwordx4 v[84:87], v6, s[54:55]
	v_add_u32_e32 v6, 0x70000, v3
	global_load_dwordx4 v[88:91], v6, s[54:55]
	v_add_u32_e32 v6, 0x78000, v3
	global_load_dwordx4 v[92:95], v6, s[54:55]
	s_waitcnt vmcnt(15) lgkmcnt(7)
	v_lshlrev_b32_e32 v8, 16, v96
	v_and_b32_e32 v9, s98, v96
	v_lshlrev_b32_e32 v10, 16, v32
	v_and_b32_e32 v11, s98, v32
	v_lshlrev_b32_e32 v12, 16, v97
	v_and_b32_e32 v13, s98, v97
	v_lshlrev_b32_e32 v14, 16, v33
	v_and_b32_e32 v15, s98, v33
	v_pk_mul_f32 v[8:9], v[8:9], v[10:11]
	v_pk_mul_f32 v[12:13], v[12:13], v[14:15]
	v_cvt_pk_bf16_f32 v32, v8, v9
	v_cvt_pk_bf16_f32 v33, v12, v13
	v_lshlrev_b32_e32 v8, 16, v98
	v_and_b32_e32 v9, s98, v98
	v_lshlrev_b32_e32 v10, 16, v34
	v_and_b32_e32 v11, s98, v34
	v_lshlrev_b32_e32 v12, 16, v99
	v_and_b32_e32 v13, s98, v99
	v_lshlrev_b32_e32 v14, 16, v35
	v_and_b32_e32 v15, s98, v35
	v_pk_mul_f32 v[8:9], v[8:9], v[10:11]
	v_pk_mul_f32 v[12:13], v[12:13], v[14:15]
	v_cvt_pk_bf16_f32 v34, v8, v9
	v_cvt_pk_bf16_f32 v35, v12, v13
	ds_read_b128 v[96:99], v5
	v_add_u32_e32 v7, 0x0, v3
	global_store_dwordx4 v7, v[32:35], s[54:55]
	s_waitcnt vmcnt(15) lgkmcnt(7)
	v_lshlrev_b32_e32 v8, 16, v100
	v_and_b32_e32 v9, s98, v100
	v_lshlrev_b32_e32 v10, 16, v36
	v_and_b32_e32 v11, s98, v36
	v_lshlrev_b32_e32 v12, 16, v101
	v_and_b32_e32 v13, s98, v101
	v_lshlrev_b32_e32 v14, 16, v37
	v_and_b32_e32 v15, s98, v37
	v_pk_mul_f32 v[8:9], v[8:9], v[10:11]
	v_pk_mul_f32 v[12:13], v[12:13], v[14:15]
	v_cvt_pk_bf16_f32 v36, v8, v9
	v_cvt_pk_bf16_f32 v37, v12, v13
	v_lshlrev_b32_e32 v8, 16, v102
	v_and_b32_e32 v9, s98, v102
	v_lshlrev_b32_e32 v10, 16, v38
	v_and_b32_e32 v11, s98, v38
	v_lshlrev_b32_e32 v12, 16, v103
	v_and_b32_e32 v13, s98, v103
	v_lshlrev_b32_e32 v14, 16, v39
	v_and_b32_e32 v15, s98, v39
	v_pk_mul_f32 v[8:9], v[8:9], v[10:11]
	v_pk_mul_f32 v[12:13], v[12:13], v[14:15]
	v_cvt_pk_bf16_f32 v38, v8, v9
	v_cvt_pk_bf16_f32 v39, v12, v13
	ds_read_b128 v[100:103], v5 offset:8448
	v_add_u32_e32 v7, 0x8000, v3
	global_store_dwordx4 v7, v[36:39], s[54:55]
	s_waitcnt vmcnt(15) lgkmcnt(7)
	v_lshlrev_b32_e32 v8, 16, v104
	v_and_b32_e32 v9, s98, v104
	v_lshlrev_b32_e32 v10, 16, v40
	v_and_b32_e32 v11, s98, v40
	v_lshlrev_b32_e32 v12, 16, v105
	v_and_b32_e32 v13, s98, v105
	v_lshlrev_b32_e32 v14, 16, v41
	v_and_b32_e32 v15, s98, v41
	v_pk_mul_f32 v[8:9], v[8:9], v[10:11]
	v_pk_mul_f32 v[12:13], v[12:13], v[14:15]
	v_cvt_pk_bf16_f32 v40, v8, v9
	v_cvt_pk_bf16_f32 v41, v12, v13
	v_lshlrev_b32_e32 v8, 16, v106
	v_and_b32_e32 v9, s98, v106
	v_lshlrev_b32_e32 v10, 16, v42
	v_and_b32_e32 v11, s98, v42
	v_lshlrev_b32_e32 v12, 16, v107
	v_and_b32_e32 v13, s98, v107
	v_lshlrev_b32_e32 v14, 16, v43
	v_and_b32_e32 v15, s98, v43
	v_pk_mul_f32 v[8:9], v[8:9], v[10:11]
	v_pk_mul_f32 v[12:13], v[12:13], v[14:15]
	v_cvt_pk_bf16_f32 v42, v8, v9
	v_cvt_pk_bf16_f32 v43, v12, v13
	ds_read_b128 v[104:107], v5 offset:16896
	v_add_u32_e32 v7, 0x10000, v3
	global_store_dwordx4 v7, v[40:43], s[54:55]
	s_waitcnt vmcnt(15) lgkmcnt(7)
	v_lshlrev_b32_e32 v8, 16, v108
	v_and_b32_e32 v9, s98, v108
	v_lshlrev_b32_e32 v10, 16, v44
	v_and_b32_e32 v11, s98, v44
	v_lshlrev_b32_e32 v12, 16, v109
	v_and_b32_e32 v13, s98, v109
	v_lshlrev_b32_e32 v14, 16, v45
	v_and_b32_e32 v15, s98, v45
	v_pk_mul_f32 v[8:9], v[8:9], v[10:11]
	v_pk_mul_f32 v[12:13], v[12:13], v[14:15]
	v_cvt_pk_bf16_f32 v44, v8, v9
	v_cvt_pk_bf16_f32 v45, v12, v13
	v_lshlrev_b32_e32 v8, 16, v110
	v_and_b32_e32 v9, s98, v110
	v_lshlrev_b32_e32 v10, 16, v46
	v_and_b32_e32 v11, s98, v46
	v_lshlrev_b32_e32 v12, 16, v111
	v_and_b32_e32 v13, s98, v111
	v_lshlrev_b32_e32 v14, 16, v47
	v_and_b32_e32 v15, s98, v47
	v_pk_mul_f32 v[8:9], v[8:9], v[10:11]
	v_pk_mul_f32 v[12:13], v[12:13], v[14:15]
	v_cvt_pk_bf16_f32 v46, v8, v9
	v_cvt_pk_bf16_f32 v47, v12, v13
	ds_read_b128 v[108:111], v5 offset:25344
	v_add_u32_e32 v7, 0x18000, v3
	global_store_dwordx4 v7, v[44:47], s[54:55]
	s_waitcnt vmcnt(15) lgkmcnt(7)
	v_lshlrev_b32_e32 v8, 16, v112
	v_and_b32_e32 v9, s98, v112
	v_lshlrev_b32_e32 v10, 16, v48
	v_and_b32_e32 v11, s98, v48
	v_lshlrev_b32_e32 v12, 16, v113
	v_and_b32_e32 v13, s98, v113
	v_lshlrev_b32_e32 v14, 16, v49
	v_and_b32_e32 v15, s98, v49
	v_pk_mul_f32 v[8:9], v[8:9], v[10:11]
	v_pk_mul_f32 v[12:13], v[12:13], v[14:15]
	v_cvt_pk_bf16_f32 v48, v8, v9
	v_cvt_pk_bf16_f32 v49, v12, v13
	v_lshlrev_b32_e32 v8, 16, v114
	v_and_b32_e32 v9, s98, v114
	v_lshlrev_b32_e32 v10, 16, v50
	v_and_b32_e32 v11, s98, v50
	v_lshlrev_b32_e32 v12, 16, v115
	v_and_b32_e32 v13, s98, v115
	v_lshlrev_b32_e32 v14, 16, v51
	v_and_b32_e32 v15, s98, v51
	v_pk_mul_f32 v[8:9], v[8:9], v[10:11]
	v_pk_mul_f32 v[12:13], v[12:13], v[14:15]
	v_cvt_pk_bf16_f32 v50, v8, v9
	v_cvt_pk_bf16_f32 v51, v12, v13
	ds_read_b128 v[112:115], v5 offset:33792
	v_add_u32_e32 v7, 0x20000, v3
	global_store_dwordx4 v7, v[48:51], s[54:55]
	s_waitcnt vmcnt(15) lgkmcnt(7)
	v_lshlrev_b32_e32 v8, 16, v116
	v_and_b32_e32 v9, s98, v116
	v_lshlrev_b32_e32 v10, 16, v52
	v_and_b32_e32 v11, s98, v52
	v_lshlrev_b32_e32 v12, 16, v117
	v_and_b32_e32 v13, s98, v117
	v_lshlrev_b32_e32 v14, 16, v53
	v_and_b32_e32 v15, s98, v53
	v_pk_mul_f32 v[8:9], v[8:9], v[10:11]
	v_pk_mul_f32 v[12:13], v[12:13], v[14:15]
	v_cvt_pk_bf16_f32 v52, v8, v9
	v_cvt_pk_bf16_f32 v53, v12, v13
	v_lshlrev_b32_e32 v8, 16, v118
	v_and_b32_e32 v9, s98, v118
	v_lshlrev_b32_e32 v10, 16, v54
	v_and_b32_e32 v11, s98, v54
	v_lshlrev_b32_e32 v12, 16, v119
	v_and_b32_e32 v13, s98, v119
	v_lshlrev_b32_e32 v14, 16, v55
	v_and_b32_e32 v15, s98, v55
	v_pk_mul_f32 v[8:9], v[8:9], v[10:11]
	v_pk_mul_f32 v[12:13], v[12:13], v[14:15]
	v_cvt_pk_bf16_f32 v54, v8, v9
	v_cvt_pk_bf16_f32 v55, v12, v13
	ds_read_b128 v[116:119], v5 offset:42240
	v_add_u32_e32 v7, 0x28000, v3
	global_store_dwordx4 v7, v[52:55], s[54:55]
	s_waitcnt vmcnt(15) lgkmcnt(7)
	v_lshlrev_b32_e32 v8, 16, v120
	v_and_b32_e32 v9, s98, v120
	v_lshlrev_b32_e32 v10, 16, v56
	v_and_b32_e32 v11, s98, v56
	v_lshlrev_b32_e32 v12, 16, v121
	v_and_b32_e32 v13, s98, v121
	v_lshlrev_b32_e32 v14, 16, v57
	v_and_b32_e32 v15, s98, v57
	v_pk_mul_f32 v[8:9], v[8:9], v[10:11]
	v_pk_mul_f32 v[12:13], v[12:13], v[14:15]
	v_cvt_pk_bf16_f32 v56, v8, v9
	v_cvt_pk_bf16_f32 v57, v12, v13
	v_lshlrev_b32_e32 v8, 16, v122
	v_and_b32_e32 v9, s98, v122
	v_lshlrev_b32_e32 v10, 16, v58
	v_and_b32_e32 v11, s98, v58
	v_lshlrev_b32_e32 v12, 16, v123
	v_and_b32_e32 v13, s98, v123
	v_lshlrev_b32_e32 v14, 16, v59
	v_and_b32_e32 v15, s98, v59
	v_pk_mul_f32 v[8:9], v[8:9], v[10:11]
	v_pk_mul_f32 v[12:13], v[12:13], v[14:15]
	v_cvt_pk_bf16_f32 v58, v8, v9
	v_cvt_pk_bf16_f32 v59, v12, v13
	ds_read_b128 v[120:123], v5 offset:50688
	v_add_u32_e32 v7, 0x30000, v3
	global_store_dwordx4 v7, v[56:59], s[54:55]
	s_waitcnt vmcnt(15) lgkmcnt(7)
	v_lshlrev_b32_e32 v8, 16, v124
	v_and_b32_e32 v9, s98, v124
	v_lshlrev_b32_e32 v10, 16, v60
	v_and_b32_e32 v11, s98, v60
	v_lshlrev_b32_e32 v12, 16, v125
	v_and_b32_e32 v13, s98, v125
	v_lshlrev_b32_e32 v14, 16, v61
	v_and_b32_e32 v15, s98, v61
	v_pk_mul_f32 v[8:9], v[8:9], v[10:11]
	v_pk_mul_f32 v[12:13], v[12:13], v[14:15]
	v_cvt_pk_bf16_f32 v60, v8, v9
	v_cvt_pk_bf16_f32 v61, v12, v13
	v_lshlrev_b32_e32 v8, 16, v126
	v_and_b32_e32 v9, s98, v126
	v_lshlrev_b32_e32 v10, 16, v62
	v_and_b32_e32 v11, s98, v62
	v_lshlrev_b32_e32 v12, 16, v127
	v_and_b32_e32 v13, s98, v127
	v_lshlrev_b32_e32 v14, 16, v63
	v_and_b32_e32 v15, s98, v63
	v_pk_mul_f32 v[8:9], v[8:9], v[10:11]
	v_pk_mul_f32 v[12:13], v[12:13], v[14:15]
	v_cvt_pk_bf16_f32 v62, v8, v9
	v_cvt_pk_bf16_f32 v63, v12, v13
	ds_read_b128 v[124:127], v5 offset:59136
	v_add_u32_e32 v7, 0x38000, v3
	global_store_dwordx4 v7, v[60:63], s[54:55]
	s_waitcnt vmcnt(15) lgkmcnt(7)
	v_lshlrev_b32_e32 v8, 16, v96
	v_and_b32_e32 v9, s98, v96
	v_lshlrev_b32_e32 v10, 16, v64
	v_and_b32_e32 v11, s98, v64
	v_lshlrev_b32_e32 v12, 16, v97
	v_and_b32_e32 v13, s98, v97
	v_lshlrev_b32_e32 v14, 16, v65
	v_and_b32_e32 v15, s98, v65
	v_pk_mul_f32 v[8:9], v[8:9], v[10:11]
	v_pk_mul_f32 v[12:13], v[12:13], v[14:15]
	v_cvt_pk_bf16_f32 v64, v8, v9
	v_cvt_pk_bf16_f32 v65, v12, v13
	v_lshlrev_b32_e32 v8, 16, v98
	v_and_b32_e32 v9, s98, v98
	v_lshlrev_b32_e32 v10, 16, v66
	v_and_b32_e32 v11, s98, v66
	v_lshlrev_b32_e32 v12, 16, v99
	v_and_b32_e32 v13, s98, v99
	v_lshlrev_b32_e32 v14, 16, v67
	v_and_b32_e32 v15, s98, v67
	v_pk_mul_f32 v[8:9], v[8:9], v[10:11]
	v_pk_mul_f32 v[12:13], v[12:13], v[14:15]
	v_cvt_pk_bf16_f32 v66, v8, v9
	v_cvt_pk_bf16_f32 v67, v12, v13
	v_add_u32_e32 v7, 0x40000, v3
	global_store_dwordx4 v7, v[64:67], s[54:55]
	s_waitcnt vmcnt(15) lgkmcnt(6)
	v_lshlrev_b32_e32 v8, 16, v100
	v_and_b32_e32 v9, s98, v100
	v_lshlrev_b32_e32 v10, 16, v68
	v_and_b32_e32 v11, s98, v68
	v_lshlrev_b32_e32 v12, 16, v101
	v_and_b32_e32 v13, s98, v101
	v_lshlrev_b32_e32 v14, 16, v69
	v_and_b32_e32 v15, s98, v69
	v_pk_mul_f32 v[8:9], v[8:9], v[10:11]
	v_pk_mul_f32 v[12:13], v[12:13], v[14:15]
	v_cvt_pk_bf16_f32 v68, v8, v9
	v_cvt_pk_bf16_f32 v69, v12, v13
	v_lshlrev_b32_e32 v8, 16, v102
	v_and_b32_e32 v9, s98, v102
	v_lshlrev_b32_e32 v10, 16, v70
	v_and_b32_e32 v11, s98, v70
	v_lshlrev_b32_e32 v12, 16, v103
	v_and_b32_e32 v13, s98, v103
	v_lshlrev_b32_e32 v14, 16, v71
	v_and_b32_e32 v15, s98, v71
	v_pk_mul_f32 v[8:9], v[8:9], v[10:11]
	v_pk_mul_f32 v[12:13], v[12:13], v[14:15]
	v_cvt_pk_bf16_f32 v70, v8, v9
	v_cvt_pk_bf16_f32 v71, v12, v13
	v_add_u32_e32 v7, 0x48000, v3
	global_store_dwordx4 v7, v[68:71], s[54:55]
	s_waitcnt vmcnt(15) lgkmcnt(5)
	v_lshlrev_b32_e32 v8, 16, v104
	v_and_b32_e32 v9, s98, v104
	v_lshlrev_b32_e32 v10, 16, v72
	v_and_b32_e32 v11, s98, v72
	v_lshlrev_b32_e32 v12, 16, v105
	v_and_b32_e32 v13, s98, v105
	v_lshlrev_b32_e32 v14, 16, v73
	v_and_b32_e32 v15, s98, v73
	v_pk_mul_f32 v[8:9], v[8:9], v[10:11]
	v_pk_mul_f32 v[12:13], v[12:13], v[14:15]
	v_cvt_pk_bf16_f32 v72, v8, v9
	v_cvt_pk_bf16_f32 v73, v12, v13
	v_lshlrev_b32_e32 v8, 16, v106
	v_and_b32_e32 v9, s98, v106
	v_lshlrev_b32_e32 v10, 16, v74
	v_and_b32_e32 v11, s98, v74
	v_lshlrev_b32_e32 v12, 16, v107
	v_and_b32_e32 v13, s98, v107
	v_lshlrev_b32_e32 v14, 16, v75
	v_and_b32_e32 v15, s98, v75
	v_pk_mul_f32 v[8:9], v[8:9], v[10:11]
	v_pk_mul_f32 v[12:13], v[12:13], v[14:15]
	v_cvt_pk_bf16_f32 v74, v8, v9
	v_cvt_pk_bf16_f32 v75, v12, v13
	v_add_u32_e32 v7, 0x50000, v3
	global_store_dwordx4 v7, v[72:75], s[54:55]
	s_waitcnt vmcnt(15) lgkmcnt(4)
	v_lshlrev_b32_e32 v8, 16, v108
	v_and_b32_e32 v9, s98, v108
	v_lshlrev_b32_e32 v10, 16, v76
	v_and_b32_e32 v11, s98, v76
	v_lshlrev_b32_e32 v12, 16, v109
	v_and_b32_e32 v13, s98, v109
	v_lshlrev_b32_e32 v14, 16, v77
	v_and_b32_e32 v15, s98, v77
	v_pk_mul_f32 v[8:9], v[8:9], v[10:11]
	v_pk_mul_f32 v[12:13], v[12:13], v[14:15]
	v_cvt_pk_bf16_f32 v76, v8, v9
	v_cvt_pk_bf16_f32 v77, v12, v13
	v_lshlrev_b32_e32 v8, 16, v110
	v_and_b32_e32 v9, s98, v110
	v_lshlrev_b32_e32 v10, 16, v78
	v_and_b32_e32 v11, s98, v78
	v_lshlrev_b32_e32 v12, 16, v111
	v_and_b32_e32 v13, s98, v111
	v_lshlrev_b32_e32 v14, 16, v79
	v_and_b32_e32 v15, s98, v79
	v_pk_mul_f32 v[8:9], v[8:9], v[10:11]
	v_pk_mul_f32 v[12:13], v[12:13], v[14:15]
	v_cvt_pk_bf16_f32 v78, v8, v9
	v_cvt_pk_bf16_f32 v79, v12, v13
	v_add_u32_e32 v7, 0x58000, v3
	global_store_dwordx4 v7, v[76:79], s[54:55]
	s_waitcnt vmcnt(15) lgkmcnt(3)
	v_lshlrev_b32_e32 v8, 16, v112
	v_and_b32_e32 v9, s98, v112
	v_lshlrev_b32_e32 v10, 16, v80
	v_and_b32_e32 v11, s98, v80
	v_lshlrev_b32_e32 v12, 16, v113
	v_and_b32_e32 v13, s98, v113
	v_lshlrev_b32_e32 v14, 16, v81
	v_and_b32_e32 v15, s98, v81
	v_pk_mul_f32 v[8:9], v[8:9], v[10:11]
	v_pk_mul_f32 v[12:13], v[12:13], v[14:15]
	v_cvt_pk_bf16_f32 v80, v8, v9
	v_cvt_pk_bf16_f32 v81, v12, v13
	v_lshlrev_b32_e32 v8, 16, v114
	v_and_b32_e32 v9, s98, v114
	v_lshlrev_b32_e32 v10, 16, v82
	v_and_b32_e32 v11, s98, v82
	v_lshlrev_b32_e32 v12, 16, v115
	v_and_b32_e32 v13, s98, v115
	v_lshlrev_b32_e32 v14, 16, v83
	v_and_b32_e32 v15, s98, v83
	v_pk_mul_f32 v[8:9], v[8:9], v[10:11]
	v_pk_mul_f32 v[12:13], v[12:13], v[14:15]
	v_cvt_pk_bf16_f32 v82, v8, v9
	v_cvt_pk_bf16_f32 v83, v12, v13
	v_add_u32_e32 v7, 0x60000, v3
	global_store_dwordx4 v7, v[80:83], s[54:55]
	s_waitcnt vmcnt(15) lgkmcnt(2)
	v_lshlrev_b32_e32 v8, 16, v116
	v_and_b32_e32 v9, s98, v116
	v_lshlrev_b32_e32 v10, 16, v84
	v_and_b32_e32 v11, s98, v84
	v_lshlrev_b32_e32 v12, 16, v117
	v_and_b32_e32 v13, s98, v117
	v_lshlrev_b32_e32 v14, 16, v85
	v_and_b32_e32 v15, s98, v85
	v_pk_mul_f32 v[8:9], v[8:9], v[10:11]
	v_pk_mul_f32 v[12:13], v[12:13], v[14:15]
	v_cvt_pk_bf16_f32 v84, v8, v9
	v_cvt_pk_bf16_f32 v85, v12, v13
	v_lshlrev_b32_e32 v8, 16, v118
	v_and_b32_e32 v9, s98, v118
	v_lshlrev_b32_e32 v10, 16, v86
	v_and_b32_e32 v11, s98, v86
	v_lshlrev_b32_e32 v12, 16, v119
	v_and_b32_e32 v13, s98, v119
	v_lshlrev_b32_e32 v14, 16, v87
	v_and_b32_e32 v15, s98, v87
	v_pk_mul_f32 v[8:9], v[8:9], v[10:11]
	v_pk_mul_f32 v[12:13], v[12:13], v[14:15]
	v_cvt_pk_bf16_f32 v86, v8, v9
	v_cvt_pk_bf16_f32 v87, v12, v13
	v_add_u32_e32 v7, 0x68000, v3
	global_store_dwordx4 v7, v[84:87], s[54:55]
	s_waitcnt vmcnt(15) lgkmcnt(1)
	v_lshlrev_b32_e32 v8, 16, v120
	v_and_b32_e32 v9, s98, v120
	v_lshlrev_b32_e32 v10, 16, v88
	v_and_b32_e32 v11, s98, v88
	v_lshlrev_b32_e32 v12, 16, v121
	v_and_b32_e32 v13, s98, v121
	v_lshlrev_b32_e32 v14, 16, v89
	v_and_b32_e32 v15, s98, v89
	v_pk_mul_f32 v[8:9], v[8:9], v[10:11]
	v_pk_mul_f32 v[12:13], v[12:13], v[14:15]
	v_cvt_pk_bf16_f32 v88, v8, v9
	v_cvt_pk_bf16_f32 v89, v12, v13
	v_lshlrev_b32_e32 v8, 16, v122
	v_and_b32_e32 v9, s98, v122
	v_lshlrev_b32_e32 v10, 16, v90
	v_and_b32_e32 v11, s98, v90
	v_lshlrev_b32_e32 v12, 16, v123
	v_and_b32_e32 v13, s98, v123
	v_lshlrev_b32_e32 v14, 16, v91
	v_and_b32_e32 v15, s98, v91
	v_pk_mul_f32 v[8:9], v[8:9], v[10:11]
	v_pk_mul_f32 v[12:13], v[12:13], v[14:15]
	v_cvt_pk_bf16_f32 v90, v8, v9
	v_cvt_pk_bf16_f32 v91, v12, v13
	v_add_u32_e32 v7, 0x70000, v3
	global_store_dwordx4 v7, v[88:91], s[54:55]
	s_waitcnt vmcnt(15) lgkmcnt(0)
	v_lshlrev_b32_e32 v8, 16, v124
	v_and_b32_e32 v9, s98, v124
	v_lshlrev_b32_e32 v10, 16, v92
	v_and_b32_e32 v11, s98, v92
	v_lshlrev_b32_e32 v12, 16, v125
	v_and_b32_e32 v13, s98, v125
	v_lshlrev_b32_e32 v14, 16, v93
	v_and_b32_e32 v15, s98, v93
	v_pk_mul_f32 v[8:9], v[8:9], v[10:11]
	v_pk_mul_f32 v[12:13], v[12:13], v[14:15]
	v_cvt_pk_bf16_f32 v92, v8, v9
	v_cvt_pk_bf16_f32 v93, v12, v13
	v_lshlrev_b32_e32 v8, 16, v126
	v_and_b32_e32 v9, s98, v126
	v_lshlrev_b32_e32 v10, 16, v94
	v_and_b32_e32 v11, s98, v94
	v_lshlrev_b32_e32 v12, 16, v127
	v_and_b32_e32 v13, s98, v127
	v_lshlrev_b32_e32 v14, 16, v95
	v_and_b32_e32 v15, s98, v95
	v_pk_mul_f32 v[8:9], v[8:9], v[10:11]
	v_pk_mul_f32 v[12:13], v[12:13], v[14:15]
	v_cvt_pk_bf16_f32 v94, v8, v9
	v_cvt_pk_bf16_f32 v95, v12, v13
	v_add_u32_e32 v7, 0x78000, v3
	global_store_dwordx4 v7, v[92:95], s[54:55]
	s_movk_i32 s68, 0x2000
	s_add_i32 s72, s72, 1
	s_add_u32 s66, s66, 0x40000
	s_addc_u32 s67, s67, 0
	s_cmp_eq_u32 s72, 4
	s_cbranch_scc0 .LBB0_993
	s_lshl_b64 s[62:63], s[58:59], 2
	s_add_u32 s3, s50, s62
	s_addc_u32 s16, s51, s63
	s_add_u32 s64, s3, 0x18000000
	s_addc_u32 s65, s16, 0
	s_add_u32 s16, s50, 0xb00000
	s_addc_u32 s72, s51, 0
	s_mov_b32 s73, 0
	s_mov_b64 s[66:67], s[50:51]

.LBB0_1004:
	s_and_b32 s70, s84, 0x10000
	v_add_u32_e32 v132, s70, v142
	v_or_b32_e32 v170, s70, v143
	ds_read_b128 v[150:153], v132
	ds_read_b128 v[154:157], v132 offset:4096
	ds_read_b128 v[158:161], v132 offset:8192
	ds_read_b128 v[162:165], v132 offset:12288
	ds_read_b128 v[166:169], v170
	ds_read_b128 v[172:175], v170 offset:4096
	v_add_u32_e32 v214, s70, v144
	v_or_b32_e32 v215, s70, v145
	ds_read_b128 v[216:219], v214
	ds_read_b128 v[220:223], v214 offset:4096
	ds_read_b128 v[224:227], v214 offset:8192
	ds_read_b128 v[228:231], v214 offset:12288
	ds_read_b128 v[232:235], v215
	ds_read_b128 v[236:239], v215 offset:4096
	v_add_u32_e32 v132, s70, v146
	v_or_b32_e32 v170, s70, v147
	s_waitcnt lgkmcnt(6)
	v_mfma_f32_32x32x16_bf16 v[112:127], v[166:169], v[150:153], v[112:127]
	s_add_u32 s68, s68, 0x80
	s_addc_u32 s69, s69, 0
	s_add_i32 s3, s3, 1
	s_cmpk_lg_i32 s68, 0x800
	s_mov_b32 s84, s85
	v_mfma_f32_32x32x16_bf16 v[80:95], v[166:169], v[154:157], v[80:95]
	v_mfma_f32_32x32x16_bf16 v[48:63], v[166:169], v[158:161], v[48:63]
	v_mfma_f32_32x32x16_bf16 v[16:31], v[166:169], v[162:165], v[16:31]
	v_mfma_f32_32x32x16_bf16 v[96:111], v[172:175], v[150:153], v[96:111]
	v_mfma_f32_32x32x16_bf16 v[64:79], v[172:175], v[154:157], v[64:79]
	v_mfma_f32_32x32x16_bf16 v[32:47], v[172:175], v[158:161], v[32:47]
	v_mfma_f32_32x32x16_bf16 v[0:15], v[172:175], v[162:165], v[0:15]
	ds_read_b128 v[150:153], v132
	ds_read_b128 v[154:157], v132 offset:4096
	ds_read_b128 v[158:161], v132 offset:8192
	ds_read_b128 v[162:165], v132 offset:12288
	ds_read_b128 v[166:169], v170
	ds_read_b128 v[172:175], v170 offset:4096
	v_add_u32_e32 v214, s70, v148
	v_or_b32_e32 v215, s70, v149
	s_waitcnt lgkmcnt(6)
	v_mfma_f32_32x32x16_bf16 v[112:127], v[232:235], v[216:219], v[112:127]
	v_mfma_f32_32x32x16_bf16 v[80:95], v[232:235], v[220:223], v[80:95]
	v_mfma_f32_32x32x16_bf16 v[48:63], v[232:235], v[224:227], v[48:63]
	v_mfma_f32_32x32x16_bf16 v[16:31], v[232:235], v[228:231], v[16:31]
	v_mfma_f32_32x32x16_bf16 v[96:111], v[236:239], v[216:219], v[96:111]
	v_mfma_f32_32x32x16_bf16 v[64:79], v[236:239], v[220:223], v[64:79]
	v_mfma_f32_32x32x16_bf16 v[32:47], v[236:239], v[224:227], v[32:47]
	v_mfma_f32_32x32x16_bf16 v[0:15], v[236:239], v[228:231], v[0:15]
	ds_read_b128 v[216:219], v214
	ds_read_b128 v[220:223], v214 offset:4096
	ds_read_b128 v[224:227], v214 offset:8192
	ds_read_b128 v[228:231], v214 offset:12288
	ds_read_b128 v[232:235], v215
	ds_read_b128 v[236:239], v215 offset:4096
	s_waitcnt lgkmcnt(6)
	v_mfma_f32_32x32x16_bf16 v[112:127], v[166:169], v[150:153], v[112:127]
	v_mfma_f32_32x32x16_bf16 v[80:95], v[166:169], v[154:157], v[80:95]
	v_mfma_f32_32x32x16_bf16 v[48:63], v[166:169], v[158:161], v[48:63]
	v_mfma_f32_32x32x16_bf16 v[16:31], v[166:169], v[162:165], v[16:31]
	v_mfma_f32_32x32x16_bf16 v[96:111], v[172:175], v[150:153], v[96:111]
	v_mfma_f32_32x32x16_bf16 v[64:79], v[172:175], v[154:157], v[64:79]
	v_mfma_f32_32x32x16_bf16 v[32:47], v[172:175], v[158:161], v[32:47]
	v_mfma_f32_32x32x16_bf16 v[0:15], v[172:175], v[162:165], v[0:15]
	s_waitcnt lgkmcnt(0)
	v_mfma_f32_32x32x16_bf16 v[112:127], v[232:235], v[216:219], v[112:127]
	v_mfma_f32_32x32x16_bf16 v[80:95], v[232:235], v[220:223], v[80:95]
	v_mfma_f32_32x32x16_bf16 v[48:63], v[232:235], v[224:227], v[48:63]
	v_mfma_f32_32x32x16_bf16 v[16:31], v[232:235], v[228:231], v[16:31]
	v_mfma_f32_32x32x16_bf16 v[96:111], v[236:239], v[216:219], v[96:111]
	v_mfma_f32_32x32x16_bf16 v[64:79], v[236:239], v[220:223], v[64:79]
	v_mfma_f32_32x32x16_bf16 v[32:47], v[236:239], v[224:227], v[32:47]
	v_mfma_f32_32x32x16_bf16 v[0:15], v[236:239], v[228:231], v[0:15]
	s_cbranch_scc0 .LBB0_1009

.LBB0_1014:
	s_and_b32 s72, s88, 0x10000
	v_add_u32_e32 v132, s72, v142
	v_or_b32_e32 v170, s72, v143
	ds_read_b128 v[150:153], v132
	ds_read_b128 v[154:157], v132 offset:4096
	ds_read_b128 v[158:161], v132 offset:8192
	ds_read_b128 v[162:165], v132 offset:12288
	ds_read_b128 v[166:169], v170
	ds_read_b128 v[172:175], v170 offset:4096
	v_add_u32_e32 v214, s72, v144
	v_or_b32_e32 v215, s72, v145
	ds_read_b128 v[216:219], v214
	ds_read_b128 v[220:223], v214 offset:4096
	ds_read_b128 v[224:227], v214 offset:8192
	ds_read_b128 v[228:231], v214 offset:12288
	ds_read_b128 v[232:235], v215
	ds_read_b128 v[236:239], v215 offset:4096
	v_add_u32_e32 v132, s72, v146
	v_or_b32_e32 v170, s72, v147
	s_waitcnt lgkmcnt(6)
	v_mfma_f32_32x32x16_bf16 v[112:127], v[166:169], v[150:153], v[112:127]
	s_add_u32 s70, s70, 0x80
	s_addc_u32 s71, s71, 0
	s_add_i32 s85, s85, 1
	s_cmpk_lg_i32 s70, 0x800
	s_mov_b32 s88, s89
	v_mfma_f32_32x32x16_bf16 v[96:111], v[166:169], v[154:157], v[96:111]
	v_mfma_f32_32x32x16_bf16 v[64:79], v[166:169], v[158:161], v[64:79]
	v_mfma_f32_32x32x16_bf16 v[32:47], v[166:169], v[162:165], v[32:47]
	v_mfma_f32_32x32x16_bf16 v[80:95], v[172:175], v[150:153], v[80:95]
	v_mfma_f32_32x32x16_bf16 v[48:63], v[172:175], v[154:157], v[48:63]
	v_mfma_f32_32x32x16_bf16 v[16:31], v[172:175], v[158:161], v[16:31]
	v_mfma_f32_32x32x16_bf16 v[0:15], v[172:175], v[162:165], v[0:15]
	ds_read_b128 v[150:153], v132
	ds_read_b128 v[154:157], v132 offset:4096
	ds_read_b128 v[158:161], v132 offset:8192
	ds_read_b128 v[162:165], v132 offset:12288
	ds_read_b128 v[166:169], v170
	ds_read_b128 v[172:175], v170 offset:4096
	v_add_u32_e32 v214, s72, v148
	v_or_b32_e32 v215, s72, v149
	s_waitcnt lgkmcnt(6)
	v_mfma_f32_32x32x16_bf16 v[112:127], v[232:235], v[216:219], v[112:127]
	v_mfma_f32_32x32x16_bf16 v[96:111], v[232:235], v[220:223], v[96:111]
	v_mfma_f32_32x32x16_bf16 v[64:79], v[232:235], v[224:227], v[64:79]
	v_mfma_f32_32x32x16_bf16 v[32:47], v[232:235], v[228:231], v[32:47]
	v_mfma_f32_32x32x16_bf16 v[80:95], v[236:239], v[216:219], v[80:95]
	v_mfma_f32_32x32x16_bf16 v[48:63], v[236:239], v[220:223], v[48:63]
	v_mfma_f32_32x32x16_bf16 v[16:31], v[236:239], v[224:227], v[16:31]
	v_mfma_f32_32x32x16_bf16 v[0:15], v[236:239], v[228:231], v[0:15]
	ds_read_b128 v[216:219], v214
	ds_read_b128 v[220:223], v214 offset:4096
	ds_read_b128 v[224:227], v214 offset:8192
	ds_read_b128 v[228:231], v214 offset:12288
	ds_read_b128 v[232:235], v215
	ds_read_b128 v[236:239], v215 offset:4096
	s_waitcnt lgkmcnt(6)
	v_mfma_f32_32x32x16_bf16 v[112:127], v[166:169], v[150:153], v[112:127]
	v_mfma_f32_32x32x16_bf16 v[96:111], v[166:169], v[154:157], v[96:111]
	v_mfma_f32_32x32x16_bf16 v[64:79], v[166:169], v[158:161], v[64:79]
	v_mfma_f32_32x32x16_bf16 v[32:47], v[166:169], v[162:165], v[32:47]
	v_mfma_f32_32x32x16_bf16 v[80:95], v[172:175], v[150:153], v[80:95]
	v_mfma_f32_32x32x16_bf16 v[48:63], v[172:175], v[154:157], v[48:63]
	v_mfma_f32_32x32x16_bf16 v[16:31], v[172:175], v[158:161], v[16:31]
	v_mfma_f32_32x32x16_bf16 v[0:15], v[172:175], v[162:165], v[0:15]
	s_waitcnt lgkmcnt(0)
	v_mfma_f32_32x32x16_bf16 v[112:127], v[232:235], v[216:219], v[112:127]
	v_mfma_f32_32x32x16_bf16 v[96:111], v[232:235], v[220:223], v[96:111]
	v_mfma_f32_32x32x16_bf16 v[64:79], v[232:235], v[224:227], v[64:79]
	v_mfma_f32_32x32x16_bf16 v[32:47], v[232:235], v[228:231], v[32:47]
	v_mfma_f32_32x32x16_bf16 v[80:95], v[236:239], v[216:219], v[80:95]
	v_mfma_f32_32x32x16_bf16 v[48:63], v[236:239], v[220:223], v[48:63]
	v_mfma_f32_32x32x16_bf16 v[16:31], v[236:239], v[224:227], v[16:31]
	v_mfma_f32_32x32x16_bf16 v[0:15], v[236:239], v[228:231], v[0:15]
	s_cbranch_scc0 .LBB0_1019

.LBB0_1019:
	v_mov_b32_e32 v128, v176
	s_waitcnt vmcnt(0) lgkmcnt(0)
	s_barrier
	s_nop 4
	v_cvt_pk_bf16_f32 v80, v80, v81
	v_and_b32_e32 v129, 0xc0, v128
	v_and_b32_e32 v130, 31, v128
	v_lshrrev_b32_e32 v131, 1, v128
	v_lshrrev_b32_e32 v128, 2, v128
	v_and_b32_e32 v128, 8, v128
	v_and_or_b32 v130, v131, s93, v130
	v_lshl_or_b32 v128, v129, 1, v128
	v_mad_u64_u32 v[128:129], s[70:71], v130, s0, v[128:129]
	v_cvt_pk_bf16_f32 v81, v82, v83
	v_cvt_pk_bf16_f32 v82, v84, v85
	v_cvt_pk_bf16_f32 v83, v86, v87
	v_add_u32_e32 v84, 0x4000, v128
	v_cvt_pk_bf16_f32 v48, v48, v49
	v_cvt_pk_bf16_f32 v49, v50, v51
	v_cvt_pk_bf16_f32 v50, v52, v53
	v_cvt_pk_bf16_f32 v51, v54, v55
	v_add_u32_e32 v52, 0x8000, v128
	v_cvt_pk_bf16_f32 v16, v16, v17
	v_cvt_pk_bf16_f32 v17, v18, v19
	v_cvt_pk_bf16_f32 v18, v20, v21
	v_cvt_pk_bf16_f32 v19, v22, v23
	ds_write2_b64 v128, v[80:81], v[82:83] offset0:8 offset1:10
	v_cvt_pk_bf16_f32 v80, v88, v89
	v_cvt_pk_bf16_f32 v81, v90, v91
	v_cvt_pk_bf16_f32 v82, v92, v93
	v_cvt_pk_bf16_f32 v83, v94, v95
	ds_write2_b64 v84, v[48:49], v[50:51] offset0:72 offset1:74
	v_cvt_pk_bf16_f32 v48, v56, v57
	v_cvt_pk_bf16_f32 v49, v58, v59
	v_cvt_pk_bf16_f32 v50, v60, v61
	v_cvt_pk_bf16_f32 v51, v62, v63
	ds_write2_b64 v52, v[16:17], v[18:19] offset0:136 offset1:138
	v_cvt_pk_bf16_f32 v16, v24, v25
	v_cvt_pk_bf16_f32 v17, v26, v27
	v_cvt_pk_bf16_f32 v18, v28, v29
	v_cvt_pk_bf16_f32 v19, v30, v31
	v_cvt_pk_bf16_f32 v112, v112, v113
	v_cvt_pk_bf16_f32 v113, v114, v115
	v_cvt_pk_bf16_f32 v114, v116, v117
	v_cvt_pk_bf16_f32 v115, v118, v119
	ds_write2_b64 v128, v[80:81], v[82:83] offset0:12 offset1:14
	v_cvt_pk_bf16_f32 v80, v96, v97
	v_cvt_pk_bf16_f32 v81, v98, v99
	v_cvt_pk_bf16_f32 v82, v100, v101
	v_cvt_pk_bf16_f32 v83, v102, v103
	ds_write2_b64 v84, v[48:49], v[50:51] offset0:76 offset1:78
	v_cvt_pk_bf16_f32 v48, v64, v65
	v_cvt_pk_bf16_f32 v49, v66, v67
	v_cvt_pk_bf16_f32 v50, v68, v69
	v_cvt_pk_bf16_f32 v51, v70, v71
	ds_write2_b64 v52, v[16:17], v[18:19] offset0:140 offset1:142
	v_cvt_pk_bf16_f32 v16, v32, v33
	v_cvt_pk_bf16_f32 v17, v34, v35
	v_cvt_pk_bf16_f32 v18, v36, v37
	v_cvt_pk_bf16_f32 v19, v38, v39
	v_add_u32_e32 v20, 0xc000, v128
	v_cvt_pk_bf16_f32 v0, v0, v1
	v_cvt_pk_bf16_f32 v1, v2, v3
	v_cvt_pk_bf16_f32 v2, v4, v5
	v_cvt_pk_bf16_f32 v3, v6, v7
	ds_write2_b64 v128, v[112:113], v[114:115] offset1:2
	v_cvt_pk_bf16_f32 v112, v120, v121
	v_cvt_pk_bf16_f32 v113, v122, v123
	v_cvt_pk_bf16_f32 v114, v124, v125
	v_cvt_pk_bf16_f32 v115, v126, v127
	ds_write2_b64 v84, v[80:81], v[82:83] offset0:64 offset1:66
	v_cvt_pk_bf16_f32 v80, v104, v105
	v_cvt_pk_bf16_f32 v81, v106, v107
	v_cvt_pk_bf16_f32 v82, v108, v109
	v_cvt_pk_bf16_f32 v83, v110, v111
	ds_write2_b64 v52, v[48:49], v[50:51] offset0:128 offset1:130
	v_cvt_pk_bf16_f32 v48, v72, v73
	v_cvt_pk_bf16_f32 v49, v74, v75
	v_cvt_pk_bf16_f32 v50, v76, v77
	v_cvt_pk_bf16_f32 v51, v78, v79
	ds_write2_b64 v20, v[16:17], v[18:19] offset0:192 offset1:194
	v_cvt_pk_bf16_f32 v16, v40, v41
	v_cvt_pk_bf16_f32 v17, v42, v43
	v_cvt_pk_bf16_f32 v18, v44, v45
	v_cvt_pk_bf16_f32 v19, v46, v47
	ds_write2_b64 v20, v[0:1], v[2:3] offset0:200 offset1:202
	v_cvt_pk_bf16_f32 v0, v8, v9
	v_cvt_pk_bf16_f32 v1, v10, v11
	v_cvt_pk_bf16_f32 v2, v12, v13
	v_cvt_pk_bf16_f32 v3, v14, v15
	v_mov_b32_e32 v5, v176
	ds_write2_b64 v128, v[112:113], v[114:115] offset0:4 offset1:6
	ds_write2_b64 v84, v[80:81], v[82:83] offset0:68 offset1:70
	ds_write2_b64 v52, v[48:49], v[50:51] offset0:132 offset1:134
	ds_write2_b64 v20, v[16:17], v[18:19] offset0:196 offset1:198
	ds_write2_b64 v20, v[0:1], v[2:3] offset0:204 offset1:206
	s_waitcnt lgkmcnt(0)
	s_barrier
	v_mov_b32_e32 v1, v176
	s_mov_b32 s98, 0xffff0000
	v_lshlrev_b32_e32 v0, 4, v1
	v_and_b32_e32 v0, 0x1f0, v0
	v_lshrrev_b32_e32 v2, 5, v1
	v_mov_b32_e32 v6, 0x210
	v_mad_u32_u24 v4, v2, v6, v0
	v_add_u32_e32 v5, 0x10800, v4
	v_lshl_or_b32 v132, s84, 9, v0
	v_lshl_add_u32 v3, v2, 11, v132
	v_add_u32_e32 v6, 0x0, v3
	global_load_dwordx4 v[32:35], v6, s[54:55]
	global_load_dwordx4 v[36:39], v6, s[64:65]
	ds_read_b128 v[40:43], v4
	v_add_u32_e32 v6, 0x8000, v3
	global_load_dwordx4 v[44:47], v6, s[54:55]
	global_load_dwordx4 v[48:51], v6, s[64:65]
	ds_read_b128 v[52:55], v4 offset:8448
	v_add_u32_e32 v6, 0x10000, v3
	global_load_dwordx4 v[56:59], v6, s[54:55]
	global_load_dwordx4 v[60:63], v6, s[64:65]
	ds_read_b128 v[64:67], v4 offset:16896
	v_add_u32_e32 v6, 0x18000, v3
	global_load_dwordx4 v[68:71], v6, s[54:55]
	global_load_dwordx4 v[72:75], v6, s[64:65]
	ds_read_b128 v[76:79], v4 offset:25344
	v_add_u32_e32 v6, 0x20000, v3
	global_load_dwordx4 v[80:83], v6, s[54:55]
	global_load_dwordx4 v[84:87], v6, s[64:65]
	ds_read_b128 v[88:91], v4 offset:33792
	v_add_u32_e32 v6, 0x28000, v3
	global_load_dwordx4 v[92:95], v6, s[54:55]
	global_load_dwordx4 v[96:99], v6, s[64:65]
	ds_read_b128 v[100:103], v4 offset:42240
	v_add_u32_e32 v6, 0x30000, v3
	global_load_dwordx4 v[104:107], v6, s[54:55]
	global_load_dwordx4 v[108:111], v6, s[64:65]
	ds_read_b128 v[112:115], v4 offset:50688
	v_add_u32_e32 v6, 0x38000, v3
	global_load_dwordx4 v[116:119], v6, s[54:55]
	global_load_dwordx4 v[120:123], v6, s[64:65]
	ds_read_b128 v[124:127], v4 offset:59136
	s_waitcnt vmcnt(14) lgkmcnt(7)
	v_lshlrev_b32_e32 v8, 16, v40
	v_and_b32_e32 v9, s98, v40
	v_lshlrev_b32_e32 v10, 16, v36
	v_and_b32_e32 v11, s98, v36
	v_lshlrev_b32_e32 v12, 16, v32
	v_and_b32_e32 v13, s98, v32
	v_lshlrev_b32_e32 v14, 16, v41
	v_and_b32_e32 v15, s98, v41
	v_lshlrev_b32_e32 v16, 16, v37
	v_and_b32_e32 v17, s98, v37
	v_lshlrev_b32_e32 v18, 16, v33
	v_and_b32_e32 v19, s98, v33
	v_pk_fma_f32 v[12:13], v[8:9], v[10:11], v[12:13]
	v_pk_fma_f32 v[18:19], v[14:15], v[16:17], v[18:19]
	v_cvt_pk_bf16_f32 v32, v12, v13
	v_cvt_pk_bf16_f32 v33, v18, v19
	v_lshlrev_b32_e32 v8, 16, v42
	v_and_b32_e32 v9, s98, v42
	v_lshlrev_b32_e32 v10, 16, v38
	v_and_b32_e32 v11, s98, v38
	v_lshlrev_b32_e32 v12, 16, v34
	v_and_b32_e32 v13, s98, v34
	v_lshlrev_b32_e32 v14, 16, v43
	v_and_b32_e32 v15, s98, v43
	v_lshlrev_b32_e32 v16, 16, v39
	v_and_b32_e32 v17, s98, v39
	v_lshlrev_b32_e32 v18, 16, v35
	v_and_b32_e32 v19, s98, v35
	v_pk_fma_f32 v[12:13], v[8:9], v[10:11], v[12:13]
	v_pk_fma_f32 v[18:19], v[14:15], v[16:17], v[18:19]
	v_cvt_pk_bf16_f32 v34, v12, v13
	v_cvt_pk_bf16_f32 v35, v18, v19
	v_add_u32_e32 v6, 0x40000, v3
	global_load_dwordx4 v[36:39], v6, s[54:55]
	ds_read_b128 v[40:43], v5
	v_add_u32_e32 v7, 0x0, v3
	global_store_dwordx4 v7, v[32:35], s[54:55]
	s_nop 1
	global_load_dwordx4 v[32:35], v6, s[64:65]
	s_waitcnt vmcnt(15) lgkmcnt(7)
	v_lshlrev_b32_e32 v8, 16, v52
	v_and_b32_e32 v9, s98, v52
	v_lshlrev_b32_e32 v10, 16, v48
	v_and_b32_e32 v11, s98, v48
	v_lshlrev_b32_e32 v12, 16, v44
	v_and_b32_e32 v13, s98, v44
	v_lshlrev_b32_e32 v14, 16, v53
	v_and_b32_e32 v15, s98, v53
	v_lshlrev_b32_e32 v16, 16, v49
	v_and_b32_e32 v17, s98, v49
	v_lshlrev_b32_e32 v18, 16, v45
	v_and_b32_e32 v19, s98, v45
	v_pk_fma_f32 v[12:13], v[8:9], v[10:11], v[12:13]
	v_pk_fma_f32 v[18:19], v[14:15], v[16:17], v[18:19]
	v_cvt_pk_bf16_f32 v44, v12, v13
	v_cvt_pk_bf16_f32 v45, v18, v19
	v_lshlrev_b32_e32 v8, 16, v54
	v_and_b32_e32 v9, s98, v54
	v_lshlrev_b32_e32 v10, 16, v50
	v_and_b32_e32 v11, s98, v50
	v_lshlrev_b32_e32 v12, 16, v46
	v_and_b32_e32 v13, s98, v46
	v_lshlrev_b32_e32 v14, 16, v55
	v_and_b32_e32 v15, s98, v55
	v_lshlrev_b32_e32 v16, 16, v51
	v_and_b32_e32 v17, s98, v51
	v_lshlrev_b32_e32 v18, 16, v47
	v_and_b32_e32 v19, s98, v47
	v_pk_fma_f32 v[12:13], v[8:9], v[10:11], v[12:13]
	v_pk_fma_f32 v[18:19], v[14:15], v[16:17], v[18:19]
	v_cvt_pk_bf16_f32 v46, v12, v13
	v_cvt_pk_bf16_f32 v47, v18, v19
	v_add_u32_e32 v6, 0x48000, v3
	global_load_dwordx4 v[48:51], v6, s[54:55]
	ds_read_b128 v[52:55], v5 offset:8448
	v_add_u32_e32 v7, 0x8000, v3
	global_store_dwordx4 v7, v[44:47], s[54:55]
	s_nop 1
	global_load_dwordx4 v[44:47], v6, s[64:65]
	s_waitcnt vmcnt(16) lgkmcnt(7)
	v_lshlrev_b32_e32 v8, 16, v64
	v_and_b32_e32 v9, s98, v64
	v_lshlrev_b32_e32 v10, 16, v60
	v_and_b32_e32 v11, s98, v60
	v_lshlrev_b32_e32 v12, 16, v56
	v_and_b32_e32 v13, s98, v56
	v_lshlrev_b32_e32 v14, 16, v65
	v_and_b32_e32 v15, s98, v65
	v_lshlrev_b32_e32 v16, 16, v61
	v_and_b32_e32 v17, s98, v61
	v_lshlrev_b32_e32 v18, 16, v57
	v_and_b32_e32 v19, s98, v57
	v_pk_fma_f32 v[12:13], v[8:9], v[10:11], v[12:13]
	v_pk_fma_f32 v[18:19], v[14:15], v[16:17], v[18:19]
	v_cvt_pk_bf16_f32 v56, v12, v13
	v_cvt_pk_bf16_f32 v57, v18, v19
	v_lshlrev_b32_e32 v8, 16, v66
	v_and_b32_e32 v9, s98, v66
	v_lshlrev_b32_e32 v10, 16, v62
	v_and_b32_e32 v11, s98, v62
	v_lshlrev_b32_e32 v12, 16, v58
	v_and_b32_e32 v13, s98, v58
	v_lshlrev_b32_e32 v14, 16, v67
	v_and_b32_e32 v15, s98, v67
	v_lshlrev_b32_e32 v16, 16, v63
	v_and_b32_e32 v17, s98, v63
	v_lshlrev_b32_e32 v18, 16, v59
	v_and_b32_e32 v19, s98, v59
	v_pk_fma_f32 v[12:13], v[8:9], v[10:11], v[12:13]
	v_pk_fma_f32 v[18:19], v[14:15], v[16:17], v[18:19]
	v_cvt_pk_bf16_f32 v58, v12, v13
	v_cvt_pk_bf16_f32 v59, v18, v19
	v_add_u32_e32 v6, 0x50000, v3
	global_load_dwordx4 v[60:63], v6, s[54:55]
	ds_read_b128 v[64:67], v5 offset:16896
	v_add_u32_e32 v7, 0x10000, v3
	global_store_dwordx4 v7, v[56:59], s[54:55]
	s_nop 1
	global_load_dwordx4 v[56:59], v6, s[64:65]
	s_waitcnt vmcnt(17) lgkmcnt(7)
	v_lshlrev_b32_e32 v8, 16, v76
	v_and_b32_e32 v9, s98, v76
	v_lshlrev_b32_e32 v10, 16, v72
	v_and_b32_e32 v11, s98, v72
	v_lshlrev_b32_e32 v12, 16, v68
	v_and_b32_e32 v13, s98, v68
	v_lshlrev_b32_e32 v14, 16, v77
	v_and_b32_e32 v15, s98, v77
	v_lshlrev_b32_e32 v16, 16, v73
	v_and_b32_e32 v17, s98, v73
	v_lshlrev_b32_e32 v18, 16, v69
	v_and_b32_e32 v19, s98, v69
	v_pk_fma_f32 v[12:13], v[8:9], v[10:11], v[12:13]
	v_pk_fma_f32 v[18:19], v[14:15], v[16:17], v[18:19]
	v_cvt_pk_bf16_f32 v68, v12, v13
	v_cvt_pk_bf16_f32 v69, v18, v19
	v_lshlrev_b32_e32 v8, 16, v78
	v_and_b32_e32 v9, s98, v78
	v_lshlrev_b32_e32 v10, 16, v74
	v_and_b32_e32 v11, s98, v74
	v_lshlrev_b32_e32 v12, 16, v70
	v_and_b32_e32 v13, s98, v70
	v_lshlrev_b32_e32 v14, 16, v79
	v_and_b32_e32 v15, s98, v79
	v_lshlrev_b32_e32 v16, 16, v75
	v_and_b32_e32 v17, s98, v75
	v_lshlrev_b32_e32 v18, 16, v71
	v_and_b32_e32 v19, s98, v71
	v_pk_fma_f32 v[12:13], v[8:9], v[10:11], v[12:13]
	v_pk_fma_f32 v[18:19], v[14:15], v[16:17], v[18:19]
	v_cvt_pk_bf16_f32 v70, v12, v13
	v_cvt_pk_bf16_f32 v71, v18, v19
	v_add_u32_e32 v6, 0x58000, v3
	global_load_dwordx4 v[72:75], v6, s[54:55]
	ds_read_b128 v[76:79], v5 offset:25344
	v_add_u32_e32 v7, 0x18000, v3
	global_store_dwordx4 v7, v[68:71], s[54:55]
	s_nop 1
	global_load_dwordx4 v[68:71], v6, s[64:65]
	s_waitcnt vmcnt(18) lgkmcnt(7)
	v_lshlrev_b32_e32 v8, 16, v88
	v_and_b32_e32 v9, s98, v88
	v_lshlrev_b32_e32 v10, 16, v84
	v_and_b32_e32 v11, s98, v84
	v_lshlrev_b32_e32 v12, 16, v80
	v_and_b32_e32 v13, s98, v80
	v_lshlrev_b32_e32 v14, 16, v89
	v_and_b32_e32 v15, s98, v89
	v_lshlrev_b32_e32 v16, 16, v85
	v_and_b32_e32 v17, s98, v85
	v_lshlrev_b32_e32 v18, 16, v81
	v_and_b32_e32 v19, s98, v81
	v_pk_fma_f32 v[12:13], v[8:9], v[10:11], v[12:13]
	v_pk_fma_f32 v[18:19], v[14:15], v[16:17], v[18:19]
	v_cvt_pk_bf16_f32 v80, v12, v13
	v_cvt_pk_bf16_f32 v81, v18, v19
	v_lshlrev_b32_e32 v8, 16, v90
	v_and_b32_e32 v9, s98, v90
	v_lshlrev_b32_e32 v10, 16, v86
	v_and_b32_e32 v11, s98, v86
	v_lshlrev_b32_e32 v12, 16, v82
	v_and_b32_e32 v13, s98, v82
	v_lshlrev_b32_e32 v14, 16, v91
	v_and_b32_e32 v15, s98, v91
	v_lshlrev_b32_e32 v16, 16, v87
	v_and_b32_e32 v17, s98, v87
	v_lshlrev_b32_e32 v18, 16, v83
	v_and_b32_e32 v19, s98, v83
	v_pk_fma_f32 v[12:13], v[8:9], v[10:11], v[12:13]
	v_pk_fma_f32 v[18:19], v[14:15], v[16:17], v[18:19]
	v_cvt_pk_bf16_f32 v82, v12, v13
	v_cvt_pk_bf16_f32 v83, v18, v19
	v_add_u32_e32 v6, 0x60000, v3
	global_load_dwordx4 v[84:87], v6, s[54:55]
	ds_read_b128 v[88:91], v5 offset:33792
	v_add_u32_e32 v7, 0x20000, v3
	global_store_dwordx4 v7, v[80:83], s[54:55]
	s_nop 1
	global_load_dwordx4 v[80:83], v6, s[64:65]
	s_waitcnt vmcnt(19) lgkmcnt(7)
	v_lshlrev_b32_e32 v8, 16, v100
	v_and_b32_e32 v9, s98, v100
	v_lshlrev_b32_e32 v10, 16, v96
	v_and_b32_e32 v11, s98, v96
	v_lshlrev_b32_e32 v12, 16, v92
	v_and_b32_e32 v13, s98, v92
	v_lshlrev_b32_e32 v14, 16, v101
	v_and_b32_e32 v15, s98, v101
	v_lshlrev_b32_e32 v16, 16, v97
	v_and_b32_e32 v17, s98, v97
	v_lshlrev_b32_e32 v18, 16, v93
	v_and_b32_e32 v19, s98, v93
	v_pk_fma_f32 v[12:13], v[8:9], v[10:11], v[12:13]
	v_pk_fma_f32 v[18:19], v[14:15], v[16:17], v[18:19]
	v_cvt_pk_bf16_f32 v92, v12, v13
	v_cvt_pk_bf16_f32 v93, v18, v19
	v_lshlrev_b32_e32 v8, 16, v102
	v_and_b32_e32 v9, s98, v102
	v_lshlrev_b32_e32 v10, 16, v98
	v_and_b32_e32 v11, s98, v98
	v_lshlrev_b32_e32 v12, 16, v94
	v_and_b32_e32 v13, s98, v94
	v_lshlrev_b32_e32 v14, 16, v103
	v_and_b32_e32 v15, s98, v103
	v_lshlrev_b32_e32 v16, 16, v99
	v_and_b32_e32 v17, s98, v99
	v_lshlrev_b32_e32 v18, 16, v95
	v_and_b32_e32 v19, s98, v95
	v_pk_fma_f32 v[12:13], v[8:9], v[10:11], v[12:13]
	v_pk_fma_f32 v[18:19], v[14:15], v[16:17], v[18:19]
	v_cvt_pk_bf16_f32 v94, v12, v13
	v_cvt_pk_bf16_f32 v95, v18, v19
	v_add_u32_e32 v6, 0x68000, v3
	global_load_dwordx4 v[96:99], v6, s[54:55]
	ds_read_b128 v[100:103], v5 offset:42240
	v_add_u32_e32 v7, 0x28000, v3
	global_store_dwordx4 v7, v[92:95], s[54:55]
	s_nop 1
	global_load_dwordx4 v[92:95], v6, s[64:65]
	s_waitcnt vmcnt(20) lgkmcnt(7)
	v_lshlrev_b32_e32 v8, 16, v112
	v_and_b32_e32 v9, s98, v112
	v_lshlrev_b32_e32 v10, 16, v108
	v_and_b32_e32 v11, s98, v108
	v_lshlrev_b32_e32 v12, 16, v104
	v_and_b32_e32 v13, s98, v104
	v_lshlrev_b32_e32 v14, 16, v113
	v_and_b32_e32 v15, s98, v113
	v_lshlrev_b32_e32 v16, 16, v109
	v_and_b32_e32 v17, s98, v109
	v_lshlrev_b32_e32 v18, 16, v105
	v_and_b32_e32 v19, s98, v105
	v_pk_fma_f32 v[12:13], v[8:9], v[10:11], v[12:13]
	v_pk_fma_f32 v[18:19], v[14:15], v[16:17], v[18:19]
	v_cvt_pk_bf16_f32 v104, v12, v13
	v_cvt_pk_bf16_f32 v105, v18, v19
	v_lshlrev_b32_e32 v8, 16, v114
	v_and_b32_e32 v9, s98, v114
	v_lshlrev_b32_e32 v10, 16, v110
	v_and_b32_e32 v11, s98, v110
	v_lshlrev_b32_e32 v12, 16, v106
	v_and_b32_e32 v13, s98, v106
	v_lshlrev_b32_e32 v14, 16, v115
	v_and_b32_e32 v15, s98, v115
	v_lshlrev_b32_e32 v16, 16, v111
	v_and_b32_e32 v17, s98, v111
	v_lshlrev_b32_e32 v18, 16, v107
	v_and_b32_e32 v19, s98, v107
	v_pk_fma_f32 v[12:13], v[8:9], v[10:11], v[12:13]
	v_pk_fma_f32 v[18:19], v[14:15], v[16:17], v[18:19]
	v_cvt_pk_bf16_f32 v106, v12, v13
	v_cvt_pk_bf16_f32 v107, v18, v19
	v_add_u32_e32 v6, 0x70000, v3
	global_load_dwordx4 v[108:111], v6, s[54:55]
	ds_read_b128 v[112:115], v5 offset:50688
	v_add_u32_e32 v7, 0x30000, v3
	global_store_dwordx4 v7, v[104:107], s[54:55]
	s_nop 1
	global_load_dwordx4 v[104:107], v6, s[64:65]
	s_waitcnt vmcnt(21) lgkmcnt(7)
	v_lshlrev_b32_e32 v8, 16, v124
	v_and_b32_e32 v9, s98, v124
	v_lshlrev_b32_e32 v10, 16, v120
	v_and_b32_e32 v11, s98, v120
	v_lshlrev_b32_e32 v12, 16, v116
	v_and_b32_e32 v13, s98, v116
	v_lshlrev_b32_e32 v14, 16, v125
	v_and_b32_e32 v15, s98, v125
	v_lshlrev_b32_e32 v16, 16, v121
	v_and_b32_e32 v17, s98, v121
	v_lshlrev_b32_e32 v18, 16, v117
	v_and_b32_e32 v19, s98, v117
	v_pk_fma_f32 v[12:13], v[8:9], v[10:11], v[12:13]
	v_pk_fma_f32 v[18:19], v[14:15], v[16:17], v[18:19]
	v_cvt_pk_bf16_f32 v116, v12, v13
	v_cvt_pk_bf16_f32 v117, v18, v19
	v_lshlrev_b32_e32 v8, 16, v126
	v_and_b32_e32 v9, s98, v126
	v_lshlrev_b32_e32 v10, 16, v122
	v_and_b32_e32 v11, s98, v122
	v_lshlrev_b32_e32 v12, 16, v118
	v_and_b32_e32 v13, s98, v118
	v_lshlrev_b32_e32 v14, 16, v127
	v_and_b32_e32 v15, s98, v127
	v_lshlrev_b32_e32 v16, 16, v123
	v_and_b32_e32 v17, s98, v123
	v_lshlrev_b32_e32 v18, 16, v119
	v_and_b32_e32 v19, s98, v119
	v_pk_fma_f32 v[12:13], v[8:9], v[10:11], v[12:13]
	v_pk_fma_f32 v[18:19], v[14:15], v[16:17], v[18:19]
	v_cvt_pk_bf16_f32 v118, v12, v13
	v_cvt_pk_bf16_f32 v119, v18, v19
	v_add_u32_e32 v6, 0x78000, v3
	global_load_dwordx4 v[120:123], v6, s[54:55]
	ds_read_b128 v[124:127], v5 offset:59136
	v_add_u32_e32 v7, 0x38000, v3
	global_store_dwordx4 v7, v[116:119], s[54:55]
	s_nop 1
	global_load_dwordx4 v[116:119], v6, s[64:65]
	s_waitcnt vmcnt(21) lgkmcnt(7)
	v_lshlrev_b32_e32 v8, 16, v40
	v_and_b32_e32 v9, s98, v40
	v_lshlrev_b32_e32 v10, 16, v32
	v_and_b32_e32 v11, s98, v32
	v_lshlrev_b32_e32 v12, 16, v36
	v_and_b32_e32 v13, s98, v36
	v_lshlrev_b32_e32 v14, 16, v41
	v_and_b32_e32 v15, s98, v41
	v_lshlrev_b32_e32 v16, 16, v33
	v_and_b32_e32 v17, s98, v33
	v_lshlrev_b32_e32 v18, 16, v37
	v_and_b32_e32 v19, s98, v37
	v_pk_fma_f32 v[12:13], v[8:9], v[10:11], v[12:13]
	v_pk_fma_f32 v[18:19], v[14:15], v[16:17], v[18:19]
	v_cvt_pk_bf16_f32 v36, v12, v13
	v_cvt_pk_bf16_f32 v37, v18, v19
	v_lshlrev_b32_e32 v8, 16, v42
	v_and_b32_e32 v9, s98, v42
	v_lshlrev_b32_e32 v10, 16, v34
	v_and_b32_e32 v11, s98, v34
	v_lshlrev_b32_e32 v12, 16, v38
	v_and_b32_e32 v13, s98, v38
	v_lshlrev_b32_e32 v14, 16, v43
	v_and_b32_e32 v15, s98, v43
	v_lshlrev_b32_e32 v16, 16, v35
	v_and_b32_e32 v17, s98, v35
	v_lshlrev_b32_e32 v18, 16, v39
	v_and_b32_e32 v19, s98, v39
	v_pk_fma_f32 v[12:13], v[8:9], v[10:11], v[12:13]
	v_pk_fma_f32 v[18:19], v[14:15], v[16:17], v[18:19]
	v_cvt_pk_bf16_f32 v38, v12, v13
	v_cvt_pk_bf16_f32 v39, v18, v19
	v_add_u32_e32 v7, 0x40000, v3
	global_store_dwordx4 v7, v[36:39], s[54:55]
	s_waitcnt vmcnt(19) lgkmcnt(6)
	v_lshlrev_b32_e32 v8, 16, v52
	v_and_b32_e32 v9, s98, v52
	v_lshlrev_b32_e32 v10, 16, v44
	v_and_b32_e32 v11, s98, v44
	v_lshlrev_b32_e32 v12, 16, v48
	v_and_b32_e32 v13, s98, v48
	v_lshlrev_b32_e32 v14, 16, v53
	v_and_b32_e32 v15, s98, v53
	v_lshlrev_b32_e32 v16, 16, v45
	v_and_b32_e32 v17, s98, v45
	v_lshlrev_b32_e32 v18, 16, v49
	v_and_b32_e32 v19, s98, v49
	v_pk_fma_f32 v[12:13], v[8:9], v[10:11], v[12:13]
	v_pk_fma_f32 v[18:19], v[14:15], v[16:17], v[18:19]
	v_cvt_pk_bf16_f32 v48, v12, v13
	v_cvt_pk_bf16_f32 v49, v18, v19
	v_lshlrev_b32_e32 v8, 16, v54
	v_and_b32_e32 v9, s98, v54
	v_lshlrev_b32_e32 v10, 16, v46
	v_and_b32_e32 v11, s98, v46
	v_lshlrev_b32_e32 v12, 16, v50
	v_and_b32_e32 v13, s98, v50
	v_lshlrev_b32_e32 v14, 16, v55
	v_and_b32_e32 v15, s98, v55
	v_lshlrev_b32_e32 v16, 16, v47
	v_and_b32_e32 v17, s98, v47
	v_lshlrev_b32_e32 v18, 16, v51
	v_and_b32_e32 v19, s98, v51
	v_pk_fma_f32 v[12:13], v[8:9], v[10:11], v[12:13]
	v_pk_fma_f32 v[18:19], v[14:15], v[16:17], v[18:19]
	v_cvt_pk_bf16_f32 v50, v12, v13
	v_cvt_pk_bf16_f32 v51, v18, v19
	v_add_u32_e32 v7, 0x48000, v3
	global_store_dwordx4 v7, v[48:51], s[54:55]
	s_waitcnt vmcnt(17) lgkmcnt(5)
	v_lshlrev_b32_e32 v8, 16, v64
	v_and_b32_e32 v9, s98, v64
	v_lshlrev_b32_e32 v10, 16, v56
	v_and_b32_e32 v11, s98, v56
	v_lshlrev_b32_e32 v12, 16, v60
	v_and_b32_e32 v13, s98, v60
	v_lshlrev_b32_e32 v14, 16, v65
	v_and_b32_e32 v15, s98, v65
	v_lshlrev_b32_e32 v16, 16, v57
	v_and_b32_e32 v17, s98, v57
	v_lshlrev_b32_e32 v18, 16, v61
	v_and_b32_e32 v19, s98, v61
	v_pk_fma_f32 v[12:13], v[8:9], v[10:11], v[12:13]
	v_pk_fma_f32 v[18:19], v[14:15], v[16:17], v[18:19]
	v_cvt_pk_bf16_f32 v60, v12, v13
	v_cvt_pk_bf16_f32 v61, v18, v19
	v_lshlrev_b32_e32 v8, 16, v66
	v_and_b32_e32 v9, s98, v66
	v_lshlrev_b32_e32 v10, 16, v58
	v_and_b32_e32 v11, s98, v58
	v_lshlrev_b32_e32 v12, 16, v62
	v_and_b32_e32 v13, s98, v62
	v_lshlrev_b32_e32 v14, 16, v67
	v_and_b32_e32 v15, s98, v67
	v_lshlrev_b32_e32 v16, 16, v59
	v_and_b32_e32 v17, s98, v59
	v_lshlrev_b32_e32 v18, 16, v63
	v_and_b32_e32 v19, s98, v63
	v_pk_fma_f32 v[12:13], v[8:9], v[10:11], v[12:13]
	v_pk_fma_f32 v[18:19], v[14:15], v[16:17], v[18:19]
	v_cvt_pk_bf16_f32 v62, v12, v13
	v_cvt_pk_bf16_f32 v63, v18, v19
	v_add_u32_e32 v7, 0x50000, v3
	global_store_dwordx4 v7, v[60:63], s[54:55]
	s_waitcnt vmcnt(15) lgkmcnt(4)
	v_lshlrev_b32_e32 v8, 16, v76
	v_and_b32_e32 v9, s98, v76
	v_lshlrev_b32_e32 v10, 16, v68
	v_and_b32_e32 v11, s98, v68
	v_lshlrev_b32_e32 v12, 16, v72
	v_and_b32_e32 v13, s98, v72
	v_lshlrev_b32_e32 v14, 16, v77
	v_and_b32_e32 v15, s98, v77
	v_lshlrev_b32_e32 v16, 16, v69
	v_and_b32_e32 v17, s98, v69
	v_lshlrev_b32_e32 v18, 16, v73
	v_and_b32_e32 v19, s98, v73
	v_pk_fma_f32 v[12:13], v[8:9], v[10:11], v[12:13]
	v_pk_fma_f32 v[18:19], v[14:15], v[16:17], v[18:19]
	v_cvt_pk_bf16_f32 v72, v12, v13
	v_cvt_pk_bf16_f32 v73, v18, v19
	v_lshlrev_b32_e32 v8, 16, v78
	v_and_b32_e32 v9, s98, v78
	v_lshlrev_b32_e32 v10, 16, v70
	v_and_b32_e32 v11, s98, v70
	v_lshlrev_b32_e32 v12, 16, v74
	v_and_b32_e32 v13, s98, v74
	v_lshlrev_b32_e32 v14, 16, v79
	v_and_b32_e32 v15, s98, v79
	v_lshlrev_b32_e32 v16, 16, v71
	v_and_b32_e32 v17, s98, v71
	v_lshlrev_b32_e32 v18, 16, v75
	v_and_b32_e32 v19, s98, v75
	v_pk_fma_f32 v[12:13], v[8:9], v[10:11], v[12:13]
	v_pk_fma_f32 v[18:19], v[14:15], v[16:17], v[18:19]
	v_cvt_pk_bf16_f32 v74, v12, v13
	v_cvt_pk_bf16_f32 v75, v18, v19
	v_add_u32_e32 v7, 0x58000, v3
	global_store_dwordx4 v7, v[72:75], s[54:55]
	s_waitcnt vmcnt(13) lgkmcnt(3)
	v_lshlrev_b32_e32 v8, 16, v88
	v_and_b32_e32 v9, s98, v88
	v_lshlrev_b32_e32 v10, 16, v80
	v_and_b32_e32 v11, s98, v80
	v_lshlrev_b32_e32 v12, 16, v84
	v_and_b32_e32 v13, s98, v84
	v_lshlrev_b32_e32 v14, 16, v89
	v_and_b32_e32 v15, s98, v89
	v_lshlrev_b32_e32 v16, 16, v81
	v_and_b32_e32 v17, s98, v81
	v_lshlrev_b32_e32 v18, 16, v85
	v_and_b32_e32 v19, s98, v85
	v_pk_fma_f32 v[12:13], v[8:9], v[10:11], v[12:13]
	v_pk_fma_f32 v[18:19], v[14:15], v[16:17], v[18:19]
	v_cvt_pk_bf16_f32 v84, v12, v13
	v_cvt_pk_bf16_f32 v85, v18, v19
	v_lshlrev_b32_e32 v8, 16, v90
	v_and_b32_e32 v9, s98, v90
	v_lshlrev_b32_e32 v10, 16, v82
	v_and_b32_e32 v11, s98, v82
	v_lshlrev_b32_e32 v12, 16, v86
	v_and_b32_e32 v13, s98, v86
	v_lshlrev_b32_e32 v14, 16, v91
	v_and_b32_e32 v15, s98, v91
	v_lshlrev_b32_e32 v16, 16, v83
	v_and_b32_e32 v17, s98, v83
	v_lshlrev_b32_e32 v18, 16, v87
	v_and_b32_e32 v19, s98, v87
	v_pk_fma_f32 v[12:13], v[8:9], v[10:11], v[12:13]
	v_pk_fma_f32 v[18:19], v[14:15], v[16:17], v[18:19]
	v_cvt_pk_bf16_f32 v86, v12, v13
	v_cvt_pk_bf16_f32 v87, v18, v19
	v_add_u32_e32 v7, 0x60000, v3
	global_store_dwordx4 v7, v[84:87], s[54:55]
	s_waitcnt vmcnt(11) lgkmcnt(2)
	v_lshlrev_b32_e32 v8, 16, v100
	v_and_b32_e32 v9, s98, v100
	v_lshlrev_b32_e32 v10, 16, v92
	v_and_b32_e32 v11, s98, v92
	v_lshlrev_b32_e32 v12, 16, v96
	v_and_b32_e32 v13, s98, v96
	v_lshlrev_b32_e32 v14, 16, v101
	v_and_b32_e32 v15, s98, v101
	v_lshlrev_b32_e32 v16, 16, v93
	v_and_b32_e32 v17, s98, v93
	v_lshlrev_b32_e32 v18, 16, v97
	v_and_b32_e32 v19, s98, v97
	v_pk_fma_f32 v[12:13], v[8:9], v[10:11], v[12:13]
	v_pk_fma_f32 v[18:19], v[14:15], v[16:17], v[18:19]
	v_cvt_pk_bf16_f32 v96, v12, v13
	v_cvt_pk_bf16_f32 v97, v18, v19
	v_lshlrev_b32_e32 v8, 16, v102
	v_and_b32_e32 v9, s98, v102
	v_lshlrev_b32_e32 v10, 16, v94
	v_and_b32_e32 v11, s98, v94
	v_lshlrev_b32_e32 v12, 16, v98
	v_and_b32_e32 v13, s98, v98
	v_lshlrev_b32_e32 v14, 16, v103
	v_and_b32_e32 v15, s98, v103
	v_lshlrev_b32_e32 v16, 16, v95
	v_and_b32_e32 v17, s98, v95
	v_lshlrev_b32_e32 v18, 16, v99
	v_and_b32_e32 v19, s98, v99
	v_pk_fma_f32 v[12:13], v[8:9], v[10:11], v[12:13]
	v_pk_fma_f32 v[18:19], v[14:15], v[16:17], v[18:19]
	v_cvt_pk_bf16_f32 v98, v12, v13
	v_cvt_pk_bf16_f32 v99, v18, v19
	v_add_u32_e32 v7, 0x68000, v3
	global_store_dwordx4 v7, v[96:99], s[54:55]
	s_waitcnt vmcnt(9) lgkmcnt(1)
	v_lshlrev_b32_e32 v8, 16, v112
	v_and_b32_e32 v9, s98, v112
	v_lshlrev_b32_e32 v10, 16, v104
	v_and_b32_e32 v11, s98, v104
	v_lshlrev_b32_e32 v12, 16, v108
	v_and_b32_e32 v13, s98, v108
	v_lshlrev_b32_e32 v14, 16, v113
	v_and_b32_e32 v15, s98, v113
	v_lshlrev_b32_e32 v16, 16, v105
	v_and_b32_e32 v17, s98, v105
	v_lshlrev_b32_e32 v18, 16, v109
	v_and_b32_e32 v19, s98, v109
	v_pk_fma_f32 v[12:13], v[8:9], v[10:11], v[12:13]
	v_pk_fma_f32 v[18:19], v[14:15], v[16:17], v[18:19]
	v_cvt_pk_bf16_f32 v108, v12, v13
	v_cvt_pk_bf16_f32 v109, v18, v19
	v_lshlrev_b32_e32 v8, 16, v114
	v_and_b32_e32 v9, s98, v114
	v_lshlrev_b32_e32 v10, 16, v106
	v_and_b32_e32 v11, s98, v106
	v_lshlrev_b32_e32 v12, 16, v110
	v_and_b32_e32 v13, s98, v110
	v_lshlrev_b32_e32 v14, 16, v115
	v_and_b32_e32 v15, s98, v115
	v_lshlrev_b32_e32 v16, 16, v107
	v_and_b32_e32 v17, s98, v107
	v_lshlrev_b32_e32 v18, 16, v111
	v_and_b32_e32 v19, s98, v111
	v_pk_fma_f32 v[12:13], v[8:9], v[10:11], v[12:13]
	v_pk_fma_f32 v[18:19], v[14:15], v[16:17], v[18:19]
	v_cvt_pk_bf16_f32 v110, v12, v13
	v_cvt_pk_bf16_f32 v111, v18, v19
	v_add_u32_e32 v7, 0x70000, v3
	global_store_dwordx4 v7, v[108:111], s[54:55]
	s_waitcnt vmcnt(7) lgkmcnt(0)
	v_lshlrev_b32_e32 v8, 16, v124
	v_and_b32_e32 v9, s98, v124
	v_lshlrev_b32_e32 v10, 16, v116
	v_and_b32_e32 v11, s98, v116
	v_lshlrev_b32_e32 v12, 16, v120
	v_and_b32_e32 v13, s98, v120
	v_lshlrev_b32_e32 v14, 16, v125
	v_and_b32_e32 v15, s98, v125
	v_lshlrev_b32_e32 v16, 16, v117
	v_and_b32_e32 v17, s98, v117
	v_lshlrev_b32_e32 v18, 16, v121
	v_and_b32_e32 v19, s98, v121
	v_pk_fma_f32 v[12:13], v[8:9], v[10:11], v[12:13]
	v_pk_fma_f32 v[18:19], v[14:15], v[16:17], v[18:19]
	v_cvt_pk_bf16_f32 v120, v12, v13
	v_cvt_pk_bf16_f32 v121, v18, v19
	v_lshlrev_b32_e32 v8, 16, v126
	v_and_b32_e32 v9, s98, v126
	v_lshlrev_b32_e32 v10, 16, v118
	v_and_b32_e32 v11, s98, v118
	v_lshlrev_b32_e32 v12, 16, v122
	v_and_b32_e32 v13, s98, v122
	v_lshlrev_b32_e32 v14, 16, v127
	v_and_b32_e32 v15, s98, v127
	v_lshlrev_b32_e32 v16, 16, v119
	v_and_b32_e32 v17, s98, v119
	v_lshlrev_b32_e32 v18, 16, v123
	v_and_b32_e32 v19, s98, v123
	v_pk_fma_f32 v[12:13], v[8:9], v[10:11], v[12:13]
	v_pk_fma_f32 v[18:19], v[14:15], v[16:17], v[18:19]
	v_cvt_pk_bf16_f32 v122, v12, v13
	v_cvt_pk_bf16_f32 v123, v18, v19
	v_add_u32_e32 v7, 0x78000, v3
	global_store_dwordx4 v7, v[120:123], s[54:55]
	s_movk_i32 s70, 0x2000
	s_add_i32 s84, s84, 1
	s_add_u32 s68, s68, 0x80000
	s_addc_u32 s69, s69, 0
	s_cmp_eq_u32 s84, 4
	s_cbranch_scc0 .LBB0_1013
	s_add_u32 s3, s50, 0x1000000
	s_addc_u32 s16, s51, 0
	s_mov_b32 s70, 0
	s_barrier

.LBB0_1024:
	s_and_b32 s68, s72, 0x10000
	v_add_u32_e32 v132, s68, v142
	v_or_b32_e32 v170, s68, v143
	ds_read_b128 v[150:153], v132
	ds_read_b128 v[154:157], v132 offset:4096
	ds_read_b128 v[158:161], v132 offset:8192
	ds_read_b128 v[162:165], v132 offset:12288
	ds_read_b128 v[166:169], v170
	ds_read_b128 v[172:175], v170 offset:4096
	v_add_u32_e32 v214, s68, v144
	v_or_b32_e32 v215, s68, v145
	ds_read_b128 v[216:219], v214
	ds_read_b128 v[220:223], v214 offset:4096
	ds_read_b128 v[224:227], v214 offset:8192
	ds_read_b128 v[228:231], v214 offset:12288
	ds_read_b128 v[232:235], v215
	ds_read_b128 v[236:239], v215 offset:4096
	v_add_u32_e32 v132, s68, v146
	v_or_b32_e32 v170, s68, v147
	s_waitcnt lgkmcnt(6)
	v_mfma_f32_32x32x16_bf16 v[112:127], v[166:169], v[150:153], v[112:127]
	s_add_u32 s66, s66, 0x80
	s_addc_u32 s67, s67, 0
	s_add_i32 s71, s71, 1
	s_cmpk_lg_i32 s66, 0x800
	s_mov_b32 s72, s73
	v_mfma_f32_32x32x16_bf16 v[96:111], v[166:169], v[154:157], v[96:111]
	v_mfma_f32_32x32x16_bf16 v[64:79], v[166:169], v[158:161], v[64:79]
	v_mfma_f32_32x32x16_bf16 v[32:47], v[166:169], v[162:165], v[32:47]
	v_mfma_f32_32x32x16_bf16 v[80:95], v[172:175], v[150:153], v[80:95]
	v_mfma_f32_32x32x16_bf16 v[48:63], v[172:175], v[154:157], v[48:63]
	v_mfma_f32_32x32x16_bf16 v[16:31], v[172:175], v[158:161], v[16:31]
	v_mfma_f32_32x32x16_bf16 v[0:15], v[172:175], v[162:165], v[0:15]
	ds_read_b128 v[150:153], v132
	ds_read_b128 v[154:157], v132 offset:4096
	ds_read_b128 v[158:161], v132 offset:8192
	ds_read_b128 v[162:165], v132 offset:12288
	ds_read_b128 v[166:169], v170
	ds_read_b128 v[172:175], v170 offset:4096
	v_add_u32_e32 v214, s68, v148
	v_or_b32_e32 v215, s68, v149
	s_waitcnt lgkmcnt(6)
	v_mfma_f32_32x32x16_bf16 v[112:127], v[232:235], v[216:219], v[112:127]
	v_mfma_f32_32x32x16_bf16 v[96:111], v[232:235], v[220:223], v[96:111]
	v_mfma_f32_32x32x16_bf16 v[64:79], v[232:235], v[224:227], v[64:79]
	v_mfma_f32_32x32x16_bf16 v[32:47], v[232:235], v[228:231], v[32:47]
	v_mfma_f32_32x32x16_bf16 v[80:95], v[236:239], v[216:219], v[80:95]
	v_mfma_f32_32x32x16_bf16 v[48:63], v[236:239], v[220:223], v[48:63]
	v_mfma_f32_32x32x16_bf16 v[16:31], v[236:239], v[224:227], v[16:31]
	v_mfma_f32_32x32x16_bf16 v[0:15], v[236:239], v[228:231], v[0:15]
	ds_read_b128 v[216:219], v214
	ds_read_b128 v[220:223], v214 offset:4096
	ds_read_b128 v[224:227], v214 offset:8192
	ds_read_b128 v[228:231], v214 offset:12288
	ds_read_b128 v[232:235], v215
	ds_read_b128 v[236:239], v215 offset:4096
	s_waitcnt lgkmcnt(6)
	v_mfma_f32_32x32x16_bf16 v[112:127], v[166:169], v[150:153], v[112:127]
	v_mfma_f32_32x32x16_bf16 v[96:111], v[166:169], v[154:157], v[96:111]
	v_mfma_f32_32x32x16_bf16 v[64:79], v[166:169], v[158:161], v[64:79]
	v_mfma_f32_32x32x16_bf16 v[32:47], v[166:169], v[162:165], v[32:47]
	v_mfma_f32_32x32x16_bf16 v[80:95], v[172:175], v[150:153], v[80:95]
	v_mfma_f32_32x32x16_bf16 v[48:63], v[172:175], v[154:157], v[48:63]
	v_mfma_f32_32x32x16_bf16 v[16:31], v[172:175], v[158:161], v[16:31]
	v_mfma_f32_32x32x16_bf16 v[0:15], v[172:175], v[162:165], v[0:15]
	s_waitcnt lgkmcnt(0)
	v_mfma_f32_32x32x16_bf16 v[112:127], v[232:235], v[216:219], v[112:127]
	v_mfma_f32_32x32x16_bf16 v[96:111], v[232:235], v[220:223], v[96:111]
	v_mfma_f32_32x32x16_bf16 v[64:79], v[232:235], v[224:227], v[64:79]
	v_mfma_f32_32x32x16_bf16 v[32:47], v[232:235], v[228:231], v[32:47]
	v_mfma_f32_32x32x16_bf16 v[80:95], v[236:239], v[216:219], v[80:95]
	v_mfma_f32_32x32x16_bf16 v[48:63], v[236:239], v[220:223], v[48:63]
	v_mfma_f32_32x32x16_bf16 v[16:31], v[236:239], v[224:227], v[16:31]
	v_mfma_f32_32x32x16_bf16 v[0:15], v[236:239], v[228:231], v[0:15]
	s_cbranch_scc0 .LBB0_1029

.LBB0_1029:
	v_mov_b32_e32 v128, v176
	s_waitcnt vmcnt(0) lgkmcnt(0)
	s_barrier
	s_nop 4
	v_cvt_pk_bf16_f32 v80, v80, v81
	v_and_b32_e32 v129, 0xc0, v128
	v_and_b32_e32 v130, 31, v128
	v_lshrrev_b32_e32 v131, 1, v128
	v_lshrrev_b32_e32 v128, 2, v128
	v_and_b32_e32 v128, 8, v128
	v_and_or_b32 v130, v131, s93, v130
	v_lshl_or_b32 v128, v129, 1, v128
	v_mad_u64_u32 v[128:129], s[66:67], v130, s0, v[128:129]
	v_cvt_pk_bf16_f32 v81, v82, v83
	v_cvt_pk_bf16_f32 v82, v84, v85
	v_cvt_pk_bf16_f32 v83, v86, v87
	v_add_u32_e32 v84, 0x4000, v128
	v_cvt_pk_bf16_f32 v48, v48, v49
	v_cvt_pk_bf16_f32 v49, v50, v51
	v_cvt_pk_bf16_f32 v50, v52, v53
	v_cvt_pk_bf16_f32 v51, v54, v55
	v_add_u32_e32 v52, 0x8000, v128
	v_cvt_pk_bf16_f32 v16, v16, v17
	v_cvt_pk_bf16_f32 v17, v18, v19
	v_cvt_pk_bf16_f32 v18, v20, v21
	v_cvt_pk_bf16_f32 v19, v22, v23
	ds_write2_b64 v128, v[80:81], v[82:83] offset0:8 offset1:10
	v_cvt_pk_bf16_f32 v80, v88, v89
	v_cvt_pk_bf16_f32 v81, v90, v91
	v_cvt_pk_bf16_f32 v82, v92, v93
	v_cvt_pk_bf16_f32 v83, v94, v95
	ds_write2_b64 v84, v[48:49], v[50:51] offset0:72 offset1:74
	v_cvt_pk_bf16_f32 v48, v56, v57
	v_cvt_pk_bf16_f32 v49, v58, v59
	v_cvt_pk_bf16_f32 v50, v60, v61
	v_cvt_pk_bf16_f32 v51, v62, v63
	ds_write2_b64 v52, v[16:17], v[18:19] offset0:136 offset1:138
	v_cvt_pk_bf16_f32 v16, v24, v25
	v_cvt_pk_bf16_f32 v17, v26, v27
	v_cvt_pk_bf16_f32 v18, v28, v29
	v_cvt_pk_bf16_f32 v19, v30, v31
	v_add_u32_e32 v20, 0xc000, v128
	v_cvt_pk_bf16_f32 v0, v0, v1
	v_cvt_pk_bf16_f32 v1, v2, v3
	v_cvt_pk_bf16_f32 v2, v4, v5
	v_cvt_pk_bf16_f32 v3, v6, v7
	v_cvt_pk_bf16_f32 v112, v112, v113
	v_cvt_pk_bf16_f32 v113, v114, v115
	v_cvt_pk_bf16_f32 v114, v116, v117
	v_cvt_pk_bf16_f32 v115, v118, v119
	ds_write2_b64 v128, v[80:81], v[82:83] offset0:12 offset1:14
	v_cvt_pk_bf16_f32 v80, v96, v97
	v_cvt_pk_bf16_f32 v81, v98, v99
	v_cvt_pk_bf16_f32 v82, v100, v101
	v_cvt_pk_bf16_f32 v83, v102, v103
	ds_write2_b64 v84, v[48:49], v[50:51] offset0:76 offset1:78
	v_cvt_pk_bf16_f32 v48, v64, v65
	v_cvt_pk_bf16_f32 v49, v66, v67
	v_cvt_pk_bf16_f32 v50, v68, v69
	v_cvt_pk_bf16_f32 v51, v70, v71
	ds_write2_b64 v52, v[16:17], v[18:19] offset0:140 offset1:142
	v_cvt_pk_bf16_f32 v16, v32, v33
	v_cvt_pk_bf16_f32 v17, v34, v35
	v_cvt_pk_bf16_f32 v18, v36, v37
	v_cvt_pk_bf16_f32 v19, v38, v39
	ds_write2_b64 v20, v[0:1], v[2:3] offset0:200 offset1:202
	v_cvt_pk_bf16_f32 v0, v8, v9
	v_cvt_pk_bf16_f32 v1, v10, v11
	v_cvt_pk_bf16_f32 v2, v12, v13
	v_cvt_pk_bf16_f32 v3, v14, v15
	ds_write2_b64 v128, v[112:113], v[114:115] offset1:2
	v_cvt_pk_bf16_f32 v112, v120, v121
	v_cvt_pk_bf16_f32 v113, v122, v123
	v_cvt_pk_bf16_f32 v114, v124, v125
	v_cvt_pk_bf16_f32 v115, v126, v127
	ds_write2_b64 v84, v[80:81], v[82:83] offset0:64 offset1:66
	v_cvt_pk_bf16_f32 v80, v104, v105
	v_cvt_pk_bf16_f32 v81, v106, v107
	v_cvt_pk_bf16_f32 v82, v108, v109
	v_cvt_pk_bf16_f32 v83, v110, v111
	ds_write2_b64 v52, v[48:49], v[50:51] offset0:128 offset1:130
	v_cvt_pk_bf16_f32 v48, v72, v73
	v_cvt_pk_bf16_f32 v49, v74, v75
	v_cvt_pk_bf16_f32 v50, v76, v77
	v_cvt_pk_bf16_f32 v51, v78, v79
	ds_write2_b64 v20, v[16:17], v[18:19] offset0:192 offset1:194
	v_cvt_pk_bf16_f32 v16, v40, v41
	v_cvt_pk_bf16_f32 v17, v42, v43
	v_cvt_pk_bf16_f32 v18, v44, v45
	v_cvt_pk_bf16_f32 v19, v46, v47
	ds_write2_b64 v20, v[0:1], v[2:3] offset0:204 offset1:206
	v_mov_b32_e32 v1, v176
	ds_write2_b64 v128, v[112:113], v[114:115] offset0:4 offset1:6
	ds_write2_b64 v84, v[80:81], v[82:83] offset0:68 offset1:70
	ds_write2_b64 v52, v[48:49], v[50:51] offset0:132 offset1:134
	ds_write2_b64 v20, v[16:17], v[18:19] offset0:196 offset1:198
	s_waitcnt lgkmcnt(0)
	s_barrier
	v_mov_b32_e32 v1, v176
	s_mov_b32 s98, 0xffff0000
	v_lshlrev_b32_e32 v0, 4, v1
	v_and_b32_e32 v0, 0x1f0, v0
	v_lshrrev_b32_e32 v2, 5, v1
	v_mov_b32_e32 v6, 0x210
	v_mad_u32_u24 v4, v2, v6, v0
	v_add_u32_e32 v5, 0x10800, v4
	v_lshlrev_b32_e32 v6, 3, v1
	v_and_b32_e32 v6, 0xf8, v6
	v_lshl_or_b32 v132, s70, 8, v6
	v_lshlrev_b32_e32 v3, 1, v132
	v_lshl_add_u32 v3, v2, 11, v3
	v_lshlrev_b32_e32 v20, 2, v132
	v_lshl_add_u32 v20, v2, 12, v20
	v_add_u32_e32 v6, 0x0, v3
	global_load_dwordx4 v[32:35], v6, s[52:53]
	ds_read_b128 v[96:99], v4
	v_add_u32_e32 v6, 0x8000, v3
	global_load_dwordx4 v[36:39], v6, s[52:53]
	ds_read_b128 v[100:103], v4 offset:8448
	v_add_u32_e32 v6, 0x10000, v3
	global_load_dwordx4 v[40:43], v6, s[52:53]
	ds_read_b128 v[104:107], v4 offset:16896
	v_add_u32_e32 v6, 0x18000, v3
	global_load_dwordx4 v[44:47], v6, s[52:53]
	ds_read_b128 v[108:111], v4 offset:25344
	v_add_u32_e32 v6, 0x20000, v3
	global_load_dwordx4 v[48:51], v6, s[52:53]
	ds_read_b128 v[112:115], v4 offset:33792
	v_add_u32_e32 v6, 0x28000, v3
	global_load_dwordx4 v[52:55], v6, s[52:53]
	ds_read_b128 v[116:119], v4 offset:42240
	v_add_u32_e32 v6, 0x30000, v3
	global_load_dwordx4 v[56:59], v6, s[52:53]
	ds_read_b128 v[120:123], v4 offset:50688
	v_add_u32_e32 v6, 0x38000, v3
	global_load_dwordx4 v[60:63], v6, s[52:53]
	ds_read_b128 v[124:127], v4 offset:59136
	v_add_u32_e32 v6, 0x40000, v3
	global_load_dwordx4 v[64:67], v6, s[52:53]
	v_add_u32_e32 v6, 0x48000, v3
	global_load_dwordx4 v[68:71], v6, s[52:53]
	v_add_u32_e32 v6, 0x50000, v3
	global_load_dwordx4 v[72:75], v6, s[52:53]
	v_add_u32_e32 v6, 0x58000, v3
	global_load_dwordx4 v[76:79], v6, s[52:53]
	v_add_u32_e32 v6, 0x60000, v3
	global_load_dwordx4 v[80:83], v6, s[52:53]
	v_add_u32_e32 v6, 0x68000, v3
	global_load_dwordx4 v[84:87], v6, s[52:53]
	v_add_u32_e32 v6, 0x70000, v3
	global_load_dwordx4 v[88:91], v6, s[52:53]
	v_add_u32_e32 v6, 0x78000, v3
	global_load_dwordx4 v[92:95], v6, s[52:53]
	s_waitcnt vmcnt(15) lgkmcnt(7)
	v_lshlrev_b32_e32 v8, 16, v32
	v_and_b32_e32 v9, s98, v32
	v_lshlrev_b32_e32 v10, 16, v33
	v_and_b32_e32 v11, s98, v33
	v_lshlrev_b32_e32 v12, 16, v34
	v_and_b32_e32 v13, s98, v34
	v_lshlrev_b32_e32 v14, 16, v35
	v_and_b32_e32 v15, s98, v35
	v_lshlrev_b32_e32 v22, 16, v96
	v_and_b32_e32 v23, s98, v96
	v_lshlrev_b32_e32 v24, 16, v97
	v_and_b32_e32 v25, s98, v97
	v_lshlrev_b32_e32 v26, 16, v98
	v_and_b32_e32 v27, s98, v98
	v_lshlrev_b32_e32 v28, 16, v99
	v_and_b32_e32 v29, s98, v99
	v_pk_fma_f32 v[22:23], v[8:9], s[38:39], v[22:23] op_sel_hi:[1,0,1]
	v_pk_fma_f32 v[24:25], v[10:11], s[38:39], v[24:25] op_sel_hi:[1,0,1]
	v_pk_fma_f32 v[26:27], v[12:13], s[38:39], v[26:27] op_sel_hi:[1,0,1]
	v_pk_fma_f32 v[28:29], v[14:15], s[38:39], v[28:29] op_sel_hi:[1,0,1]
	ds_read_b128 v[96:99], v5
	v_add_u32_e32 v7, 0x0, v20
	global_store_dwordx4 v7, v[22:25], s[64:65]
	global_store_dwordx4 v7, v[26:29], s[64:65] offset:16
	s_waitcnt vmcnt(16) lgkmcnt(7)
	v_lshlrev_b32_e32 v8, 16, v36
	v_and_b32_e32 v9, s98, v36
	v_lshlrev_b32_e32 v10, 16, v37
	v_and_b32_e32 v11, s98, v37
	v_lshlrev_b32_e32 v12, 16, v38
	v_and_b32_e32 v13, s98, v38
	v_lshlrev_b32_e32 v14, 16, v39
	v_and_b32_e32 v15, s98, v39
	v_lshlrev_b32_e32 v22, 16, v100
	v_and_b32_e32 v23, s98, v100
	v_lshlrev_b32_e32 v24, 16, v101
	v_and_b32_e32 v25, s98, v101
	v_lshlrev_b32_e32 v26, 16, v102
	v_and_b32_e32 v27, s98, v102
	v_lshlrev_b32_e32 v28, 16, v103
	v_and_b32_e32 v29, s98, v103
	v_pk_fma_f32 v[22:23], v[8:9], s[38:39], v[22:23] op_sel_hi:[1,0,1]
	v_pk_fma_f32 v[24:25], v[10:11], s[38:39], v[24:25] op_sel_hi:[1,0,1]
	v_pk_fma_f32 v[26:27], v[12:13], s[38:39], v[26:27] op_sel_hi:[1,0,1]
	v_pk_fma_f32 v[28:29], v[14:15], s[38:39], v[28:29] op_sel_hi:[1,0,1]
	ds_read_b128 v[100:103], v5 offset:8448
	v_add_u32_e32 v7, 0x10000, v20
	global_store_dwordx4 v7, v[22:25], s[64:65]
	global_store_dwordx4 v7, v[26:29], s[64:65] offset:16
	s_waitcnt vmcnt(17) lgkmcnt(7)
	v_lshlrev_b32_e32 v8, 16, v40
	v_and_b32_e32 v9, s98, v40
	v_lshlrev_b32_e32 v10, 16, v41
	v_and_b32_e32 v11, s98, v41
	v_lshlrev_b32_e32 v12, 16, v42
	v_and_b32_e32 v13, s98, v42
	v_lshlrev_b32_e32 v14, 16, v43
	v_and_b32_e32 v15, s98, v43
	v_lshlrev_b32_e32 v22, 16, v104
	v_and_b32_e32 v23, s98, v104
	v_lshlrev_b32_e32 v24, 16, v105
	v_and_b32_e32 v25, s98, v105
	v_lshlrev_b32_e32 v26, 16, v106
	v_and_b32_e32 v27, s98, v106
	v_lshlrev_b32_e32 v28, 16, v107
	v_and_b32_e32 v29, s98, v107
	v_pk_fma_f32 v[22:23], v[8:9], s[38:39], v[22:23] op_sel_hi:[1,0,1]
	v_pk_fma_f32 v[24:25], v[10:11], s[38:39], v[24:25] op_sel_hi:[1,0,1]
	v_pk_fma_f32 v[26:27], v[12:13], s[38:39], v[26:27] op_sel_hi:[1,0,1]
	v_pk_fma_f32 v[28:29], v[14:15], s[38:39], v[28:29] op_sel_hi:[1,0,1]
	ds_read_b128 v[104:107], v5 offset:16896
	v_add_u32_e32 v7, 0x20000, v20
	global_store_dwordx4 v7, v[22:25], s[64:65]
	global_store_dwordx4 v7, v[26:29], s[64:65] offset:16
	s_waitcnt vmcnt(18) lgkmcnt(7)
	v_lshlrev_b32_e32 v8, 16, v44
	v_and_b32_e32 v9, s98, v44
	v_lshlrev_b32_e32 v10, 16, v45
	v_and_b32_e32 v11, s98, v45
	v_lshlrev_b32_e32 v12, 16, v46
	v_and_b32_e32 v13, s98, v46
	v_lshlrev_b32_e32 v14, 16, v47
	v_and_b32_e32 v15, s98, v47
	v_lshlrev_b32_e32 v22, 16, v108
	v_and_b32_e32 v23, s98, v108
	v_lshlrev_b32_e32 v24, 16, v109
	v_and_b32_e32 v25, s98, v109
	v_lshlrev_b32_e32 v26, 16, v110
	v_and_b32_e32 v27, s98, v110
	v_lshlrev_b32_e32 v28, 16, v111
	v_and_b32_e32 v29, s98, v111
	v_pk_fma_f32 v[22:23], v[8:9], s[38:39], v[22:23] op_sel_hi:[1,0,1]
	v_pk_fma_f32 v[24:25], v[10:11], s[38:39], v[24:25] op_sel_hi:[1,0,1]
	v_pk_fma_f32 v[26:27], v[12:13], s[38:39], v[26:27] op_sel_hi:[1,0,1]
	v_pk_fma_f32 v[28:29], v[14:15], s[38:39], v[28:29] op_sel_hi:[1,0,1]
	ds_read_b128 v[108:111], v5 offset:25344
	v_add_u32_e32 v7, 0x30000, v20
	global_store_dwordx4 v7, v[22:25], s[64:65]
	global_store_dwordx4 v7, v[26:29], s[64:65] offset:16
	s_waitcnt vmcnt(19) lgkmcnt(7)
	v_lshlrev_b32_e32 v8, 16, v48
	v_and_b32_e32 v9, s98, v48
	v_lshlrev_b32_e32 v10, 16, v49
	v_and_b32_e32 v11, s98, v49
	v_lshlrev_b32_e32 v12, 16, v50
	v_and_b32_e32 v13, s98, v50
	v_lshlrev_b32_e32 v14, 16, v51
	v_and_b32_e32 v15, s98, v51
	v_lshlrev_b32_e32 v22, 16, v112
	v_and_b32_e32 v23, s98, v112
	v_lshlrev_b32_e32 v24, 16, v113
	v_and_b32_e32 v25, s98, v113
	v_lshlrev_b32_e32 v26, 16, v114
	v_and_b32_e32 v27, s98, v114
	v_lshlrev_b32_e32 v28, 16, v115
	v_and_b32_e32 v29, s98, v115
	v_pk_fma_f32 v[22:23], v[8:9], s[38:39], v[22:23] op_sel_hi:[1,0,1]
	v_pk_fma_f32 v[24:25], v[10:11], s[38:39], v[24:25] op_sel_hi:[1,0,1]
	v_pk_fma_f32 v[26:27], v[12:13], s[38:39], v[26:27] op_sel_hi:[1,0,1]
	v_pk_fma_f32 v[28:29], v[14:15], s[38:39], v[28:29] op_sel_hi:[1,0,1]
	ds_read_b128 v[112:115], v5 offset:33792
	v_add_u32_e32 v7, 0x40000, v20
	global_store_dwordx4 v7, v[22:25], s[64:65]
	global_store_dwordx4 v7, v[26:29], s[64:65] offset:16
	s_waitcnt vmcnt(20) lgkmcnt(7)
	v_lshlrev_b32_e32 v8, 16, v52
	v_and_b32_e32 v9, s98, v52
	v_lshlrev_b32_e32 v10, 16, v53
	v_and_b32_e32 v11, s98, v53
	v_lshlrev_b32_e32 v12, 16, v54
	v_and_b32_e32 v13, s98, v54
	v_lshlrev_b32_e32 v14, 16, v55
	v_and_b32_e32 v15, s98, v55
	v_lshlrev_b32_e32 v22, 16, v116
	v_and_b32_e32 v23, s98, v116
	v_lshlrev_b32_e32 v24, 16, v117
	v_and_b32_e32 v25, s98, v117
	v_lshlrev_b32_e32 v26, 16, v118
	v_and_b32_e32 v27, s98, v118
	v_lshlrev_b32_e32 v28, 16, v119
	v_and_b32_e32 v29, s98, v119
	v_pk_fma_f32 v[22:23], v[8:9], s[38:39], v[22:23] op_sel_hi:[1,0,1]
	v_pk_fma_f32 v[24:25], v[10:11], s[38:39], v[24:25] op_sel_hi:[1,0,1]
	v_pk_fma_f32 v[26:27], v[12:13], s[38:39], v[26:27] op_sel_hi:[1,0,1]
	v_pk_fma_f32 v[28:29], v[14:15], s[38:39], v[28:29] op_sel_hi:[1,0,1]
	ds_read_b128 v[116:119], v5 offset:42240
	v_add_u32_e32 v7, 0x50000, v20
	global_store_dwordx4 v7, v[22:25], s[64:65]
	global_store_dwordx4 v7, v[26:29], s[64:65] offset:16
	s_waitcnt vmcnt(21) lgkmcnt(7)
	v_lshlrev_b32_e32 v8, 16, v56
	v_and_b32_e32 v9, s98, v56
	v_lshlrev_b32_e32 v10, 16, v57
	v_and_b32_e32 v11, s98, v57
	v_lshlrev_b32_e32 v12, 16, v58
	v_and_b32_e32 v13, s98, v58
	v_lshlrev_b32_e32 v14, 16, v59
	v_and_b32_e32 v15, s98, v59
	v_lshlrev_b32_e32 v22, 16, v120
	v_and_b32_e32 v23, s98, v120
	v_lshlrev_b32_e32 v24, 16, v121
	v_and_b32_e32 v25, s98, v121
	v_lshlrev_b32_e32 v26, 16, v122
	v_and_b32_e32 v27, s98, v122
	v_lshlrev_b32_e32 v28, 16, v123
	v_and_b32_e32 v29, s98, v123
	v_pk_fma_f32 v[22:23], v[8:9], s[38:39], v[22:23] op_sel_hi:[1,0,1]
	v_pk_fma_f32 v[24:25], v[10:11], s[38:39], v[24:25] op_sel_hi:[1,0,1]
	v_pk_fma_f32 v[26:27], v[12:13], s[38:39], v[26:27] op_sel_hi:[1,0,1]
	v_pk_fma_f32 v[28:29], v[14:15], s[38:39], v[28:29] op_sel_hi:[1,0,1]
	ds_read_b128 v[120:123], v5 offset:50688
	v_add_u32_e32 v7, 0x60000, v20
	global_store_dwordx4 v7, v[22:25], s[64:65]
	global_store_dwordx4 v7, v[26:29], s[64:65] offset:16
	s_waitcnt vmcnt(22) lgkmcnt(7)
	v_lshlrev_b32_e32 v8, 16, v60
	v_and_b32_e32 v9, s98, v60
	v_lshlrev_b32_e32 v10, 16, v61
	v_and_b32_e32 v11, s98, v61
	v_lshlrev_b32_e32 v12, 16, v62
	v_and_b32_e32 v13, s98, v62
	v_lshlrev_b32_e32 v14, 16, v63
	v_and_b32_e32 v15, s98, v63
	v_lshlrev_b32_e32 v22, 16, v124
	v_and_b32_e32 v23, s98, v124
	v_lshlrev_b32_e32 v24, 16, v125
	v_and_b32_e32 v25, s98, v125
	v_lshlrev_b32_e32 v26, 16, v126
	v_and_b32_e32 v27, s98, v126
	v_lshlrev_b32_e32 v28, 16, v127
	v_and_b32_e32 v29, s98, v127
	v_pk_fma_f32 v[22:23], v[8:9], s[38:39], v[22:23] op_sel_hi:[1,0,1]
	v_pk_fma_f32 v[24:25], v[10:11], s[38:39], v[24:25] op_sel_hi:[1,0,1]
	v_pk_fma_f32 v[26:27], v[12:13], s[38:39], v[26:27] op_sel_hi:[1,0,1]
	v_pk_fma_f32 v[28:29], v[14:15], s[38:39], v[28:29] op_sel_hi:[1,0,1]
	ds_read_b128 v[124:127], v5 offset:59136
	v_add_u32_e32 v7, 0x70000, v20
	global_store_dwordx4 v7, v[22:25], s[64:65]
	global_store_dwordx4 v7, v[26:29], s[64:65] offset:16
	s_waitcnt vmcnt(23) lgkmcnt(7)
	v_lshlrev_b32_e32 v8, 16, v64
	v_and_b32_e32 v9, s98, v64
	v_lshlrev_b32_e32 v10, 16, v65
	v_and_b32_e32 v11, s98, v65
	v_lshlrev_b32_e32 v12, 16, v66
	v_and_b32_e32 v13, s98, v66
	v_lshlrev_b32_e32 v14, 16, v67
	v_and_b32_e32 v15, s98, v67
	v_lshlrev_b32_e32 v22, 16, v96
	v_and_b32_e32 v23, s98, v96
	v_lshlrev_b32_e32 v24, 16, v97
	v_and_b32_e32 v25, s98, v97
	v_lshlrev_b32_e32 v26, 16, v98
	v_and_b32_e32 v27, s98, v98
	v_lshlrev_b32_e32 v28, 16, v99
	v_and_b32_e32 v29, s98, v99
	v_pk_fma_f32 v[22:23], v[8:9], s[38:39], v[22:23] op_sel_hi:[1,0,1]
	v_pk_fma_f32 v[24:25], v[10:11], s[38:39], v[24:25] op_sel_hi:[1,0,1]
	v_pk_fma_f32 v[26:27], v[12:13], s[38:39], v[26:27] op_sel_hi:[1,0,1]
	v_pk_fma_f32 v[28:29], v[14:15], s[38:39], v[28:29] op_sel_hi:[1,0,1]
	v_add_u32_e32 v7, 0x80000, v20
	global_store_dwordx4 v7, v[22:25], s[64:65]
	global_store_dwordx4 v7, v[26:29], s[64:65] offset:16
	s_waitcnt vmcnt(24) lgkmcnt(6)
	v_lshlrev_b32_e32 v8, 16, v68
	v_and_b32_e32 v9, s98, v68
	v_lshlrev_b32_e32 v10, 16, v69
	v_and_b32_e32 v11, s98, v69
	v_lshlrev_b32_e32 v12, 16, v70
	v_and_b32_e32 v13, s98, v70
	v_lshlrev_b32_e32 v14, 16, v71
	v_and_b32_e32 v15, s98, v71
	v_lshlrev_b32_e32 v22, 16, v100
	v_and_b32_e32 v23, s98, v100
	v_lshlrev_b32_e32 v24, 16, v101
	v_and_b32_e32 v25, s98, v101
	v_lshlrev_b32_e32 v26, 16, v102
	v_and_b32_e32 v27, s98, v102
	v_lshlrev_b32_e32 v28, 16, v103
	v_and_b32_e32 v29, s98, v103
	v_pk_fma_f32 v[22:23], v[8:9], s[38:39], v[22:23] op_sel_hi:[1,0,1]
	v_pk_fma_f32 v[24:25], v[10:11], s[38:39], v[24:25] op_sel_hi:[1,0,1]
	v_pk_fma_f32 v[26:27], v[12:13], s[38:39], v[26:27] op_sel_hi:[1,0,1]
	v_pk_fma_f32 v[28:29], v[14:15], s[38:39], v[28:29] op_sel_hi:[1,0,1]
	v_add_u32_e32 v7, 0x90000, v20
	global_store_dwordx4 v7, v[22:25], s[64:65]
	global_store_dwordx4 v7, v[26:29], s[64:65] offset:16
	s_waitcnt vmcnt(25) lgkmcnt(5)
	v_lshlrev_b32_e32 v8, 16, v72
	v_and_b32_e32 v9, s98, v72
	v_lshlrev_b32_e32 v10, 16, v73
	v_and_b32_e32 v11, s98, v73
	v_lshlrev_b32_e32 v12, 16, v74
	v_and_b32_e32 v13, s98, v74
	v_lshlrev_b32_e32 v14, 16, v75
	v_and_b32_e32 v15, s98, v75
	v_lshlrev_b32_e32 v22, 16, v104
	v_and_b32_e32 v23, s98, v104
	v_lshlrev_b32_e32 v24, 16, v105
	v_and_b32_e32 v25, s98, v105
	v_lshlrev_b32_e32 v26, 16, v106
	v_and_b32_e32 v27, s98, v106
	v_lshlrev_b32_e32 v28, 16, v107
	v_and_b32_e32 v29, s98, v107
	v_pk_fma_f32 v[22:23], v[8:9], s[38:39], v[22:23] op_sel_hi:[1,0,1]
	v_pk_fma_f32 v[24:25], v[10:11], s[38:39], v[24:25] op_sel_hi:[1,0,1]
	v_pk_fma_f32 v[26:27], v[12:13], s[38:39], v[26:27] op_sel_hi:[1,0,1]
	v_pk_fma_f32 v[28:29], v[14:15], s[38:39], v[28:29] op_sel_hi:[1,0,1]
	v_add_u32_e32 v7, 0xa0000, v20
	global_store_dwordx4 v7, v[22:25], s[64:65]
	global_store_dwordx4 v7, v[26:29], s[64:65] offset:16
	s_waitcnt vmcnt(26) lgkmcnt(4)
	v_lshlrev_b32_e32 v8, 16, v76
	v_and_b32_e32 v9, s98, v76
	v_lshlrev_b32_e32 v10, 16, v77
	v_and_b32_e32 v11, s98, v77
	v_lshlrev_b32_e32 v12, 16, v78
	v_and_b32_e32 v13, s98, v78
	v_lshlrev_b32_e32 v14, 16, v79
	v_and_b32_e32 v15, s98, v79
	v_lshlrev_b32_e32 v22, 16, v108
	v_and_b32_e32 v23, s98, v108
	v_lshlrev_b32_e32 v24, 16, v109
	v_and_b32_e32 v25, s98, v109
	v_lshlrev_b32_e32 v26, 16, v110
	v_and_b32_e32 v27, s98, v110
	v_lshlrev_b32_e32 v28, 16, v111
	v_and_b32_e32 v29, s98, v111
	v_pk_fma_f32 v[22:23], v[8:9], s[38:39], v[22:23] op_sel_hi:[1,0,1]
	v_pk_fma_f32 v[24:25], v[10:11], s[38:39], v[24:25] op_sel_hi:[1,0,1]
	v_pk_fma_f32 v[26:27], v[12:13], s[38:39], v[26:27] op_sel_hi:[1,0,1]
	v_pk_fma_f32 v[28:29], v[14:15], s[38:39], v[28:29] op_sel_hi:[1,0,1]
	v_add_u32_e32 v7, 0xb0000, v20
	global_store_dwordx4 v7, v[22:25], s[64:65]
	global_store_dwordx4 v7, v[26:29], s[64:65] offset:16
	s_waitcnt vmcnt(27) lgkmcnt(3)
	v_lshlrev_b32_e32 v8, 16, v80
	v_and_b32_e32 v9, s98, v80
	v_lshlrev_b32_e32 v10, 16, v81
	v_and_b32_e32 v11, s98, v81
	v_lshlrev_b32_e32 v12, 16, v82
	v_and_b32_e32 v13, s98, v82
	v_lshlrev_b32_e32 v14, 16, v83
	v_and_b32_e32 v15, s98, v83
	v_lshlrev_b32_e32 v22, 16, v112
	v_and_b32_e32 v23, s98, v112
	v_lshlrev_b32_e32 v24, 16, v113
	v_and_b32_e32 v25, s98, v113
	v_lshlrev_b32_e32 v26, 16, v114
	v_and_b32_e32 v27, s98, v114
	v_lshlrev_b32_e32 v28, 16, v115
	v_and_b32_e32 v29, s98, v115
	v_pk_fma_f32 v[22:23], v[8:9], s[38:39], v[22:23] op_sel_hi:[1,0,1]
	v_pk_fma_f32 v[24:25], v[10:11], s[38:39], v[24:25] op_sel_hi:[1,0,1]
	v_pk_fma_f32 v[26:27], v[12:13], s[38:39], v[26:27] op_sel_hi:[1,0,1]
	v_pk_fma_f32 v[28:29], v[14:15], s[38:39], v[28:29] op_sel_hi:[1,0,1]
	v_add_u32_e32 v7, 0xc0000, v20
	global_store_dwordx4 v7, v[22:25], s[64:65]
	global_store_dwordx4 v7, v[26:29], s[64:65] offset:16
	s_waitcnt vmcnt(28) lgkmcnt(2)
	v_lshlrev_b32_e32 v8, 16, v84
	v_and_b32_e32 v9, s98, v84
	v_lshlrev_b32_e32 v10, 16, v85
	v_and_b32_e32 v11, s98, v85
	v_lshlrev_b32_e32 v12, 16, v86
	v_and_b32_e32 v13, s98, v86
	v_lshlrev_b32_e32 v14, 16, v87
	v_and_b32_e32 v15, s98, v87
	v_lshlrev_b32_e32 v22, 16, v116
	v_and_b32_e32 v23, s98, v116
	v_lshlrev_b32_e32 v24, 16, v117
	v_and_b32_e32 v25, s98, v117
	v_lshlrev_b32_e32 v26, 16, v118
	v_and_b32_e32 v27, s98, v118
	v_lshlrev_b32_e32 v28, 16, v119
	v_and_b32_e32 v29, s98, v119
	v_pk_fma_f32 v[22:23], v[8:9], s[38:39], v[22:23] op_sel_hi:[1,0,1]
	v_pk_fma_f32 v[24:25], v[10:11], s[38:39], v[24:25] op_sel_hi:[1,0,1]
	v_pk_fma_f32 v[26:27], v[12:13], s[38:39], v[26:27] op_sel_hi:[1,0,1]
	v_pk_fma_f32 v[28:29], v[14:15], s[38:39], v[28:29] op_sel_hi:[1,0,1]
	v_add_u32_e32 v7, 0xd0000, v20
	global_store_dwordx4 v7, v[22:25], s[64:65]
	global_store_dwordx4 v7, v[26:29], s[64:65] offset:16
	s_waitcnt vmcnt(29) lgkmcnt(1)
	v_lshlrev_b32_e32 v8, 16, v88
	v_and_b32_e32 v9, s98, v88
	v_lshlrev_b32_e32 v10, 16, v89
	v_and_b32_e32 v11, s98, v89
	v_lshlrev_b32_e32 v12, 16, v90
	v_and_b32_e32 v13, s98, v90
	v_lshlrev_b32_e32 v14, 16, v91
	v_and_b32_e32 v15, s98, v91
	v_lshlrev_b32_e32 v22, 16, v120
	v_and_b32_e32 v23, s98, v120
	v_lshlrev_b32_e32 v24, 16, v121
	v_and_b32_e32 v25, s98, v121
	v_lshlrev_b32_e32 v26, 16, v122
	v_and_b32_e32 v27, s98, v122
	v_lshlrev_b32_e32 v28, 16, v123
	v_and_b32_e32 v29, s98, v123
	v_pk_fma_f32 v[22:23], v[8:9], s[38:39], v[22:23] op_sel_hi:[1,0,1]
	v_pk_fma_f32 v[24:25], v[10:11], s[38:39], v[24:25] op_sel_hi:[1,0,1]
	v_pk_fma_f32 v[26:27], v[12:13], s[38:39], v[26:27] op_sel_hi:[1,0,1]
	v_pk_fma_f32 v[28:29], v[14:15], s[38:39], v[28:29] op_sel_hi:[1,0,1]
	v_add_u32_e32 v7, 0xe0000, v20
	global_store_dwordx4 v7, v[22:25], s[64:65]
	global_store_dwordx4 v7, v[26:29], s[64:65] offset:16
	s_waitcnt vmcnt(30) lgkmcnt(0)
	v_lshlrev_b32_e32 v8, 16, v92
	v_and_b32_e32 v9, s98, v92
	v_lshlrev_b32_e32 v10, 16, v93
	v_and_b32_e32 v11, s98, v93
	v_lshlrev_b32_e32 v12, 16, v94
	v_and_b32_e32 v13, s98, v94
	v_lshlrev_b32_e32 v14, 16, v95
	v_and_b32_e32 v15, s98, v95
	v_lshlrev_b32_e32 v22, 16, v124
	v_and_b32_e32 v23, s98, v124
	v_lshlrev_b32_e32 v24, 16, v125
	v_and_b32_e32 v25, s98, v125
	v_lshlrev_b32_e32 v26, 16, v126
	v_and_b32_e32 v27, s98, v126
	v_lshlrev_b32_e32 v28, 16, v127
	v_and_b32_e32 v29, s98, v127
	v_pk_fma_f32 v[22:23], v[8:9], s[38:39], v[22:23] op_sel_hi:[1,0,1]
	v_pk_fma_f32 v[24:25], v[10:11], s[38:39], v[24:25] op_sel_hi:[1,0,1]
	v_pk_fma_f32 v[26:27], v[12:13], s[38:39], v[26:27] op_sel_hi:[1,0,1]
	v_pk_fma_f32 v[28:29], v[14:15], s[38:39], v[28:29] op_sel_hi:[1,0,1]
	v_add_u32_e32 v7, 0xf0000, v20
	global_store_dwordx4 v7, v[22:25], s[64:65]
	global_store_dwordx4 v7, v[26:29], s[64:65] offset:16
	s_movk_i32 s66, 0x2000
	s_add_i32 s70, s70, 1
	s_add_u32 s50, s50, 0x80000
	s_addc_u32 s51, s51, 0
	s_cmp_eq_u32 s70, 4
	s_cbranch_scc0 .LBB0_1023
	s_lshl_b64 s[52:53], s[8:9], 12
	s_mov_b64 s[50:51], 0
	s_barrier
	s_add_u32 s3, s96, s50
	s_addc_u32 s16, s97, s51
	v_mov_b32_e32 v26, v176
	s_add_u32 s3, s3, s62
	v_ashrrev_i32_e32 v0, 1, v26
	s_addc_u32 s16, s16, s63
	v_and_b32_e32 v16, 0xffffffe0, v0
	s_add_u32 s54, s3, 0x18000000
	v_ashrrev_i32_e32 v17, 31, v16
	v_lshlrev_b32_e32 v2, 2, v26
	s_addc_u32 s55, s16, 0
	v_lshlrev_b64 v[24:25], 12, v[16:17]
	v_and_b32_e32 v132, 0xfc, v2
	v_lshl_add_u64 v[0:1], s[54:55], 0, v[24:25]
	v_lshlrev_b32_e32 v22, 2, v132
	v_mov_b32_e32 v23, v133
	v_lshl_add_u64 v[12:13], v[0:1], 0, v[22:23]
	global_load_dwordx4 v[0:3], v[12:13], off
	global_load_dwordx4 v[4:7], v[12:13], off offset:1024
	global_load_dwordx4 v[8:11], v[12:13], off offset:2048
	s_nop 0
	global_load_dwordx4 v[12:15], v[12:13], off offset:3072
	v_xor_b32_e32 v20, 16, v171
	v_and_b32_e32 v30, 63, v26
	v_lshlrev_b64 v[26:27], 10, v[16:17]
	v_cmp_lt_i32_e32 vcc, v20, v178
	v_lshl_add_u64 v[26:27], s[94:95], 0, v[26:27]
	v_lshlrev_b64 v[28:29], 11, v[16:17]
	v_cndmask_b32_e32 v20, v171, v20, vcc
	v_cmp_lt_i32_e32 vcc, v177, v178
	v_readlane_b32 s60, v255, 6
	v_lshl_add_u64 v[24:25], s[52:53], 0, v[24:25]
	v_lshl_add_u64 v[26:27], v[26:27], 0, v[132:133]
	v_lshl_add_u64 v[28:29], s[46:47], 0, v[28:29]
	v_lshlrev_b32_e32 v132, 3, v30
	v_lshlrev_b32_e32 v36, 2, v20
	v_cndmask_b32_e32 v20, v171, v177, vcc
	v_readlane_b32 s64, v255, 10
	v_readlane_b32 s65, v255, 11
	v_readlane_b32 s66, v255, 12
	v_readlane_b32 s67, v255, 13
	v_lshl_or_b32 v24, v30, 4, v24
	v_lshl_add_u64 v[28:29], v[28:29], 0, v[132:133]
	v_lshl_add_u64 v[18:19], s[54:55], 0, v[22:23]
	s_mov_b32 s3, 0
	v_lshlrev_b32_e32 v141, 2, v20
	v_lshl_add_u64 v[20:21], s[64:65], 0, v[22:23]
	v_lshl_add_u64 v[22:23], s[66:67], 0, v[22:23]
	v_lshl_add_u64 v[24:25], s[10:11], 0, v[24:25]
	v_lshl_add_u64 v[26:27], s[12:13], 0, v[26:27]
	v_lshl_add_u64 v[28:29], s[14:15], 0, v[28:29]
	v_readlane_b32 s61, v255, 7
	v_readlane_b32 s62, v255, 8
	v_readlane_b32 s63, v255, 9
	v_readlane_b32 s68, v255, 14
	v_readlane_b32 s69, v255, 15
	v_readlane_b32 s70, v255, 16
	v_readlane_b32 s71, v255, 17
	v_readlane_b32 s72, v255, 18
	v_readlane_b32 s73, v255, 19
	v_readlane_b32 s74, v255, 20
	v_readlane_b32 s75, v255, 21

.LBB0_1036:
	s_and_b32 s64, s68, 0x10000
	v_add_u32_e32 v132, s64, v143
	v_or_b32_e32 v151, s64, v144
	ds_read_b128 v[152:155], v132
	ds_read_b128 v[156:159], v132 offset:4096
	ds_read_b128 v[160:163], v132 offset:8192
	ds_read_b128 v[164:167], v132 offset:12288
	ds_read_b128 v[172:175], v151
	ds_read_b128 v[180:183], v151 offset:4096
	v_add_u32_e32 v214, s64, v145
	v_or_b32_e32 v215, s64, v146
	ds_read_b128 v[216:219], v214
	ds_read_b128 v[220:223], v214 offset:4096
	ds_read_b128 v[224:227], v214 offset:8192
	ds_read_b128 v[228:231], v214 offset:12288
	ds_read_b128 v[232:235], v215
	ds_read_b128 v[236:239], v215 offset:4096
	v_add_u32_e32 v132, s64, v147
	v_or_b32_e32 v151, s64, v148
	s_waitcnt lgkmcnt(6)
	v_mfma_f32_32x32x16_bf16 v[112:127], v[172:175], v[152:155], v[112:127]
	s_add_u32 s62, s62, 0x80
	s_addc_u32 s63, s63, 0
	s_add_i32 s3, s3, 1
	s_cmpk_lg_i32 s62, 0x800
	s_mov_b32 s68, s69
	v_mfma_f32_32x32x16_bf16 v[80:95], v[172:175], v[156:159], v[80:95]
	v_mfma_f32_32x32x16_bf16 v[48:63], v[172:175], v[160:163], v[48:63]
	v_mfma_f32_32x32x16_bf16 v[16:31], v[172:175], v[164:167], v[16:31]
	v_mfma_f32_32x32x16_bf16 v[96:111], v[180:183], v[152:155], v[96:111]
	v_mfma_f32_32x32x16_bf16 v[64:79], v[180:183], v[156:159], v[64:79]
	v_mfma_f32_32x32x16_bf16 v[32:47], v[180:183], v[160:163], v[32:47]
	v_mfma_f32_32x32x16_bf16 v[0:15], v[180:183], v[164:167], v[0:15]
	ds_read_b128 v[152:155], v132
	ds_read_b128 v[156:159], v132 offset:4096
	ds_read_b128 v[160:163], v132 offset:8192
	ds_read_b128 v[164:167], v132 offset:12288
	ds_read_b128 v[172:175], v151
	ds_read_b128 v[180:183], v151 offset:4096
	v_add_u32_e32 v214, s64, v149
	v_or_b32_e32 v215, s64, v150
	s_waitcnt lgkmcnt(6)
	v_mfma_f32_32x32x16_bf16 v[112:127], v[232:235], v[216:219], v[112:127]
	v_mfma_f32_32x32x16_bf16 v[80:95], v[232:235], v[220:223], v[80:95]
	v_mfma_f32_32x32x16_bf16 v[48:63], v[232:235], v[224:227], v[48:63]
	v_mfma_f32_32x32x16_bf16 v[16:31], v[232:235], v[228:231], v[16:31]
	v_mfma_f32_32x32x16_bf16 v[96:111], v[236:239], v[216:219], v[96:111]
	v_mfma_f32_32x32x16_bf16 v[64:79], v[236:239], v[220:223], v[64:79]
	v_mfma_f32_32x32x16_bf16 v[32:47], v[236:239], v[224:227], v[32:47]
	v_mfma_f32_32x32x16_bf16 v[0:15], v[236:239], v[228:231], v[0:15]
	ds_read_b128 v[216:219], v214
	ds_read_b128 v[220:223], v214 offset:4096
	ds_read_b128 v[224:227], v214 offset:8192
	ds_read_b128 v[228:231], v214 offset:12288
	ds_read_b128 v[232:235], v215
	ds_read_b128 v[236:239], v215 offset:4096
	s_waitcnt lgkmcnt(6)
	v_mfma_f32_32x32x16_bf16 v[112:127], v[172:175], v[152:155], v[112:127]
	v_mfma_f32_32x32x16_bf16 v[80:95], v[172:175], v[156:159], v[80:95]
	v_mfma_f32_32x32x16_bf16 v[48:63], v[172:175], v[160:163], v[48:63]
	v_mfma_f32_32x32x16_bf16 v[16:31], v[172:175], v[164:167], v[16:31]
	v_mfma_f32_32x32x16_bf16 v[96:111], v[180:183], v[152:155], v[96:111]
	v_mfma_f32_32x32x16_bf16 v[64:79], v[180:183], v[156:159], v[64:79]
	v_mfma_f32_32x32x16_bf16 v[32:47], v[180:183], v[160:163], v[32:47]
	v_mfma_f32_32x32x16_bf16 v[0:15], v[180:183], v[164:167], v[0:15]
	s_waitcnt lgkmcnt(0)
	v_mfma_f32_32x32x16_bf16 v[112:127], v[232:235], v[216:219], v[112:127]
	v_mfma_f32_32x32x16_bf16 v[80:95], v[232:235], v[220:223], v[80:95]
	v_mfma_f32_32x32x16_bf16 v[48:63], v[232:235], v[224:227], v[48:63]
	v_mfma_f32_32x32x16_bf16 v[16:31], v[232:235], v[228:231], v[16:31]
	v_mfma_f32_32x32x16_bf16 v[96:111], v[236:239], v[216:219], v[96:111]
	v_mfma_f32_32x32x16_bf16 v[64:79], v[236:239], v[220:223], v[64:79]
	v_mfma_f32_32x32x16_bf16 v[32:47], v[236:239], v[224:227], v[32:47]
	v_mfma_f32_32x32x16_bf16 v[0:15], v[236:239], v[228:231], v[0:15]
	s_cbranch_scc0 .LBB0_1041

.LBB0_1046:
	s_and_b32 s60, s63, 0x10000
	v_add_u32_e32 v132, s60, v143
	v_or_b32_e32 v151, s60, v144
	ds_read_b128 v[152:155], v132
	ds_read_b128 v[156:159], v132 offset:4096
	ds_read_b128 v[160:163], v132 offset:8192
	ds_read_b128 v[164:167], v132 offset:12288
	ds_read_b128 v[172:175], v151
	ds_read_b128 v[180:183], v151 offset:4096
	v_add_u32_e32 v214, s60, v145
	v_or_b32_e32 v215, s60, v146
	ds_read_b128 v[216:219], v214
	ds_read_b128 v[220:223], v214 offset:4096
	ds_read_b128 v[224:227], v214 offset:8192
	ds_read_b128 v[228:231], v214 offset:12288
	ds_read_b128 v[232:235], v215
	ds_read_b128 v[236:239], v215 offset:4096
	v_add_u32_e32 v132, s60, v147
	v_or_b32_e32 v151, s60, v148
	s_waitcnt lgkmcnt(6)
	v_mfma_f32_32x32x16_bf16 v[112:127], v[172:175], v[152:155], v[112:127]
	s_add_u32 s58, s58, 0x80
	s_addc_u32 s59, s59, 0
	s_add_i32 s62, s62, 1
	s_cmpk_lg_i32 s58, 0x200
	s_mov_b32 s63, s64
	v_mfma_f32_32x32x16_bf16 v[96:111], v[172:175], v[156:159], v[96:111]
	v_mfma_f32_32x32x16_bf16 v[64:79], v[172:175], v[160:163], v[64:79]
	v_mfma_f32_32x32x16_bf16 v[32:47], v[172:175], v[164:167], v[32:47]
	v_mfma_f32_32x32x16_bf16 v[80:95], v[180:183], v[152:155], v[80:95]
	v_mfma_f32_32x32x16_bf16 v[48:63], v[180:183], v[156:159], v[48:63]
	v_mfma_f32_32x32x16_bf16 v[16:31], v[180:183], v[160:163], v[16:31]
	v_mfma_f32_32x32x16_bf16 v[0:15], v[180:183], v[164:167], v[0:15]
	ds_read_b128 v[152:155], v132
	ds_read_b128 v[156:159], v132 offset:4096
	ds_read_b128 v[160:163], v132 offset:8192
	ds_read_b128 v[164:167], v132 offset:12288
	ds_read_b128 v[172:175], v151
	ds_read_b128 v[180:183], v151 offset:4096
	v_add_u32_e32 v214, s60, v149
	v_or_b32_e32 v215, s60, v150
	s_waitcnt lgkmcnt(6)
	v_mfma_f32_32x32x16_bf16 v[112:127], v[232:235], v[216:219], v[112:127]
	v_mfma_f32_32x32x16_bf16 v[96:111], v[232:235], v[220:223], v[96:111]
	v_mfma_f32_32x32x16_bf16 v[64:79], v[232:235], v[224:227], v[64:79]
	v_mfma_f32_32x32x16_bf16 v[32:47], v[232:235], v[228:231], v[32:47]
	v_mfma_f32_32x32x16_bf16 v[80:95], v[236:239], v[216:219], v[80:95]
	v_mfma_f32_32x32x16_bf16 v[48:63], v[236:239], v[220:223], v[48:63]
	v_mfma_f32_32x32x16_bf16 v[16:31], v[236:239], v[224:227], v[16:31]
	v_mfma_f32_32x32x16_bf16 v[0:15], v[236:239], v[228:231], v[0:15]
	ds_read_b128 v[216:219], v214
	ds_read_b128 v[220:223], v214 offset:4096
	ds_read_b128 v[224:227], v214 offset:8192
	ds_read_b128 v[228:231], v214 offset:12288
	ds_read_b128 v[232:235], v215
	ds_read_b128 v[236:239], v215 offset:4096
	s_waitcnt lgkmcnt(6)
	v_mfma_f32_32x32x16_bf16 v[112:127], v[172:175], v[152:155], v[112:127]
	v_mfma_f32_32x32x16_bf16 v[96:111], v[172:175], v[156:159], v[96:111]
	v_mfma_f32_32x32x16_bf16 v[64:79], v[172:175], v[160:163], v[64:79]
	v_mfma_f32_32x32x16_bf16 v[32:47], v[172:175], v[164:167], v[32:47]
	v_mfma_f32_32x32x16_bf16 v[80:95], v[180:183], v[152:155], v[80:95]
	v_mfma_f32_32x32x16_bf16 v[48:63], v[180:183], v[156:159], v[48:63]
	v_mfma_f32_32x32x16_bf16 v[16:31], v[180:183], v[160:163], v[16:31]
	v_mfma_f32_32x32x16_bf16 v[0:15], v[180:183], v[164:167], v[0:15]
	s_waitcnt lgkmcnt(0)
	v_mfma_f32_32x32x16_bf16 v[112:127], v[232:235], v[216:219], v[112:127]
	v_mfma_f32_32x32x16_bf16 v[96:111], v[232:235], v[220:223], v[96:111]
	v_mfma_f32_32x32x16_bf16 v[64:79], v[232:235], v[224:227], v[64:79]
	v_mfma_f32_32x32x16_bf16 v[32:47], v[232:235], v[228:231], v[32:47]
	v_mfma_f32_32x32x16_bf16 v[80:95], v[236:239], v[216:219], v[80:95]
	v_mfma_f32_32x32x16_bf16 v[48:63], v[236:239], v[220:223], v[48:63]
	v_mfma_f32_32x32x16_bf16 v[16:31], v[236:239], v[224:227], v[16:31]
	v_mfma_f32_32x32x16_bf16 v[0:15], v[236:239], v[228:231], v[0:15]
	s_cbranch_scc0 .LBB0_1051

.LBB0_1051:
	v_mov_b32_e32 v128, v176
	s_waitcnt vmcnt(0) lgkmcnt(0)
	s_barrier
	s_nop 4
	v_cvt_pk_bf16_f32 v80, v80, v81
	v_and_b32_e32 v129, 0xc0, v128
	v_and_b32_e32 v130, 31, v128
	v_lshrrev_b32_e32 v131, 1, v128
	v_lshrrev_b32_e32 v128, 2, v128
	v_and_b32_e32 v128, 8, v128
	v_and_or_b32 v130, v131, s93, v130
	v_lshl_or_b32 v128, v129, 1, v128
	v_mad_u64_u32 v[128:129], s[58:59], v130, s0, v[128:129]
	v_cvt_pk_bf16_f32 v81, v82, v83
	v_cvt_pk_bf16_f32 v82, v84, v85
	v_cvt_pk_bf16_f32 v83, v86, v87
	v_add_u32_e32 v84, 0x4000, v128
	v_cvt_pk_bf16_f32 v48, v48, v49
	v_cvt_pk_bf16_f32 v49, v50, v51
	v_cvt_pk_bf16_f32 v50, v52, v53
	v_cvt_pk_bf16_f32 v51, v54, v55
	v_add_u32_e32 v52, 0x8000, v128
	v_cvt_pk_bf16_f32 v16, v16, v17
	v_cvt_pk_bf16_f32 v17, v18, v19
	v_cvt_pk_bf16_f32 v18, v20, v21
	v_cvt_pk_bf16_f32 v19, v22, v23
	ds_write2_b64 v128, v[80:81], v[82:83] offset0:8 offset1:10
	v_cvt_pk_bf16_f32 v80, v88, v89
	v_cvt_pk_bf16_f32 v81, v90, v91
	v_cvt_pk_bf16_f32 v82, v92, v93
	v_cvt_pk_bf16_f32 v83, v94, v95
	ds_write2_b64 v84, v[48:49], v[50:51] offset0:72 offset1:74
	v_cvt_pk_bf16_f32 v48, v56, v57
	v_cvt_pk_bf16_f32 v49, v58, v59
	v_cvt_pk_bf16_f32 v50, v60, v61
	v_cvt_pk_bf16_f32 v51, v62, v63
	ds_write2_b64 v52, v[16:17], v[18:19] offset0:136 offset1:138
	v_cvt_pk_bf16_f32 v16, v24, v25
	v_cvt_pk_bf16_f32 v17, v26, v27
	v_cvt_pk_bf16_f32 v18, v28, v29
	v_cvt_pk_bf16_f32 v19, v30, v31
	v_add_u32_e32 v20, 0xc000, v128
	v_cvt_pk_bf16_f32 v0, v0, v1
	v_cvt_pk_bf16_f32 v1, v2, v3
	v_cvt_pk_bf16_f32 v2, v4, v5
	v_cvt_pk_bf16_f32 v3, v6, v7
	v_cvt_pk_bf16_f32 v112, v112, v113
	v_cvt_pk_bf16_f32 v113, v114, v115
	v_cvt_pk_bf16_f32 v114, v116, v117
	v_cvt_pk_bf16_f32 v115, v118, v119
	ds_write2_b64 v128, v[80:81], v[82:83] offset0:12 offset1:14
	v_cvt_pk_bf16_f32 v80, v96, v97
	v_cvt_pk_bf16_f32 v81, v98, v99
	v_cvt_pk_bf16_f32 v82, v100, v101
	v_cvt_pk_bf16_f32 v83, v102, v103
	ds_write2_b64 v84, v[48:49], v[50:51] offset0:76 offset1:78
	v_cvt_pk_bf16_f32 v48, v64, v65
	v_cvt_pk_bf16_f32 v49, v66, v67
	v_cvt_pk_bf16_f32 v50, v68, v69
	v_cvt_pk_bf16_f32 v51, v70, v71
	ds_write2_b64 v52, v[16:17], v[18:19] offset0:140 offset1:142
	v_cvt_pk_bf16_f32 v16, v32, v33
	v_cvt_pk_bf16_f32 v17, v34, v35
	v_cvt_pk_bf16_f32 v18, v36, v37
	v_cvt_pk_bf16_f32 v19, v38, v39
	ds_write2_b64 v20, v[0:1], v[2:3] offset0:200 offset1:202
	v_cvt_pk_bf16_f32 v0, v8, v9
	v_cvt_pk_bf16_f32 v1, v10, v11
	v_cvt_pk_bf16_f32 v2, v12, v13
	v_cvt_pk_bf16_f32 v3, v14, v15
	ds_write2_b64 v128, v[112:113], v[114:115] offset1:2
	v_cvt_pk_bf16_f32 v112, v120, v121
	v_cvt_pk_bf16_f32 v113, v122, v123
	v_cvt_pk_bf16_f32 v114, v124, v125
	v_cvt_pk_bf16_f32 v115, v126, v127
	ds_write2_b64 v84, v[80:81], v[82:83] offset0:64 offset1:66
	v_cvt_pk_bf16_f32 v80, v104, v105
	v_cvt_pk_bf16_f32 v81, v106, v107
	v_cvt_pk_bf16_f32 v82, v108, v109
	v_cvt_pk_bf16_f32 v83, v110, v111
	ds_write2_b64 v52, v[48:49], v[50:51] offset0:128 offset1:130
	v_cvt_pk_bf16_f32 v48, v72, v73
	v_cvt_pk_bf16_f32 v49, v74, v75
	v_cvt_pk_bf16_f32 v50, v76, v77
	v_cvt_pk_bf16_f32 v51, v78, v79
	ds_write2_b64 v20, v[16:17], v[18:19] offset0:192 offset1:194
	v_cvt_pk_bf16_f32 v16, v40, v41
	v_cvt_pk_bf16_f32 v17, v42, v43
	v_cvt_pk_bf16_f32 v18, v44, v45
	v_cvt_pk_bf16_f32 v19, v46, v47
	ds_write2_b64 v20, v[0:1], v[2:3] offset0:204 offset1:206
	v_mov_b32_e32 v1, v176
	ds_write2_b64 v128, v[112:113], v[114:115] offset0:4 offset1:6
	ds_write2_b64 v84, v[80:81], v[82:83] offset0:68 offset1:70
	ds_write2_b64 v52, v[48:49], v[50:51] offset0:132 offset1:134
	ds_write2_b64 v20, v[16:17], v[18:19] offset0:196 offset1:198
	s_waitcnt lgkmcnt(0)
	s_barrier
	v_mov_b32_e32 v1, v176
	s_mov_b32 s98, 0xffff0000
	v_lshlrev_b32_e32 v0, 4, v1
	v_and_b32_e32 v0, 0x1f0, v0
	v_lshrrev_b32_e32 v2, 5, v1
	v_mov_b32_e32 v6, 0x210
	v_mad_u32_u24 v4, v2, v6, v0
	v_add_u32_e32 v5, 0x10800, v4
	v_lshl_or_b32 v132, s16, 9, v0
	v_lshl_add_u32 v3, v2, 11, v132
	v_add_u32_e32 v6, 0x0, v3
	global_load_dwordx4 v[32:35], v6, s[52:53]
	ds_read_b128 v[96:99], v4
	v_add_u32_e32 v6, 0x8000, v3
	global_load_dwordx4 v[36:39], v6, s[52:53]
	ds_read_b128 v[100:103], v4 offset:8448
	v_add_u32_e32 v6, 0x10000, v3
	global_load_dwordx4 v[40:43], v6, s[52:53]
	ds_read_b128 v[104:107], v4 offset:16896
	v_add_u32_e32 v6, 0x18000, v3
	global_load_dwordx4 v[44:47], v6, s[52:53]
	ds_read_b128 v[108:111], v4 offset:25344
	v_add_u32_e32 v6, 0x20000, v3
	global_load_dwordx4 v[48:51], v6, s[52:53]
	ds_read_b128 v[112:115], v4 offset:33792
	v_add_u32_e32 v6, 0x28000, v3
	global_load_dwordx4 v[52:55], v6, s[52:53]
	ds_read_b128 v[116:119], v4 offset:42240
	v_add_u32_e32 v6, 0x30000, v3
	global_load_dwordx4 v[56:59], v6, s[52:53]
	ds_read_b128 v[120:123], v4 offset:50688
	v_add_u32_e32 v6, 0x38000, v3
	global_load_dwordx4 v[60:63], v6, s[52:53]
	ds_read_b128 v[124:127], v4 offset:59136
	v_add_u32_e32 v6, 0x40000, v3
	global_load_dwordx4 v[64:67], v6, s[52:53]
	v_add_u32_e32 v6, 0x48000, v3
	global_load_dwordx4 v[68:71], v6, s[52:53]
	v_add_u32_e32 v6, 0x50000, v3
	global_load_dwordx4 v[72:75], v6, s[52:53]
	v_add_u32_e32 v6, 0x58000, v3
	global_load_dwordx4 v[76:79], v6, s[52:53]
	v_add_u32_e32 v6, 0x60000, v3
	global_load_dwordx4 v[80:83], v6, s[52:53]
	v_add_u32_e32 v6, 0x68000, v3
	global_load_dwordx4 v[84:87], v6, s[52:53]
	v_add_u32_e32 v6, 0x70000, v3
	global_load_dwordx4 v[88:91], v6, s[52:53]
	v_add_u32_e32 v6, 0x78000, v3
	global_load_dwordx4 v[92:95], v6, s[52:53]
	s_waitcnt vmcnt(15) lgkmcnt(7)
	v_lshlrev_b32_e32 v8, 16, v96
	v_and_b32_e32 v9, s98, v96
	v_lshlrev_b32_e32 v10, 16, v32
	v_and_b32_e32 v11, s98, v32
	v_lshlrev_b32_e32 v12, 16, v97
	v_and_b32_e32 v13, s98, v97
	v_lshlrev_b32_e32 v14, 16, v33
	v_and_b32_e32 v15, s98, v33
	v_pk_mul_f32 v[8:9], v[8:9], v[10:11]
	v_pk_mul_f32 v[12:13], v[12:13], v[14:15]
	v_cvt_pk_bf16_f32 v32, v8, v9
	v_cvt_pk_bf16_f32 v33, v12, v13
	v_lshlrev_b32_e32 v8, 16, v98
	v_and_b32_e32 v9, s98, v98
	v_lshlrev_b32_e32 v10, 16, v34
	v_and_b32_e32 v11, s98, v34
	v_lshlrev_b32_e32 v12, 16, v99
	v_and_b32_e32 v13, s98, v99
	v_lshlrev_b32_e32 v14, 16, v35
	v_and_b32_e32 v15, s98, v35
	v_pk_mul_f32 v[8:9], v[8:9], v[10:11]
	v_pk_mul_f32 v[12:13], v[12:13], v[14:15]
	v_cvt_pk_bf16_f32 v34, v8, v9
	v_cvt_pk_bf16_f32 v35, v12, v13
	ds_read_b128 v[96:99], v5
	v_add_u32_e32 v7, 0x0, v3
	global_store_dwordx4 v7, v[32:35], s[52:53]
	s_waitcnt vmcnt(15) lgkmcnt(7)
	v_lshlrev_b32_e32 v8, 16, v100
	v_and_b32_e32 v9, s98, v100
	v_lshlrev_b32_e32 v10, 16, v36
	v_and_b32_e32 v11, s98, v36
	v_lshlrev_b32_e32 v12, 16, v101
	v_and_b32_e32 v13, s98, v101
	v_lshlrev_b32_e32 v14, 16, v37
	v_and_b32_e32 v15, s98, v37
	v_pk_mul_f32 v[8:9], v[8:9], v[10:11]
	v_pk_mul_f32 v[12:13], v[12:13], v[14:15]
	v_cvt_pk_bf16_f32 v36, v8, v9
	v_cvt_pk_bf16_f32 v37, v12, v13
	v_lshlrev_b32_e32 v8, 16, v102
	v_and_b32_e32 v9, s98, v102
	v_lshlrev_b32_e32 v10, 16, v38
	v_and_b32_e32 v11, s98, v38
	v_lshlrev_b32_e32 v12, 16, v103
	v_and_b32_e32 v13, s98, v103
	v_lshlrev_b32_e32 v14, 16, v39
	v_and_b32_e32 v15, s98, v39
	v_pk_mul_f32 v[8:9], v[8:9], v[10:11]
	v_pk_mul_f32 v[12:13], v[12:13], v[14:15]
	v_cvt_pk_bf16_f32 v38, v8, v9
	v_cvt_pk_bf16_f32 v39, v12, v13
	ds_read_b128 v[100:103], v5 offset:8448
	v_add_u32_e32 v7, 0x8000, v3
	global_store_dwordx4 v7, v[36:39], s[52:53]
	s_waitcnt vmcnt(15) lgkmcnt(7)
	v_lshlrev_b32_e32 v8, 16, v104
	v_and_b32_e32 v9, s98, v104
	v_lshlrev_b32_e32 v10, 16, v40
	v_and_b32_e32 v11, s98, v40
	v_lshlrev_b32_e32 v12, 16, v105
	v_and_b32_e32 v13, s98, v105
	v_lshlrev_b32_e32 v14, 16, v41
	v_and_b32_e32 v15, s98, v41
	v_pk_mul_f32 v[8:9], v[8:9], v[10:11]
	v_pk_mul_f32 v[12:13], v[12:13], v[14:15]
	v_cvt_pk_bf16_f32 v40, v8, v9
	v_cvt_pk_bf16_f32 v41, v12, v13
	v_lshlrev_b32_e32 v8, 16, v106
	v_and_b32_e32 v9, s98, v106
	v_lshlrev_b32_e32 v10, 16, v42
	v_and_b32_e32 v11, s98, v42
	v_lshlrev_b32_e32 v12, 16, v107
	v_and_b32_e32 v13, s98, v107
	v_lshlrev_b32_e32 v14, 16, v43
	v_and_b32_e32 v15, s98, v43
	v_pk_mul_f32 v[8:9], v[8:9], v[10:11]
	v_pk_mul_f32 v[12:13], v[12:13], v[14:15]
	v_cvt_pk_bf16_f32 v42, v8, v9
	v_cvt_pk_bf16_f32 v43, v12, v13
	ds_read_b128 v[104:107], v5 offset:16896
	v_add_u32_e32 v7, 0x10000, v3
	global_store_dwordx4 v7, v[40:43], s[52:53]
	s_waitcnt vmcnt(15) lgkmcnt(7)
	v_lshlrev_b32_e32 v8, 16, v108
	v_and_b32_e32 v9, s98, v108
	v_lshlrev_b32_e32 v10, 16, v44
	v_and_b32_e32 v11, s98, v44
	v_lshlrev_b32_e32 v12, 16, v109
	v_and_b32_e32 v13, s98, v109
	v_lshlrev_b32_e32 v14, 16, v45
	v_and_b32_e32 v15, s98, v45
	v_pk_mul_f32 v[8:9], v[8:9], v[10:11]
	v_pk_mul_f32 v[12:13], v[12:13], v[14:15]
	v_cvt_pk_bf16_f32 v44, v8, v9
	v_cvt_pk_bf16_f32 v45, v12, v13
	v_lshlrev_b32_e32 v8, 16, v110
	v_and_b32_e32 v9, s98, v110
	v_lshlrev_b32_e32 v10, 16, v46
	v_and_b32_e32 v11, s98, v46
	v_lshlrev_b32_e32 v12, 16, v111
	v_and_b32_e32 v13, s98, v111
	v_lshlrev_b32_e32 v14, 16, v47
	v_and_b32_e32 v15, s98, v47
	v_pk_mul_f32 v[8:9], v[8:9], v[10:11]
	v_pk_mul_f32 v[12:13], v[12:13], v[14:15]
	v_cvt_pk_bf16_f32 v46, v8, v9
	v_cvt_pk_bf16_f32 v47, v12, v13
	ds_read_b128 v[108:111], v5 offset:25344
	v_add_u32_e32 v7, 0x18000, v3
	global_store_dwordx4 v7, v[44:47], s[52:53]
	s_waitcnt vmcnt(15) lgkmcnt(7)
	v_lshlrev_b32_e32 v8, 16, v112
	v_and_b32_e32 v9, s98, v112
	v_lshlrev_b32_e32 v10, 16, v48
	v_and_b32_e32 v11, s98, v48
	v_lshlrev_b32_e32 v12, 16, v113
	v_and_b32_e32 v13, s98, v113
	v_lshlrev_b32_e32 v14, 16, v49
	v_and_b32_e32 v15, s98, v49
	v_pk_mul_f32 v[8:9], v[8:9], v[10:11]
	v_pk_mul_f32 v[12:13], v[12:13], v[14:15]
	v_cvt_pk_bf16_f32 v48, v8, v9
	v_cvt_pk_bf16_f32 v49, v12, v13
	v_lshlrev_b32_e32 v8, 16, v114
	v_and_b32_e32 v9, s98, v114
	v_lshlrev_b32_e32 v10, 16, v50
	v_and_b32_e32 v11, s98, v50
	v_lshlrev_b32_e32 v12, 16, v115
	v_and_b32_e32 v13, s98, v115
	v_lshlrev_b32_e32 v14, 16, v51
	v_and_b32_e32 v15, s98, v51
	v_pk_mul_f32 v[8:9], v[8:9], v[10:11]
	v_pk_mul_f32 v[12:13], v[12:13], v[14:15]
	v_cvt_pk_bf16_f32 v50, v8, v9
	v_cvt_pk_bf16_f32 v51, v12, v13
	ds_read_b128 v[112:115], v5 offset:33792
	v_add_u32_e32 v7, 0x20000, v3
	global_store_dwordx4 v7, v[48:51], s[52:53]
	s_waitcnt vmcnt(15) lgkmcnt(7)
	v_lshlrev_b32_e32 v8, 16, v116
	v_and_b32_e32 v9, s98, v116
	v_lshlrev_b32_e32 v10, 16, v52
	v_and_b32_e32 v11, s98, v52
	v_lshlrev_b32_e32 v12, 16, v117
	v_and_b32_e32 v13, s98, v117
	v_lshlrev_b32_e32 v14, 16, v53
	v_and_b32_e32 v15, s98, v53
	v_pk_mul_f32 v[8:9], v[8:9], v[10:11]
	v_pk_mul_f32 v[12:13], v[12:13], v[14:15]
	v_cvt_pk_bf16_f32 v52, v8, v9
	v_cvt_pk_bf16_f32 v53, v12, v13
	v_lshlrev_b32_e32 v8, 16, v118
	v_and_b32_e32 v9, s98, v118
	v_lshlrev_b32_e32 v10, 16, v54
	v_and_b32_e32 v11, s98, v54
	v_lshlrev_b32_e32 v12, 16, v119
	v_and_b32_e32 v13, s98, v119
	v_lshlrev_b32_e32 v14, 16, v55
	v_and_b32_e32 v15, s98, v55
	v_pk_mul_f32 v[8:9], v[8:9], v[10:11]
	v_pk_mul_f32 v[12:13], v[12:13], v[14:15]
	v_cvt_pk_bf16_f32 v54, v8, v9
	v_cvt_pk_bf16_f32 v55, v12, v13
	ds_read_b128 v[116:119], v5 offset:42240
	v_add_u32_e32 v7, 0x28000, v3
	global_store_dwordx4 v7, v[52:55], s[52:53]
	s_waitcnt vmcnt(15) lgkmcnt(7)
	v_lshlrev_b32_e32 v8, 16, v120
	v_and_b32_e32 v9, s98, v120
	v_lshlrev_b32_e32 v10, 16, v56
	v_and_b32_e32 v11, s98, v56
	v_lshlrev_b32_e32 v12, 16, v121
	v_and_b32_e32 v13, s98, v121
	v_lshlrev_b32_e32 v14, 16, v57
	v_and_b32_e32 v15, s98, v57
	v_pk_mul_f32 v[8:9], v[8:9], v[10:11]
	v_pk_mul_f32 v[12:13], v[12:13], v[14:15]
	v_cvt_pk_bf16_f32 v56, v8, v9
	v_cvt_pk_bf16_f32 v57, v12, v13
	v_lshlrev_b32_e32 v8, 16, v122
	v_and_b32_e32 v9, s98, v122
	v_lshlrev_b32_e32 v10, 16, v58
	v_and_b32_e32 v11, s98, v58
	v_lshlrev_b32_e32 v12, 16, v123
	v_and_b32_e32 v13, s98, v123
	v_lshlrev_b32_e32 v14, 16, v59
	v_and_b32_e32 v15, s98, v59
	v_pk_mul_f32 v[8:9], v[8:9], v[10:11]
	v_pk_mul_f32 v[12:13], v[12:13], v[14:15]
	v_cvt_pk_bf16_f32 v58, v8, v9
	v_cvt_pk_bf16_f32 v59, v12, v13
	ds_read_b128 v[120:123], v5 offset:50688
	v_add_u32_e32 v7, 0x30000, v3
	global_store_dwordx4 v7, v[56:59], s[52:53]
	s_waitcnt vmcnt(15) lgkmcnt(7)
	v_lshlrev_b32_e32 v8, 16, v124
	v_and_b32_e32 v9, s98, v124
	v_lshlrev_b32_e32 v10, 16, v60
	v_and_b32_e32 v11, s98, v60
	v_lshlrev_b32_e32 v12, 16, v125
	v_and_b32_e32 v13, s98, v125
	v_lshlrev_b32_e32 v14, 16, v61
	v_and_b32_e32 v15, s98, v61
	v_pk_mul_f32 v[8:9], v[8:9], v[10:11]
	v_pk_mul_f32 v[12:13], v[12:13], v[14:15]
	v_cvt_pk_bf16_f32 v60, v8, v9
	v_cvt_pk_bf16_f32 v61, v12, v13
	v_lshlrev_b32_e32 v8, 16, v126
	v_and_b32_e32 v9, s98, v126
	v_lshlrev_b32_e32 v10, 16, v62
	v_and_b32_e32 v11, s98, v62
	v_lshlrev_b32_e32 v12, 16, v127
	v_and_b32_e32 v13, s98, v127
	v_lshlrev_b32_e32 v14, 16, v63
	v_and_b32_e32 v15, s98, v63
	v_pk_mul_f32 v[8:9], v[8:9], v[10:11]
	v_pk_mul_f32 v[12:13], v[12:13], v[14:15]
	v_cvt_pk_bf16_f32 v62, v8, v9
	v_cvt_pk_bf16_f32 v63, v12, v13
	ds_read_b128 v[124:127], v5 offset:59136
	v_add_u32_e32 v7, 0x38000, v3
	global_store_dwordx4 v7, v[60:63], s[52:53]
	s_waitcnt vmcnt(15) lgkmcnt(7)
	v_lshlrev_b32_e32 v8, 16, v96
	v_and_b32_e32 v9, s98, v96
	v_lshlrev_b32_e32 v10, 16, v64
	v_and_b32_e32 v11, s98, v64
	v_lshlrev_b32_e32 v12, 16, v97
	v_and_b32_e32 v13, s98, v97
	v_lshlrev_b32_e32 v14, 16, v65
	v_and_b32_e32 v15, s98, v65
	v_pk_mul_f32 v[8:9], v[8:9], v[10:11]
	v_pk_mul_f32 v[12:13], v[12:13], v[14:15]
	v_cvt_pk_bf16_f32 v64, v8, v9
	v_cvt_pk_bf16_f32 v65, v12, v13
	v_lshlrev_b32_e32 v8, 16, v98
	v_and_b32_e32 v9, s98, v98
	v_lshlrev_b32_e32 v10, 16, v66
	v_and_b32_e32 v11, s98, v66
	v_lshlrev_b32_e32 v12, 16, v99
	v_and_b32_e32 v13, s98, v99
	v_lshlrev_b32_e32 v14, 16, v67
	v_and_b32_e32 v15, s98, v67
	v_pk_mul_f32 v[8:9], v[8:9], v[10:11]
	v_pk_mul_f32 v[12:13], v[12:13], v[14:15]
	v_cvt_pk_bf16_f32 v66, v8, v9
	v_cvt_pk_bf16_f32 v67, v12, v13
	v_add_u32_e32 v7, 0x40000, v3
	global_store_dwordx4 v7, v[64:67], s[52:53]
	s_waitcnt vmcnt(15) lgkmcnt(6)
	v_lshlrev_b32_e32 v8, 16, v100
	v_and_b32_e32 v9, s98, v100
	v_lshlrev_b32_e32 v10, 16, v68
	v_and_b32_e32 v11, s98, v68
	v_lshlrev_b32_e32 v12, 16, v101
	v_and_b32_e32 v13, s98, v101
	v_lshlrev_b32_e32 v14, 16, v69
	v_and_b32_e32 v15, s98, v69
	v_pk_mul_f32 v[8:9], v[8:9], v[10:11]
	v_pk_mul_f32 v[12:13], v[12:13], v[14:15]
	v_cvt_pk_bf16_f32 v68, v8, v9
	v_cvt_pk_bf16_f32 v69, v12, v13
	v_lshlrev_b32_e32 v8, 16, v102
	v_and_b32_e32 v9, s98, v102
	v_lshlrev_b32_e32 v10, 16, v70
	v_and_b32_e32 v11, s98, v70
	v_lshlrev_b32_e32 v12, 16, v103
	v_and_b32_e32 v13, s98, v103
	v_lshlrev_b32_e32 v14, 16, v71
	v_and_b32_e32 v15, s98, v71
	v_pk_mul_f32 v[8:9], v[8:9], v[10:11]
	v_pk_mul_f32 v[12:13], v[12:13], v[14:15]
	v_cvt_pk_bf16_f32 v70, v8, v9
	v_cvt_pk_bf16_f32 v71, v12, v13
	v_add_u32_e32 v7, 0x48000, v3
	global_store_dwordx4 v7, v[68:71], s[52:53]
	s_waitcnt vmcnt(15) lgkmcnt(5)
	v_lshlrev_b32_e32 v8, 16, v104
	v_and_b32_e32 v9, s98, v104
	v_lshlrev_b32_e32 v10, 16, v72
	v_and_b32_e32 v11, s98, v72
	v_lshlrev_b32_e32 v12, 16, v105
	v_and_b32_e32 v13, s98, v105
	v_lshlrev_b32_e32 v14, 16, v73
	v_and_b32_e32 v15, s98, v73
	v_pk_mul_f32 v[8:9], v[8:9], v[10:11]
	v_pk_mul_f32 v[12:13], v[12:13], v[14:15]
	v_cvt_pk_bf16_f32 v72, v8, v9
	v_cvt_pk_bf16_f32 v73, v12, v13
	v_lshlrev_b32_e32 v8, 16, v106
	v_and_b32_e32 v9, s98, v106
	v_lshlrev_b32_e32 v10, 16, v74
	v_and_b32_e32 v11, s98, v74
	v_lshlrev_b32_e32 v12, 16, v107
	v_and_b32_e32 v13, s98, v107
	v_lshlrev_b32_e32 v14, 16, v75
	v_and_b32_e32 v15, s98, v75
	v_pk_mul_f32 v[8:9], v[8:9], v[10:11]
	v_pk_mul_f32 v[12:13], v[12:13], v[14:15]
	v_cvt_pk_bf16_f32 v74, v8, v9
	v_cvt_pk_bf16_f32 v75, v12, v13
	v_add_u32_e32 v7, 0x50000, v3
	global_store_dwordx4 v7, v[72:75], s[52:53]
	s_waitcnt vmcnt(15) lgkmcnt(4)
	v_lshlrev_b32_e32 v8, 16, v108
	v_and_b32_e32 v9, s98, v108
	v_lshlrev_b32_e32 v10, 16, v76
	v_and_b32_e32 v11, s98, v76
	v_lshlrev_b32_e32 v12, 16, v109
	v_and_b32_e32 v13, s98, v109
	v_lshlrev_b32_e32 v14, 16, v77
	v_and_b32_e32 v15, s98, v77
	v_pk_mul_f32 v[8:9], v[8:9], v[10:11]
	v_pk_mul_f32 v[12:13], v[12:13], v[14:15]
	v_cvt_pk_bf16_f32 v76, v8, v9
	v_cvt_pk_bf16_f32 v77, v12, v13
	v_lshlrev_b32_e32 v8, 16, v110
	v_and_b32_e32 v9, s98, v110
	v_lshlrev_b32_e32 v10, 16, v78
	v_and_b32_e32 v11, s98, v78
	v_lshlrev_b32_e32 v12, 16, v111
	v_and_b32_e32 v13, s98, v111
	v_lshlrev_b32_e32 v14, 16, v79
	v_and_b32_e32 v15, s98, v79
	v_pk_mul_f32 v[8:9], v[8:9], v[10:11]
	v_pk_mul_f32 v[12:13], v[12:13], v[14:15]
	v_cvt_pk_bf16_f32 v78, v8, v9
	v_cvt_pk_bf16_f32 v79, v12, v13
	v_add_u32_e32 v7, 0x58000, v3
	global_store_dwordx4 v7, v[76:79], s[52:53]
	s_waitcnt vmcnt(15) lgkmcnt(3)
	v_lshlrev_b32_e32 v8, 16, v112
	v_and_b32_e32 v9, s98, v112
	v_lshlrev_b32_e32 v10, 16, v80
	v_and_b32_e32 v11, s98, v80
	v_lshlrev_b32_e32 v12, 16, v113
	v_and_b32_e32 v13, s98, v113
	v_lshlrev_b32_e32 v14, 16, v81
	v_and_b32_e32 v15, s98, v81
	v_pk_mul_f32 v[8:9], v[8:9], v[10:11]
	v_pk_mul_f32 v[12:13], v[12:13], v[14:15]
	v_cvt_pk_bf16_f32 v80, v8, v9
	v_cvt_pk_bf16_f32 v81, v12, v13
	v_lshlrev_b32_e32 v8, 16, v114
	v_and_b32_e32 v9, s98, v114
	v_lshlrev_b32_e32 v10, 16, v82
	v_and_b32_e32 v11, s98, v82
	v_lshlrev_b32_e32 v12, 16, v115
	v_and_b32_e32 v13, s98, v115
	v_lshlrev_b32_e32 v14, 16, v83
	v_and_b32_e32 v15, s98, v83
	v_pk_mul_f32 v[8:9], v[8:9], v[10:11]
	v_pk_mul_f32 v[12:13], v[12:13], v[14:15]
	v_cvt_pk_bf16_f32 v82, v8, v9
	v_cvt_pk_bf16_f32 v83, v12, v13
	v_add_u32_e32 v7, 0x60000, v3
	global_store_dwordx4 v7, v[80:83], s[52:53]
	s_waitcnt vmcnt(15) lgkmcnt(2)
	v_lshlrev_b32_e32 v8, 16, v116
	v_and_b32_e32 v9, s98, v116
	v_lshlrev_b32_e32 v10, 16, v84
	v_and_b32_e32 v11, s98, v84
	v_lshlrev_b32_e32 v12, 16, v117
	v_and_b32_e32 v13, s98, v117
	v_lshlrev_b32_e32 v14, 16, v85
	v_and_b32_e32 v15, s98, v85
	v_pk_mul_f32 v[8:9], v[8:9], v[10:11]
	v_pk_mul_f32 v[12:13], v[12:13], v[14:15]
	v_cvt_pk_bf16_f32 v84, v8, v9
	v_cvt_pk_bf16_f32 v85, v12, v13
	v_lshlrev_b32_e32 v8, 16, v118
	v_and_b32_e32 v9, s98, v118
	v_lshlrev_b32_e32 v10, 16, v86
	v_and_b32_e32 v11, s98, v86
	v_lshlrev_b32_e32 v12, 16, v119
	v_and_b32_e32 v13, s98, v119
	v_lshlrev_b32_e32 v14, 16, v87
	v_and_b32_e32 v15, s98, v87
	v_pk_mul_f32 v[8:9], v[8:9], v[10:11]
	v_pk_mul_f32 v[12:13], v[12:13], v[14:15]
	v_cvt_pk_bf16_f32 v86, v8, v9
	v_cvt_pk_bf16_f32 v87, v12, v13
	v_add_u32_e32 v7, 0x68000, v3
	global_store_dwordx4 v7, v[84:87], s[52:53]
	s_waitcnt vmcnt(15) lgkmcnt(1)
	v_lshlrev_b32_e32 v8, 16, v120
	v_and_b32_e32 v9, s98, v120
	v_lshlrev_b32_e32 v10, 16, v88
	v_and_b32_e32 v11, s98, v88
	v_lshlrev_b32_e32 v12, 16, v121
	v_and_b32_e32 v13, s98, v121
	v_lshlrev_b32_e32 v14, 16, v89
	v_and_b32_e32 v15, s98, v89
	v_pk_mul_f32 v[8:9], v[8:9], v[10:11]
	v_pk_mul_f32 v[12:13], v[12:13], v[14:15]
	v_cvt_pk_bf16_f32 v88, v8, v9
	v_cvt_pk_bf16_f32 v89, v12, v13
	v_lshlrev_b32_e32 v8, 16, v122
	v_and_b32_e32 v9, s98, v122
	v_lshlrev_b32_e32 v10, 16, v90
	v_and_b32_e32 v11, s98, v90
	v_lshlrev_b32_e32 v12, 16, v123
	v_and_b32_e32 v13, s98, v123
	v_lshlrev_b32_e32 v14, 16, v91
	v_and_b32_e32 v15, s98, v91
	v_pk_mul_f32 v[8:9], v[8:9], v[10:11]
	v_pk_mul_f32 v[12:13], v[12:13], v[14:15]
	v_cvt_pk_bf16_f32 v90, v8, v9
	v_cvt_pk_bf16_f32 v91, v12, v13
	v_add_u32_e32 v7, 0x70000, v3
	global_store_dwordx4 v7, v[88:91], s[52:53]
	s_waitcnt vmcnt(15) lgkmcnt(0)
	v_lshlrev_b32_e32 v8, 16, v124
	v_and_b32_e32 v9, s98, v124
	v_lshlrev_b32_e32 v10, 16, v92
	v_and_b32_e32 v11, s98, v92
	v_lshlrev_b32_e32 v12, 16, v125
	v_and_b32_e32 v13, s98, v125
	v_lshlrev_b32_e32 v14, 16, v93
	v_and_b32_e32 v15, s98, v93
	v_pk_mul_f32 v[8:9], v[8:9], v[10:11]
	v_pk_mul_f32 v[12:13], v[12:13], v[14:15]
	v_cvt_pk_bf16_f32 v92, v8, v9
	v_cvt_pk_bf16_f32 v93, v12, v13
	v_lshlrev_b32_e32 v8, 16, v126
	v_and_b32_e32 v9, s98, v126
	v_lshlrev_b32_e32 v10, 16, v94
	v_and_b32_e32 v11, s98, v94
	v_lshlrev_b32_e32 v12, 16, v127
	v_and_b32_e32 v13, s98, v127
	v_lshlrev_b32_e32 v14, 16, v95
	v_and_b32_e32 v15, s98, v95
	v_pk_mul_f32 v[8:9], v[8:9], v[10:11]
	v_pk_mul_f32 v[12:13], v[12:13], v[14:15]
	v_cvt_pk_bf16_f32 v94, v8, v9
	v_cvt_pk_bf16_f32 v95, v12, v13
	v_add_u32_e32 v7, 0x78000, v3
	global_store_dwordx4 v7, v[92:95], s[52:53]
	s_movk_i32 s58, 0x2000
	s_add_i32 s16, s16, 1
	s_add_u32 s50, s50, 0x20000
	s_addc_u32 s51, s51, 0
	s_cmp_eq_u32 s16, 4
	s_cbranch_scc0 .LBB0_1045
	s_lshl_b64 s[48:49], s[48:49], 7
	s_add_u32 s46, s96, s46
	s_addc_u32 s47, s97, s47
	s_mov_b32 s9, 0
	s_mov_b64 s[50:51], s[96:97]
	s_branch .LBB0_1056

.LBB0_1057:
	s_and_b32 s16, s16, 0x10000
	v_add_u32_e32 v132, s16, v143
	v_or_b32_e32 v151, s16, v144
	ds_read_b128 v[152:155], v132
	ds_read_b128 v[156:159], v132 offset:4096
	ds_read_b128 v[160:163], v132 offset:8192
	ds_read_b128 v[164:167], v132 offset:12288
	ds_read_b128 v[172:175], v151
	ds_read_b128 v[180:183], v151 offset:4096
	v_add_u32_e32 v214, s16, v145
	v_or_b32_e32 v215, s16, v146
	ds_read_b128 v[216:219], v214
	ds_read_b128 v[220:223], v214 offset:4096
	ds_read_b128 v[224:227], v214 offset:8192
	ds_read_b128 v[228:231], v214 offset:12288
	ds_read_b128 v[232:235], v215
	ds_read_b128 v[236:239], v215 offset:4096
	v_add_u32_e32 v132, s16, v147
	v_or_b32_e32 v151, s16, v148
	s_waitcnt lgkmcnt(6)
	v_mfma_f32_32x32x16_bf16 v[112:127], v[172:175], v[152:155], v[112:127]
	s_add_u32 s52, s52, 0x80
	s_addc_u32 s53, s53, 0
	s_add_i32 s3, s3, 1
	s_cmpk_lg_i32 s52, 0x800
	v_mfma_f32_32x32x16_bf16 v[96:111], v[172:175], v[156:159], v[96:111]
	v_mfma_f32_32x32x16_bf16 v[64:79], v[172:175], v[160:163], v[64:79]
	v_mfma_f32_32x32x16_bf16 v[32:47], v[172:175], v[164:167], v[32:47]
	v_mfma_f32_32x32x16_bf16 v[80:95], v[180:183], v[152:155], v[80:95]
	v_mfma_f32_32x32x16_bf16 v[48:63], v[180:183], v[156:159], v[48:63]
	v_mfma_f32_32x32x16_bf16 v[16:31], v[180:183], v[160:163], v[16:31]
	v_mfma_f32_32x32x16_bf16 v[0:15], v[180:183], v[164:167], v[0:15]
	ds_read_b128 v[152:155], v132
	ds_read_b128 v[156:159], v132 offset:4096
	ds_read_b128 v[160:163], v132 offset:8192
	ds_read_b128 v[164:167], v132 offset:12288
	ds_read_b128 v[172:175], v151
	ds_read_b128 v[180:183], v151 offset:4096
	v_add_u32_e32 v214, s16, v149
	v_or_b32_e32 v215, s16, v150
	s_mov_b32 s16, s56
	s_waitcnt lgkmcnt(6)
	v_mfma_f32_32x32x16_bf16 v[112:127], v[232:235], v[216:219], v[112:127]
	v_mfma_f32_32x32x16_bf16 v[96:111], v[232:235], v[220:223], v[96:111]
	v_mfma_f32_32x32x16_bf16 v[64:79], v[232:235], v[224:227], v[64:79]
	v_mfma_f32_32x32x16_bf16 v[32:47], v[232:235], v[228:231], v[32:47]
	v_mfma_f32_32x32x16_bf16 v[80:95], v[236:239], v[216:219], v[80:95]
	v_mfma_f32_32x32x16_bf16 v[48:63], v[236:239], v[220:223], v[48:63]
	v_mfma_f32_32x32x16_bf16 v[16:31], v[236:239], v[224:227], v[16:31]
	v_mfma_f32_32x32x16_bf16 v[0:15], v[236:239], v[228:231], v[0:15]
	ds_read_b128 v[216:219], v214
	ds_read_b128 v[220:223], v214 offset:4096
	ds_read_b128 v[224:227], v214 offset:8192
	ds_read_b128 v[228:231], v214 offset:12288
	ds_read_b128 v[232:235], v215
	ds_read_b128 v[236:239], v215 offset:4096
	s_waitcnt lgkmcnt(6)
	v_mfma_f32_32x32x16_bf16 v[112:127], v[172:175], v[152:155], v[112:127]
	v_mfma_f32_32x32x16_bf16 v[96:111], v[172:175], v[156:159], v[96:111]
	v_mfma_f32_32x32x16_bf16 v[64:79], v[172:175], v[160:163], v[64:79]
	v_mfma_f32_32x32x16_bf16 v[32:47], v[172:175], v[164:167], v[32:47]
	v_mfma_f32_32x32x16_bf16 v[80:95], v[180:183], v[152:155], v[80:95]
	v_mfma_f32_32x32x16_bf16 v[48:63], v[180:183], v[156:159], v[48:63]
	v_mfma_f32_32x32x16_bf16 v[16:31], v[180:183], v[160:163], v[16:31]
	v_mfma_f32_32x32x16_bf16 v[0:15], v[180:183], v[164:167], v[0:15]
	s_waitcnt lgkmcnt(0)
	v_mfma_f32_32x32x16_bf16 v[112:127], v[232:235], v[216:219], v[112:127]
	v_mfma_f32_32x32x16_bf16 v[96:111], v[232:235], v[220:223], v[96:111]
	v_mfma_f32_32x32x16_bf16 v[64:79], v[232:235], v[224:227], v[64:79]
	v_mfma_f32_32x32x16_bf16 v[32:47], v[232:235], v[228:231], v[32:47]
	v_mfma_f32_32x32x16_bf16 v[80:95], v[236:239], v[216:219], v[80:95]
	v_mfma_f32_32x32x16_bf16 v[48:63], v[236:239], v[220:223], v[48:63]
	v_mfma_f32_32x32x16_bf16 v[16:31], v[236:239], v[224:227], v[16:31]
	v_mfma_f32_32x32x16_bf16 v[0:15], v[236:239], v[228:231], v[0:15]
	s_cbranch_scc0 .LBB0_1062

.LBB0_1069:
	global_load_dwordx4 v[6:9], v[0:1], off offset:-2048
	global_load_dwordx4 v[10:13], v[0:1], off offset:-1024
	global_load_dwordx4 v[14:17], v[0:1], off
	global_load_dwordx4 v[18:21], v[0:1], off offset:1024
	v_add_u32_e32 v3, 0x100, v3
	v_cmp_lt_u32_e32 vcc, s25, v3
	v_lshl_add_u64 v[0:1], v[0:1], 0, s[12:13]
	s_or_b64 s[4:5], vcc, s[4:5]
	s_waitcnt vmcnt(3)
	v_lshlrev_b32_e32 v5, 16, v9
	v_lshlrev_b32_e32 v9, 16, v7
	s_waitcnt vmcnt(2)
	v_lshlrev_b32_e32 v13, 16, v13
	v_lshlrev_b32_e32 v11, 16, v11
	s_waitcnt vmcnt(1)
	v_lshlrev_b32_e32 v17, 16, v17
	v_lshlrev_b32_e32 v15, 16, v15
	s_waitcnt vmcnt(0)
	v_lshlrev_b32_e32 v21, 16, v21
	v_lshlrev_b32_e32 v19, 16, v19
	v_or_b32_e32 v7, v5, v8
	v_or_b32_e32 v6, v9, v6
	v_or_b32_e32 v9, v13, v12
	v_or_b32_e32 v8, v11, v10
	v_or_b32_e32 v11, v17, v16
	v_or_b32_e32 v10, v15, v14
	v_or_b32_e32 v13, v21, v20
	v_or_b32_e32 v12, v19, v18
	ds_write2st64_b64 v4, v[6:7], v[8:9] offset1:1
	ds_write2st64_b64 v4, v[10:11], v[12:13] offset0:2 offset1:3
	v_add_u32_e32 v4, 0x800, v4
	s_andn2_b64 exec, exec, s[4:5]
	s_cbranch_execnz .LBB0_1069
	s_or_b64 exec, exec, s[4:5]
	s_lshl_b32 s60, s2, 8
	v_add_u32_e32 v0, s60, v74
	s_add_u32 s6, s96, s0
	v_ashrrev_i32_e32 v1, 31, v0
	s_addc_u32 s7, s97, s1
	v_lshlrev_b32_e32 v77, 13, v2
	v_lshlrev_b64 v[0:1], 10, v[0:1]
	v_lshlrev_b32_e32 v2, 4, v84
	v_and_b32_e32 v72, 16, v2
	v_lshl_add_u64 v[0:1], s[6:7], 0, v[0:1]
	v_add_u32_e32 v86, 0x10000, v77
	v_lshlrev_b32_e32 v2, 1, v84
	v_and_b32_e32 v2, 0x60, v2
	v_mov_b32_e32 v3, v73
	v_lshl_add_u64 v[4:5], s[6:7], 0, v[72:73]
	v_lshl_add_u64 v[0:1], v[0:1], 0, v[72:73]
	v_and_or_b32 v88, v84, 14, v86
	v_lshl_add_u64 v[16:17], v[0:1], 0, v[2:3]
	v_lshl_add_u64 v[0:1], v[4:5], 0, v[2:3]
	ds_read_u16 v6, v88
	ds_read_u16 v7, v88 offset:16
	ds_read_u16 v8, v88 offset:32
	ds_read_u16 v9, v88 offset:48
	ds_read_u16 v10, v88 offset:64
	ds_read_u16 v11, v88 offset:80
	ds_read_u16 v18, v88 offset:96
	ds_read_u16 v19, v88 offset:112
	v_lshl_add_u64 v[78:79], v[0:1], 0, s[16:17]
	s_waitcnt lgkmcnt(7)
	v_lshlrev_b32_e32 v72, 7, v6
	v_lshl_add_u64 v[0:1], v[78:79], 0, v[72:73]
	s_waitcnt lgkmcnt(6)
	v_lshlrev_b32_e32 v72, 7, v7
	v_lshl_add_u64 v[2:3], v[78:79], 0, v[72:73]
	s_waitcnt lgkmcnt(5)
	v_lshlrev_b32_e32 v72, 7, v8
	global_load_dwordx4 v[56:59], v[0:1], off
	global_load_dwordx4 v[48:51], v[2:3], off
	v_lshl_add_u64 v[0:1], v[78:79], 0, v[72:73]
	s_waitcnt lgkmcnt(4)
	v_lshlrev_b32_e32 v72, 7, v9
	v_lshl_add_u64 v[2:3], v[78:79], 0, v[72:73]
	s_waitcnt lgkmcnt(3)
	v_lshlrev_b32_e32 v72, 7, v10
	global_load_dwordx4 v[40:43], v[0:1], off
	global_load_dwordx4 v[32:35], v[2:3], off
	v_lshl_add_u64 v[0:1], v[78:79], 0, v[72:73]
	s_waitcnt lgkmcnt(2)
	v_lshlrev_b32_e32 v72, 7, v11
	v_lshl_add_u64 v[2:3], v[78:79], 0, v[72:73]
	s_waitcnt lgkmcnt(1)
	v_lshlrev_b32_e32 v72, 7, v18
	global_load_dwordx4 v[24:27], v[0:1], off
	global_load_dwordx4 v[12:15], v[2:3], off
	v_lshl_add_u64 v[0:1], v[78:79], 0, v[72:73]
	s_waitcnt lgkmcnt(0)
	v_lshlrev_b32_e32 v72, 7, v19
	v_add_co_u32_e32 v4, vcc, 0x38000000, v16
	v_lshl_add_u64 v[2:3], v[78:79], 0, v[72:73]
	s_nop 0
	v_addc_co_u32_e32 v5, vcc, 0, v17, vcc
	global_load_dwordx4 v[8:11], v[0:1], off
	s_nop 0
	global_load_dwordx4 v[0:3], v[2:3], off
	v_and_b32_e32 v18, 15, v84
	global_load_dwordx4 v[4:7], v[4:5], off
	ds_read_u16 v72, v88 offset:128
	ds_read_u16 v96, v88 offset:144
	ds_read_u16 v95, v88 offset:160
	ds_read_u16 v94, v88 offset:176
	ds_read_u16 v93, v88 offset:192
	ds_read_u16 v92, v88 offset:208
	ds_read_u16 v91, v88 offset:224
	ds_read_u16 v90, v88 offset:240
	v_lshrrev_b32_e32 v87, 2, v84
	v_lshl_add_u64 v[80:81], v[16:17], 0, s[14:15]
	s_mov_b32 s3, 0
	v_and_or_b32 v89, v87, 12, v77
	v_cmp_eq_u32_e64 s[0:1], 0, v18
	s_branch .LBB0_1073

	.amdhsa_kernel _Z14fwd_megakernel6Params
		.amdhsa_group_segment_fixed_size 151556
		.amdhsa_private_segment_fixed_size 0
		.amdhsa_kernarg_size 440
		.amdhsa_user_sgpr_count 2
		.amdhsa_user_sgpr_dispatch_ptr 0
		.amdhsa_user_sgpr_queue_ptr 0
		.amdhsa_user_sgpr_kernarg_segment_ptr 1
		.amdhsa_user_sgpr_dispatch_id 0
		.amdhsa_user_sgpr_kernarg_preload_length 0
		.amdhsa_user_sgpr_kernarg_preload_offset 0
		.amdhsa_user_sgpr_private_segment_size 0
		.amdhsa_uses_dynamic_stack 0
		.amdhsa_enable_private_segment 0
		.amdhsa_system_sgpr_workgroup_id_x 1
		.amdhsa_system_sgpr_workgroup_id_y 0
		.amdhsa_system_sgpr_workgroup_id_z 0
		.amdhsa_system_sgpr_workgroup_info 0
		.amdhsa_system_vgpr_workitem_id 2
		.amdhsa_next_free_vgpr 256
		.amdhsa_next_free_sgpr 102
		.amdhsa_accum_offset 256
		.amdhsa_reserve_vcc 1
		.amdhsa_float_round_mode_32 0
		.amdhsa_float_round_mode_16_64 0
		.amdhsa_float_denorm_mode_32 3
		.amdhsa_float_denorm_mode_16_64 3
		.amdhsa_dx10_clamp 1
		.amdhsa_ieee_mode 1
		.amdhsa_fp16_overflow 0
		.amdhsa_tg_split 0
		.amdhsa_exception_fp_ieee_invalid_op 0
		.amdhsa_exception_fp_denorm_src 0
		.amdhsa_exception_fp_ieee_div_zero 0
		.amdhsa_exception_fp_ieee_overflow 0
		.amdhsa_exception_fp_ieee_underflow 0
		.amdhsa_exception_fp_ieee_inexact 0
		.amdhsa_exception_int_div_zero 0
	.end_amdhsa_kernel

amdhsa.kernels:
  - .agpr_count:     0
    .args:
      - .offset:         0
        .size:           184
        .value_kind:     by_value
      - .offset:         184
        .size:           4
        .value_kind:     hidden_block_count_x
      - .offset:         188
        .size:           4
        .value_kind:     hidden_block_count_y
      - .offset:         192
        .size:           4
        .value_kind:     hidden_block_count_z
      - .offset:         196
        .size:           2
        .value_kind:     hidden_group_size_x
      - .offset:         198
        .size:           2
        .value_kind:     hidden_group_size_y
      - .offset:         200
        .size:           2
        .value_kind:     hidden_group_size_z
      - .offset:         202
        .size:           2
        .value_kind:     hidden_remainder_x
      - .offset:         204
        .size:           2
        .value_kind:     hidden_remainder_y
      - .offset:         206
        .size:           2
        .value_kind:     hidden_remainder_z
      - .offset:         224
        .size:           8
        .value_kind:     hidden_global_offset_x
      - .offset:         232
        .size:           8
        .value_kind:     hidden_global_offset_y
      - .offset:         240
        .size:           8
        .value_kind:     hidden_global_offset_z
      - .offset:         248
        .size:           2
        .value_kind:     hidden_grid_dims
      - .offset:         272
        .size:           8
        .value_kind:     hidden_multigrid_sync_arg
    .group_segment_fixed_size: 151556
    .kernarg_segment_align: 8
    .kernarg_segment_size: 440
    .language:       OpenCL C
    .language_version:
      - 2
      - 0
    .max_flat_workgroup_size: 512
    .name:           _Z14fwd_megakernel6Params
    .private_segment_fixed_size: 0
    .sgpr_count:     108
    .sgpr_spill_count: 31
    .symbol:         _Z14fwd_megakernel6Params.kd
    .uniform_work_group_size: 1
    .uses_dynamic_stack: false
    .vgpr_count:     256
    .vgpr_spill_count: 0
    .wavefront_size: 64
